# baseline (speedup 1.0000x reference)
; #define PG8_STAGE(bufoff, gbase, voff) do { _Pragma("unroll") for (int _i = 0; _i < 2; ++_i) \
;         __builtin_amdgcn_global_load_lds((const unsigned*)((const char*)(gbase) + (voff)[_i]), (PG8_LAS unsigned*)(lds + (bufoff) + ldsw + _i * 8192), 16, 0, 0); } while (0)
; #define PG8_LDA(dst, b, h) do { _Pragma("unroll") for (int m = 0; m < 4; ++m) _Pragma("unroll") for (int k = 0; k < 2; ++k) dst[m][k] = *(const PG8_LAS bf16x8*)(lds + PG8_SA(b, h) + aoff + m * 2048 + k * 1024); } while (0)
; #define PG8_LDB(dst, b, h) do { _Pragma("unroll") for (int n = 0; n < 2; ++n) _Pragma("unroll") for (int k = 0; k < 2; ++k) dst[n][k] = *(const PG8_LAS bf16x8*)(lds + PG8_SB(b, h) + boff + n * 2048 + k * 1024); } while (0)
; #define PG8_WAIT_V(n) asm volatile("s_waitcnt vmcnt(" #n ")" ::: "memory")
; #define PG8_WAIT_L(n) asm volatile("s_waitcnt lgkmcnt(" #n ")" ::: "memory")
; #define PG8_BAR __builtin_amdgcn_s_barrier()
; template <class Epi, class Sched, bool ALIGN_EPI = false, bool SP2 = false>
; __device__ __forceinline__ void gemm_phase(PG8_LAS unsigned char* lds, const Gemm g, const Sched& S, const Epi& E) {
;     ...
;         const bool has_next = S.next(ui + 1, nxt);
;         const char* nA = has_next ? (const char*)g.A + (size_t)nxt.pm * tstep : cA; const char* nB = has_next ? (const char*)g.Bt + (size_t)nxt.pn * tstep : cB;
;         for (int t = 0; t < nt; t += 2) {
;             if constexpr (Epi::MID_HOOK) { if (t == Epi::MID_T) E.mid(acc, cur, wr, wc, fr, fq); }
;             const bool last = (t == nt - 2);
;             const char* a1 = cA + (size_t)(t + 1) * kstep;
;             const char* a2 = last ? nA : cA + (size_t)(t + 2) * kstep; const char* b2 = last ? nB : cB + (size_t)(t + 2) * kstep;
;             const char* a3 = a2 + kstep; const char* b3 = b2 + kstep;
;             if (last && has_next) S.a_ready(nxt);
;             if constexpr (SP2) {
;             PG8_LDB(B0, 0, 0); PG8_LDB(B1, 0, 1); PG8_SCHED; PG8_LDA(At, 0, 0); PG8_STAGE(PG8_SA(1, 1), a1 + hstep, voffA);
;             PG8_WAIT_V(8); PG8_WAIT_L(0); PG8_BAR; PG8_MMA(0, 0, At, B0); PG8_MMA(0, 1, At, B1); PG8_BAR; PG8_SCHED;
;             PG8_LDA(At, 0, 1); PG8_STAGE(PG8_SB(0, 0), b2, voffB); PG8_STAGE(PG8_SB(0, 1), b2 + hstep, voffB); PG8_STAGE(PG8_SA(0, 0), a2, voffA);
;             PG8_WAIT_V(8); PG8_WAIT_L(0); PG8_BAR; PG8_MMA(1, 0, At, B0); PG8_MMA(1, 1, At, B1); PG8_BAR; PG8_SCHED;
.LBB0_128:
	s_ashr_i32 s67, s66, 31
	s_lshl_b64 s[14:15], s[66:67], 20
	s_add_u32 s70, s37, s14
	s_addc_u32 s71, s38, s15
	s_and_b64 s[14:15], s[68:69], exec
	s_cselect_b32 s2, s71, s1
	s_cselect_b32 s11, s70, s0
	s_ashr_i32 s65, s64, 31
	s_lshl_b64 s[14:15], s[64:65], 20
	s_add_u32 s72, s31, s14
	s_addc_u32 s73, s36, s15
	s_and_b64 s[14:15], s[68:69], exec
	s_cselect_b32 s18, s73, s13
	s_cselect_b32 s19, s72, s12
	s_add_u32 s0, s0, 0x80080
	s_addc_u32 s1, s1, 0
	s_add_u32 s34, s12, 0x100
	s_addc_u32 s41, s13, 0
	s_mov_b32 s42, -2
	v_lshl_add_u64 v[194:195], s[0:1], 0, v[144:145]
	s_add_i32 m0, s74, 0xc000
	global_load_lds_dwordx4 v[194:195], off
	s_add_i32 m0, s74, 0xe000
	v_lshl_add_u64 v[194:195], s[0:1], 0, v[146:147]
	global_load_lds_dwordx4 v[194:195], off
	s_add_u32 s12, s0, 0xfff80080
	s_addc_u32 s13, s1, -1
	s_add_i32 s43, 0, 0x10000
	s_cmp_eq_u32 s42, 28
	s_cselect_b32 s15, s2, s13
	s_cselect_b32 s14, s11, s12
	s_cselect_b32 s13, s18, s41
	s_cselect_b32 s12, s19, s34
	s_add_i32 s65, 0, 0x14000
	s_waitcnt vmcnt(8)
	s_waitcnt lgkmcnt(0)
	s_barrier
	s_setprio 1
	s_waitcnt lgkmcnt(0)
	v_mfma_f32_16x16x32_bf16 v[124:127], v[128:131], v[172:175], 0
	v_mfma_f32_16x16x32_bf16 v[120:123], v[148:151], v[172:175], 0
	v_mfma_f32_16x16x32_bf16 v[108:111], v[128:131], v[184:187], 0
	v_mfma_f32_16x16x32_bf16 v[104:107], v[148:151], v[184:187], 0
	v_mfma_f32_16x16x32_bf16 v[92:95], v[128:131], v[206:209], 0
	v_mfma_f32_16x16x32_bf16 v[88:91], v[148:151], v[206:209], 0
	v_mfma_f32_16x16x32_bf16 v[76:79], v[128:131], v[214:217], 0
	v_mfma_f32_16x16x32_bf16 v[72:75], v[148:151], v[214:217], 0
	v_mfma_f32_16x16x32_bf16 v[124:127], v[132:135], v[180:183], v[124:127]
	v_mfma_f32_16x16x32_bf16 v[120:123], v[152:155], v[180:183], v[120:123]
	v_mfma_f32_16x16x32_bf16 v[108:111], v[132:135], v[188:191], v[108:111]
	v_mfma_f32_16x16x32_bf16 v[104:107], v[152:155], v[188:191], v[104:107]
	v_mfma_f32_16x16x32_bf16 v[92:95], v[132:135], v[210:213], v[92:95]
	v_mfma_f32_16x16x32_bf16 v[88:91], v[152:155], v[210:213], v[88:91]
	v_mfma_f32_16x16x32_bf16 v[76:79], v[132:135], v[218:221], v[76:79]
	v_mfma_f32_16x16x32_bf16 v[72:75], v[152:155], v[218:221], v[72:75]
	s_setprio 0
	s_setprio 1
	v_mfma_f32_16x16x32_bf16 v[116:119], v[156:159], v[172:175], 0
	v_mfma_f32_16x16x32_bf16 v[112:115], v[164:167], v[172:175], 0
	v_mfma_f32_16x16x32_bf16 v[100:103], v[156:159], v[184:187], 0
	v_mfma_f32_16x16x32_bf16 v[96:99], v[164:167], v[184:187], 0
	v_mfma_f32_16x16x32_bf16 v[84:87], v[156:159], v[206:209], 0
	v_mfma_f32_16x16x32_bf16 v[80:83], v[164:167], v[206:209], 0
	v_mfma_f32_16x16x32_bf16 v[68:71], v[156:159], v[214:217], 0
	v_mfma_f32_16x16x32_bf16 v[64:67], v[164:167], v[214:217], 0
	v_mfma_f32_16x16x32_bf16 v[116:119], v[160:163], v[180:183], v[116:119]
	v_mfma_f32_16x16x32_bf16 v[112:115], v[168:171], v[180:183], v[112:115]
	v_mfma_f32_16x16x32_bf16 v[100:103], v[160:163], v[188:191], v[100:103]
	v_mfma_f32_16x16x32_bf16 v[96:99], v[168:171], v[188:191], v[96:99]
	s_barrier
	s_setprio 2
	v_mfma_f32_16x16x32_bf16 v[84:87], v[160:163], v[210:213], v[84:87]
	v_mfma_f32_16x16x32_bf16 v[80:83], v[168:171], v[210:213], v[80:83]
	v_mfma_f32_16x16x32_bf16 v[68:71], v[160:163], v[218:221], v[68:71]
	v_mfma_f32_16x16x32_bf16 v[64:67], v[168:171], v[218:221], v[64:67]
	s_setprio 0
	s_add_i32 s43, s43, s39
	v_lshl_add_u64 v[194:195], s[12:13], 0, v[138:139]
	s_mov_b32 m0, s43
	s_nop 0
	global_load_lds_dwordx4 v[194:195], off
	s_add_i32 m0, s43, 0x2000
	s_add_u32 s86, s12, 0x80000
	v_lshl_add_u64 v[196:197], s[12:13], 0, v[142:143]
	s_addc_u32 s87, s13, 0
	s_add_i32 s43, s65, s39
	global_load_lds_dwordx4 v[196:197], off
	v_lshl_add_u64 v[202:203], s[86:87], 0, v[138:139]
	s_mov_b32 m0, s43
	v_lshl_add_u64 v[204:205], s[14:15], 0, v[140:141]
	global_load_lds_dwordx4 v[202:203], off
	s_add_i32 m0, s43, 0x2000
	v_lshl_add_u64 v[202:203], s[86:87], 0, v[142:143]
	global_load_lds_dwordx4 v[202:203], off
	s_mov_b32 m0, s74
	v_lshl_add_u64 v[202:203], s[14:15], 0, v[136:137]
	global_load_lds_dwordx4 v[202:203], off
	s_mov_b32 m0, s75
	s_nop 0
	global_load_lds_dwordx4 v[204:205], off
	ds_read_b128 v[172:175], v179 offset:16384
	ds_read_b128 v[180:183], v179 offset:17408
	ds_read_b128 v[184:187], v179 offset:18432
	ds_read_b128 v[188:191], v179 offset:19456
	ds_read_b128 v[206:209], v179 offset:20480
	ds_read_b128 v[210:213], v179 offset:21504
	ds_read_b128 v[214:217], v179 offset:22528
	ds_read_b128 v[218:221], v179 offset:23552
	s_waitcnt vmcnt(8)
	s_waitcnt lgkmcnt(0)
	s_barrier
	s_setprio 1
	s_waitcnt lgkmcnt(0)
	v_mfma_f32_16x16x32_bf16 v[60:63], v[128:131], v[172:175], 0
	v_mfma_f32_16x16x32_bf16 v[56:59], v[148:151], v[172:175], 0
	v_mfma_f32_16x16x32_bf16 v[44:47], v[128:131], v[184:187], 0
	v_mfma_f32_16x16x32_bf16 v[40:43], v[148:151], v[184:187], 0
	v_mfma_f32_16x16x32_bf16 v[28:31], v[128:131], v[206:209], 0
	v_mfma_f32_16x16x32_bf16 v[24:27], v[148:151], v[206:209], 0
	v_mfma_f32_16x16x32_bf16 v[12:15], v[128:131], v[214:217], 0
	v_mfma_f32_16x16x32_bf16 v[8:11], v[148:151], v[214:217], 0
	v_mfma_f32_16x16x32_bf16 v[60:63], v[132:135], v[180:183], v[60:63]
	v_mfma_f32_16x16x32_bf16 v[56:59], v[152:155], v[180:183], v[56:59]
	v_mfma_f32_16x16x32_bf16 v[44:47], v[132:135], v[188:191], v[44:47]
	v_mfma_f32_16x16x32_bf16 v[40:43], v[152:155], v[188:191], v[40:43]
	v_mfma_f32_16x16x32_bf16 v[28:31], v[132:135], v[210:213], v[28:31]
	v_mfma_f32_16x16x32_bf16 v[24:27], v[152:155], v[210:213], v[24:27]
	v_mfma_f32_16x16x32_bf16 v[12:15], v[132:135], v[218:221], v[12:15]
	v_mfma_f32_16x16x32_bf16 v[8:11], v[152:155], v[218:221], v[8:11]
	s_setprio 0
	s_setprio 1
	v_mfma_f32_16x16x32_bf16 v[52:55], v[156:159], v[172:175], 0
	v_mfma_f32_16x16x32_bf16 v[48:51], v[164:167], v[172:175], 0
	v_mfma_f32_16x16x32_bf16 v[36:39], v[156:159], v[184:187], 0
	v_mfma_f32_16x16x32_bf16 v[32:35], v[164:167], v[184:187], 0
	v_mfma_f32_16x16x32_bf16 v[20:23], v[156:159], v[206:209], 0
	v_mfma_f32_16x16x32_bf16 v[16:19], v[164:167], v[206:209], 0
	v_mfma_f32_16x16x32_bf16 v[4:7], v[156:159], v[214:217], 0
	v_mfma_f32_16x16x32_bf16 v[0:3], v[164:167], v[214:217], 0
	v_mfma_f32_16x16x32_bf16 v[52:55], v[160:163], v[180:183], v[52:55]
	v_mfma_f32_16x16x32_bf16 v[48:51], v[168:171], v[180:183], v[48:51]
	v_mfma_f32_16x16x32_bf16 v[36:39], v[160:163], v[188:191], v[36:39]
	v_mfma_f32_16x16x32_bf16 v[32:35], v[168:171], v[188:191], v[32:35]
	s_barrier
; #define PG8_STAGE(bufoff, gbase, voff) do { _Pragma("unroll") for (int _i = 0; _i < 2; ++_i) \
;         __builtin_amdgcn_global_load_lds((const unsigned*)((const char*)(gbase) + (voff)[_i]), (PG8_LAS unsigned*)(lds + (bufoff) + ldsw + _i * 8192), 16, 0, 0); } while (0)
; #define PG8_LDA(dst, b, h) do { _Pragma("unroll") for (int m = 0; m < 4; ++m) _Pragma("unroll") for (int k = 0; k < 2; ++k) dst[m][k] = *(const PG8_LAS bf16x8*)(lds + PG8_SA(b, h) + aoff + m * 2048 + k * 1024); } while (0)
; #define PG8_LDB(dst, b, h) do { _Pragma("unroll") for (int n = 0; n < 2; ++n) _Pragma("unroll") for (int k = 0; k < 2; ++k) dst[n][k] = *(const PG8_LAS bf16x8*)(lds + PG8_SB(b, h) + boff + n * 2048 + k * 1024); } while (0)
; #define PG8_MMA(ai, bj, At, Bt) do { __builtin_amdgcn_s_setprio(1); _Pragma("unroll") for (int m = 0; m < 4; ++m) _Pragma("unroll") for (int n = 0; n < 2; ++n) _Pragma("unroll") for (int k = 0; k < 2; ++k) \
;         acc[ai][bj][m][n] = __builtin_amdgcn_mfma_f32_16x16x32_bf16(Bt[n][k], At[m][k], acc[ai][bj][m][n], 0, 0, 0); __builtin_amdgcn_s_setprio(0); } while (0)
; #define PG8_WAIT_V(n) asm volatile("s_waitcnt vmcnt(" #n ")" ::: "memory")
; #define PG8_WAIT_L(n) asm volatile("s_waitcnt lgkmcnt(" #n ")" ::: "memory")
; #define PG8_BAR __builtin_amdgcn_s_barrier()
; #define PG8_SCHED __builtin_amdgcn_sched_barrier(0)
; template <class Epi, class Sched, bool ALIGN_EPI = false, bool SP2 = false>
; __device__ __forceinline__ void gemm_phase(PG8_LAS unsigned char* lds, const Gemm g, const Sched& S, const Epi& E) {
;     ...
;             PG8_WAIT_V(8); PG8_WAIT_L(0); PG8_BAR; PG8_MMA(1, 0, At, B0); PG8_MMA(1, 1, At, B1); PG8_BAR; PG8_SCHED;
;             PG8_LDB(B0, 1, 0); PG8_LDB(B1, 1, 1); PG8_SCHED; PG8_LDA(At, 1, 0); PG8_STAGE(PG8_SA(0, 1), a2 + hstep, voffA);
;             PG8_WAIT_V(8); PG8_WAIT_L(0); PG8_BAR; PG8_MMA(0, 0, At, B0); PG8_MMA(0, 1, At, B1); PG8_BAR; PG8_SCHED;
;             PG8_LDA(At, 1, 1); PG8_STAGE(PG8_SB(1, 0), b3, voffB); PG8_STAGE(PG8_SB(1, 1), b3 + hstep, voffB); PG8_STAGE(PG8_SA(1, 0), a3, voffA);
	s_setprio 2
	v_mfma_f32_16x16x32_bf16 v[20:23], v[160:163], v[210:213], v[20:23]
	v_mfma_f32_16x16x32_bf16 v[16:19], v[168:171], v[210:213], v[16:19]
	v_mfma_f32_16x16x32_bf16 v[4:7], v[160:163], v[218:221], v[4:7]
	v_mfma_f32_16x16x32_bf16 v[0:3], v[168:171], v[218:221], v[0:3]
	s_setprio 0
	s_add_i32 s43, 0, 0x18000
	s_add_i32 s65, 0, 0x1c000
	s_add_u32 s14, s14, 0x80000
	s_addc_u32 s15, s15, 0
	s_mov_b32 m0, s76
	v_lshl_add_u64 v[232:233], s[14:15], 0, v[136:137]
	global_load_lds_dwordx4 v[232:233], off
	s_mov_b32 m0, s77
	v_lshl_add_u64 v[232:233], s[14:15], 0, v[140:141]
	global_load_lds_dwordx4 v[232:233], off
	v_add_u32_e32 v152, 0x18000, v178
	v_add_u32_e32 v168, 0x1c000, v178
	ds_read_b128 v[128:131], v152
	ds_read_b128 v[132:135], v152 offset:1024
	ds_read_b128 v[148:151], v152 offset:2048
	ds_read_b128 v[152:155], v152 offset:3072
	ds_read_b128 v[156:159], v168
	ds_read_b128 v[160:163], v168 offset:1024
	ds_read_b128 v[164:167], v168 offset:2048
	ds_read_b128 v[168:171], v168 offset:3072
	ds_read_b128 v[172:175], v179 offset:32768
	ds_read_b128 v[180:183], v179 offset:33792
	ds_read_b128 v[184:187], v179 offset:34816
	ds_read_b128 v[188:191], v179 offset:35840
	ds_read_b128 v[206:209], v179 offset:36864
	ds_read_b128 v[210:213], v179 offset:37888
	ds_read_b128 v[214:217], v179 offset:38912
	ds_read_b128 v[218:221], v179 offset:39936
	s_waitcnt vmcnt(8)
	s_waitcnt lgkmcnt(0)
	s_barrier
	s_setprio 1
	s_waitcnt lgkmcnt(0)
	v_mfma_f32_16x16x32_bf16 v[124:127], v[128:131], v[172:175], v[124:127]
	v_mfma_f32_16x16x32_bf16 v[120:123], v[148:151], v[172:175], v[120:123]
	v_mfma_f32_16x16x32_bf16 v[108:111], v[128:131], v[184:187], v[108:111]
	v_mfma_f32_16x16x32_bf16 v[104:107], v[148:151], v[184:187], v[104:107]
	v_mfma_f32_16x16x32_bf16 v[92:95], v[128:131], v[206:209], v[92:95]
	v_mfma_f32_16x16x32_bf16 v[88:91], v[148:151], v[206:209], v[88:91]
	v_mfma_f32_16x16x32_bf16 v[76:79], v[128:131], v[214:217], v[76:79]
	v_mfma_f32_16x16x32_bf16 v[72:75], v[148:151], v[214:217], v[72:75]
	v_mfma_f32_16x16x32_bf16 v[124:127], v[132:135], v[180:183], v[124:127]
	v_mfma_f32_16x16x32_bf16 v[120:123], v[152:155], v[180:183], v[120:123]
	v_mfma_f32_16x16x32_bf16 v[108:111], v[132:135], v[188:191], v[108:111]
	v_mfma_f32_16x16x32_bf16 v[104:107], v[152:155], v[188:191], v[104:107]
	v_mfma_f32_16x16x32_bf16 v[92:95], v[132:135], v[210:213], v[92:95]
	v_mfma_f32_16x16x32_bf16 v[88:91], v[152:155], v[210:213], v[88:91]
	v_mfma_f32_16x16x32_bf16 v[76:79], v[132:135], v[218:221], v[76:79]
	v_mfma_f32_16x16x32_bf16 v[72:75], v[152:155], v[218:221], v[72:75]
	s_setprio 0
	s_setprio 1
	v_mfma_f32_16x16x32_bf16 v[116:119], v[156:159], v[172:175], v[116:119]
	v_mfma_f32_16x16x32_bf16 v[112:115], v[164:167], v[172:175], v[112:115]
	v_mfma_f32_16x16x32_bf16 v[100:103], v[156:159], v[184:187], v[100:103]
	v_mfma_f32_16x16x32_bf16 v[96:99], v[164:167], v[184:187], v[96:99]
	v_mfma_f32_16x16x32_bf16 v[84:87], v[156:159], v[206:209], v[84:87]
	v_mfma_f32_16x16x32_bf16 v[80:83], v[164:167], v[206:209], v[80:83]
	v_mfma_f32_16x16x32_bf16 v[68:71], v[156:159], v[214:217], v[68:71]
	v_mfma_f32_16x16x32_bf16 v[64:67], v[164:167], v[214:217], v[64:67]
	v_mfma_f32_16x16x32_bf16 v[116:119], v[160:163], v[180:183], v[116:119]
	v_mfma_f32_16x16x32_bf16 v[112:115], v[168:171], v[180:183], v[112:115]
	v_mfma_f32_16x16x32_bf16 v[100:103], v[160:163], v[188:191], v[100:103]
	v_mfma_f32_16x16x32_bf16 v[96:99], v[168:171], v[188:191], v[96:99]
	s_barrier
	s_setprio 2
	v_mfma_f32_16x16x32_bf16 v[84:87], v[160:163], v[210:213], v[84:87]
	v_mfma_f32_16x16x32_bf16 v[80:83], v[168:171], v[210:213], v[80:83]
	v_mfma_f32_16x16x32_bf16 v[68:71], v[160:163], v[218:221], v[68:71]
	v_mfma_f32_16x16x32_bf16 v[64:67], v[168:171], v[218:221], v[64:67]
	s_setprio 0
	s_add_i32 s14, s43, s39
	v_lshl_add_u64 v[194:195], v[194:195], 0, s[16:17]
	s_mov_b32 m0, s14
	s_nop 0
	global_load_lds_dwordx4 v[194:195], off
	s_add_i32 m0, s14, 0x2000
	s_add_u32 s12, s12, 0x80080
	v_lshl_add_u64 v[194:195], v[196:197], 0, s[16:17]
	s_addc_u32 s13, s13, 0
	s_add_i32 s14, s65, s39
	global_load_lds_dwordx4 v[194:195], off
	s_mov_b32 m0, s14
	v_lshl_add_u64 v[194:195], s[12:13], 0, v[138:139]
	global_load_lds_dwordx4 v[194:195], off
	s_add_i32 m0, s14, 0x2000
	v_lshl_add_u64 v[194:195], s[12:13], 0, v[142:143]
	global_load_lds_dwordx4 v[194:195], off
	s_mov_b32 m0, s80
	v_lshl_add_u64 v[194:195], v[202:203], 0, s[16:17]
	global_load_lds_dwordx4 v[194:195], off
	s_mov_b32 m0, s81
	v_lshl_add_u64 v[194:195], v[204:205], 0, s[16:17]
	global_load_lds_dwordx4 v[194:195], off
	ds_read_b128 v[172:175], v179 offset:49152
	ds_read_b128 v[180:183], v179 offset:50176
	ds_read_b128 v[184:187], v179 offset:51200
	ds_read_b128 v[188:191], v179 offset:52224
	ds_read_b128 v[206:209], v179 offset:53248
	ds_read_b128 v[210:213], v179 offset:54272
	ds_read_b128 v[214:217], v179 offset:55296
	ds_read_b128 v[218:221], v179 offset:56320
	s_waitcnt vmcnt(8)
	s_waitcnt lgkmcnt(0)
	s_barrier
; #define PG8_STAGE(bufoff, gbase, voff) do { _Pragma("unroll") for (int _i = 0; _i < 2; ++_i) \
;         __builtin_amdgcn_global_load_lds((const unsigned*)((const char*)(gbase) + (voff)[_i]), (PG8_LAS unsigned*)(lds + (bufoff) + ldsw + _i * 8192), 16, 0, 0); } while (0)
; #define PG8_LDA(dst, b, h) do { _Pragma("unroll") for (int m = 0; m < 4; ++m) _Pragma("unroll") for (int k = 0; k < 2; ++k) dst[m][k] = *(const PG8_LAS bf16x8*)(lds + PG8_SA(b, h) + aoff + m * 2048 + k * 1024); } while (0)
; #define PG8_LDB(dst, b, h) do { _Pragma("unroll") for (int n = 0; n < 2; ++n) _Pragma("unroll") for (int k = 0; k < 2; ++k) dst[n][k] = *(const PG8_LAS bf16x8*)(lds + PG8_SB(b, h) + boff + n * 2048 + k * 1024); } while (0)
; #define PG8_MMA(ai, bj, At, Bt) do { __builtin_amdgcn_s_setprio(1); _Pragma("unroll") for (int m = 0; m < 4; ++m) _Pragma("unroll") for (int n = 0; n < 2; ++n) _Pragma("unroll") for (int k = 0; k < 2; ++k) \
;         acc[ai][bj][m][n] = __builtin_amdgcn_mfma_f32_16x16x32_bf16(Bt[n][k], At[m][k], acc[ai][bj][m][n], 0, 0, 0); __builtin_amdgcn_s_setprio(0); } while (0)
; #define PG8_WAIT_V(n) asm volatile("s_waitcnt vmcnt(" #n ")" ::: "memory")
; #define PG8_WAIT_L(n) asm volatile("s_waitcnt lgkmcnt(" #n ")" ::: "memory")
; #define PG8_BAR __builtin_amdgcn_s_barrier()
; #define PG8_SCHED __builtin_amdgcn_sched_barrier(0)
; template <class Epi, class Sched, bool ALIGN_EPI = false, bool SP2 = false>
; __device__ __forceinline__ void gemm_phase(PG8_LAS unsigned char* lds, const Gemm g, const Sched& S, const Epi& E) {
;     ...
;         for (int t = 0; t < nt; t += 2) {
;             if constexpr (Epi::MID_HOOK) { if (t == Epi::MID_T) E.mid(acc, cur, wr, wc, fr, fq); }
;             const bool last = (t == nt - 2);
;             const char* a1 = cA + (size_t)(t + 1) * kstep;
;             const char* a2 = last ? nA : cA + (size_t)(t + 2) * kstep; const char* b2 = last ? nB : cB + (size_t)(t + 2) * kstep;
;             const char* a3 = a2 + kstep; const char* b3 = b2 + kstep;
;             if (last && has_next) S.a_ready(nxt);
;             if constexpr (SP2) {
;             PG8_LDB(B0, 0, 0); PG8_LDB(B1, 0, 1); PG8_SCHED; PG8_LDA(At, 0, 0); PG8_STAGE(PG8_SA(1, 1), a1 + hstep, voffA);
;             PG8_WAIT_V(8); PG8_WAIT_L(0); PG8_BAR; PG8_MMA(0, 0, At, B0); PG8_MMA(0, 1, At, B1); PG8_BAR; PG8_SCHED;
	s_setprio 1
	s_waitcnt lgkmcnt(0)
	v_mfma_f32_16x16x32_bf16 v[60:63], v[128:131], v[172:175], v[60:63]
	v_mfma_f32_16x16x32_bf16 v[56:59], v[148:151], v[172:175], v[56:59]
	v_mfma_f32_16x16x32_bf16 v[44:47], v[128:131], v[184:187], v[44:47]
	v_mfma_f32_16x16x32_bf16 v[40:43], v[148:151], v[184:187], v[40:43]
	v_mfma_f32_16x16x32_bf16 v[28:31], v[128:131], v[206:209], v[28:31]
	v_mfma_f32_16x16x32_bf16 v[24:27], v[148:151], v[206:209], v[24:27]
	v_mfma_f32_16x16x32_bf16 v[12:15], v[128:131], v[214:217], v[12:15]
	v_mfma_f32_16x16x32_bf16 v[8:11], v[148:151], v[214:217], v[8:11]
	v_mfma_f32_16x16x32_bf16 v[60:63], v[132:135], v[180:183], v[60:63]
	v_mfma_f32_16x16x32_bf16 v[56:59], v[152:155], v[180:183], v[56:59]
	v_mfma_f32_16x16x32_bf16 v[44:47], v[132:135], v[188:191], v[44:47]
	v_mfma_f32_16x16x32_bf16 v[40:43], v[152:155], v[188:191], v[40:43]
	v_mfma_f32_16x16x32_bf16 v[28:31], v[132:135], v[210:213], v[28:31]
	v_mfma_f32_16x16x32_bf16 v[24:27], v[152:155], v[210:213], v[24:27]
	v_mfma_f32_16x16x32_bf16 v[12:15], v[132:135], v[218:221], v[12:15]
	v_mfma_f32_16x16x32_bf16 v[8:11], v[152:155], v[218:221], v[8:11]
	s_setprio 0
	s_setprio 1
	v_mfma_f32_16x16x32_bf16 v[52:55], v[156:159], v[172:175], v[52:55]
	v_mfma_f32_16x16x32_bf16 v[48:51], v[164:167], v[172:175], v[48:51]
	v_mfma_f32_16x16x32_bf16 v[36:39], v[156:159], v[184:187], v[36:39]
	v_mfma_f32_16x16x32_bf16 v[32:35], v[164:167], v[184:187], v[32:35]
	v_mfma_f32_16x16x32_bf16 v[20:23], v[156:159], v[206:209], v[20:23]
	v_mfma_f32_16x16x32_bf16 v[16:19], v[164:167], v[206:209], v[16:19]
	v_mfma_f32_16x16x32_bf16 v[4:7], v[156:159], v[214:217], v[4:7]
	v_mfma_f32_16x16x32_bf16 v[0:3], v[164:167], v[214:217], v[0:3]
	v_mfma_f32_16x16x32_bf16 v[52:55], v[160:163], v[180:183], v[52:55]
	v_mfma_f32_16x16x32_bf16 v[48:51], v[168:171], v[180:183], v[48:51]
	v_mfma_f32_16x16x32_bf16 v[36:39], v[160:163], v[188:191], v[36:39]
	v_mfma_f32_16x16x32_bf16 v[32:35], v[168:171], v[188:191], v[32:35]
	s_barrier
	s_setprio 2
	v_mfma_f32_16x16x32_bf16 v[20:23], v[160:163], v[210:213], v[20:23]
	v_mfma_f32_16x16x32_bf16 v[16:19], v[168:171], v[210:213], v[16:19]
	v_mfma_f32_16x16x32_bf16 v[4:7], v[160:163], v[218:221], v[4:7]
	v_mfma_f32_16x16x32_bf16 v[0:3], v[168:171], v[218:221], v[0:3]
	s_setprio 0
	s_add_i32 s42, s42, 2
	s_add_u32 s0, s0, 0x100
	s_addc_u32 s1, s1, 0
	s_add_u32 s34, s34, 0x100
	s_addc_u32 s41, s41, 0
	s_cmp_gt_u32 s42, 29
	s_branch .LBB0_129
.LBB0_129:
	v_lshl_add_u64 v[194:195], s[0:1], 0, v[144:145]
	s_add_i32 m0, s74, 0xc000
	s_nop 0
	global_load_lds_dwordx4 v[194:195], off
	s_add_i32 m0, s74, 0xe000
	v_lshl_add_u64 v[194:195], s[0:1], 0, v[146:147]
	global_load_lds_dwordx4 v[194:195], off
	s_add_u32 s12, s0, 0xfff80080
	s_addc_u32 s13, s1, -1
	s_add_i32 s43, 0, 0x10000
	s_cmp_eq_u32 s42, 28
	s_cselect_b32 s15, s2, s13
	s_cselect_b32 s14, s11, s12
	s_cselect_b32 s13, s18, s41
	s_cselect_b32 s12, s19, s34
	s_add_i32 s65, 0, 0x14000
	v_add_u32_e32 v152, 0x10000, v178
	v_add_u32_e32 v168, 0x14000, v178
	ds_read_b128 v[128:131], v152
	ds_read_b128 v[132:135], v152 offset:1024
	ds_read_b128 v[148:151], v152 offset:2048
	ds_read_b128 v[152:155], v152 offset:3072
	ds_read_b128 v[156:159], v168
	ds_read_b128 v[160:163], v168 offset:1024
	ds_read_b128 v[164:167], v168 offset:2048
	ds_read_b128 v[168:171], v168 offset:3072
	ds_read_b128 v[172:175], v179
	ds_read_b128 v[180:183], v179 offset:1024
	ds_read_b128 v[184:187], v179 offset:2048
	ds_read_b128 v[188:191], v179 offset:3072
	ds_read_b128 v[206:209], v179 offset:4096
	ds_read_b128 v[210:213], v179 offset:5120
	ds_read_b128 v[214:217], v179 offset:6144
	ds_read_b128 v[218:221], v179 offset:7168
	s_waitcnt vmcnt(8)
	s_waitcnt lgkmcnt(0)
	s_barrier
	s_setprio 1
	s_waitcnt lgkmcnt(0)
	v_mfma_f32_16x16x32_bf16 v[124:127], v[128:131], v[172:175], v[124:127]
	v_mfma_f32_16x16x32_bf16 v[120:123], v[148:151], v[172:175], v[120:123]
	v_mfma_f32_16x16x32_bf16 v[108:111], v[128:131], v[184:187], v[108:111]
	v_mfma_f32_16x16x32_bf16 v[104:107], v[148:151], v[184:187], v[104:107]
	v_mfma_f32_16x16x32_bf16 v[92:95], v[128:131], v[206:209], v[92:95]
	v_mfma_f32_16x16x32_bf16 v[88:91], v[148:151], v[206:209], v[88:91]
	v_mfma_f32_16x16x32_bf16 v[76:79], v[128:131], v[214:217], v[76:79]
	v_mfma_f32_16x16x32_bf16 v[72:75], v[148:151], v[214:217], v[72:75]
	v_mfma_f32_16x16x32_bf16 v[124:127], v[132:135], v[180:183], v[124:127]
	v_mfma_f32_16x16x32_bf16 v[120:123], v[152:155], v[180:183], v[120:123]
	v_mfma_f32_16x16x32_bf16 v[108:111], v[132:135], v[188:191], v[108:111]
	v_mfma_f32_16x16x32_bf16 v[104:107], v[152:155], v[188:191], v[104:107]
	v_mfma_f32_16x16x32_bf16 v[92:95], v[132:135], v[210:213], v[92:95]
	v_mfma_f32_16x16x32_bf16 v[88:91], v[152:155], v[210:213], v[88:91]
	v_mfma_f32_16x16x32_bf16 v[76:79], v[132:135], v[218:221], v[76:79]
	v_mfma_f32_16x16x32_bf16 v[72:75], v[152:155], v[218:221], v[72:75]
	s_setprio 0
	s_setprio 1
	v_mfma_f32_16x16x32_bf16 v[116:119], v[156:159], v[172:175], v[116:119]
	v_mfma_f32_16x16x32_bf16 v[112:115], v[164:167], v[172:175], v[112:115]
	v_mfma_f32_16x16x32_bf16 v[100:103], v[156:159], v[184:187], v[100:103]
	v_mfma_f32_16x16x32_bf16 v[96:99], v[164:167], v[184:187], v[96:99]
	v_mfma_f32_16x16x32_bf16 v[84:87], v[156:159], v[206:209], v[84:87]
	v_mfma_f32_16x16x32_bf16 v[80:83], v[164:167], v[206:209], v[80:83]
	v_mfma_f32_16x16x32_bf16 v[68:71], v[156:159], v[214:217], v[68:71]
	v_mfma_f32_16x16x32_bf16 v[64:67], v[164:167], v[214:217], v[64:67]
	v_mfma_f32_16x16x32_bf16 v[116:119], v[160:163], v[180:183], v[116:119]
	v_mfma_f32_16x16x32_bf16 v[112:115], v[168:171], v[180:183], v[112:115]
	v_mfma_f32_16x16x32_bf16 v[100:103], v[160:163], v[188:191], v[100:103]
	v_mfma_f32_16x16x32_bf16 v[96:99], v[168:171], v[188:191], v[96:99]
	s_barrier
; #define PG8_STAGE(bufoff, gbase, voff) do { _Pragma("unroll") for (int _i = 0; _i < 2; ++_i) \
;         __builtin_amdgcn_global_load_lds((const unsigned*)((const char*)(gbase) + (voff)[_i]), (PG8_LAS unsigned*)(lds + (bufoff) + ldsw + _i * 8192), 16, 0, 0); } while (0)
; #define PG8_LDA(dst, b, h) do { _Pragma("unroll") for (int m = 0; m < 4; ++m) _Pragma("unroll") for (int k = 0; k < 2; ++k) dst[m][k] = *(const PG8_LAS bf16x8*)(lds + PG8_SA(b, h) + aoff + m * 2048 + k * 1024); } while (0)
; #define PG8_LDB(dst, b, h) do { _Pragma("unroll") for (int n = 0; n < 2; ++n) _Pragma("unroll") for (int k = 0; k < 2; ++k) dst[n][k] = *(const PG8_LAS bf16x8*)(lds + PG8_SB(b, h) + boff + n * 2048 + k * 1024); } while (0)
; #define PG8_MMA(ai, bj, At, Bt) do { __builtin_amdgcn_s_setprio(1); _Pragma("unroll") for (int m = 0; m < 4; ++m) _Pragma("unroll") for (int n = 0; n < 2; ++n) _Pragma("unroll") for (int k = 0; k < 2; ++k) \
;         acc[ai][bj][m][n] = __builtin_amdgcn_mfma_f32_16x16x32_bf16(Bt[n][k], At[m][k], acc[ai][bj][m][n], 0, 0, 0); __builtin_amdgcn_s_setprio(0); } while (0)
; #define PG8_WAIT_V(n) asm volatile("s_waitcnt vmcnt(" #n ")" ::: "memory")
; #define PG8_WAIT_L(n) asm volatile("s_waitcnt lgkmcnt(" #n ")" ::: "memory")
; #define PG8_BAR __builtin_amdgcn_s_barrier()
; #define PG8_SCHED __builtin_amdgcn_sched_barrier(0)
; template <class Epi, class Sched, bool ALIGN_EPI = false, bool SP2 = false>
; __device__ __forceinline__ void gemm_phase(PG8_LAS unsigned char* lds, const Gemm g, const Sched& S, const Epi& E) {
;     ...
;             PG8_WAIT_V(8); PG8_WAIT_L(0); PG8_BAR; PG8_MMA(0, 0, At, B0); PG8_MMA(0, 1, At, B1); PG8_BAR; PG8_SCHED;
;             PG8_LDA(At, 0, 1); PG8_STAGE(PG8_SB(0, 0), b2, voffB); PG8_STAGE(PG8_SB(0, 1), b2 + hstep, voffB); PG8_STAGE(PG8_SA(0, 0), a2, voffA);
;             PG8_WAIT_V(8); PG8_WAIT_L(0); PG8_BAR; PG8_MMA(1, 0, At, B0); PG8_MMA(1, 1, At, B1); PG8_BAR; PG8_SCHED;
;             PG8_LDB(B0, 1, 0); PG8_LDB(B1, 1, 1); PG8_SCHED; PG8_LDA(At, 1, 0); PG8_STAGE(PG8_SA(0, 1), a2 + hstep, voffA);
	s_setprio 2
	v_mfma_f32_16x16x32_bf16 v[84:87], v[160:163], v[210:213], v[84:87]
	v_mfma_f32_16x16x32_bf16 v[80:83], v[168:171], v[210:213], v[80:83]
	v_mfma_f32_16x16x32_bf16 v[68:71], v[160:163], v[218:221], v[68:71]
	v_mfma_f32_16x16x32_bf16 v[64:67], v[168:171], v[218:221], v[64:67]
	s_setprio 0
	s_add_i32 s43, s43, s39
	v_lshl_add_u64 v[194:195], s[12:13], 0, v[138:139]
	s_mov_b32 m0, s43
	s_nop 0
	global_load_lds_dwordx4 v[194:195], off
	s_add_i32 m0, s43, 0x2000
	s_add_u32 s86, s12, 0x80000
	v_lshl_add_u64 v[196:197], s[12:13], 0, v[142:143]
	s_addc_u32 s87, s13, 0
	s_add_i32 s43, s65, s39
	global_load_lds_dwordx4 v[196:197], off
	v_lshl_add_u64 v[202:203], s[86:87], 0, v[138:139]
	s_mov_b32 m0, s43
	v_lshl_add_u64 v[204:205], s[14:15], 0, v[140:141]
	global_load_lds_dwordx4 v[202:203], off
	s_add_i32 m0, s43, 0x2000
	v_lshl_add_u64 v[202:203], s[86:87], 0, v[142:143]
	global_load_lds_dwordx4 v[202:203], off
	s_mov_b32 m0, s74
	v_lshl_add_u64 v[202:203], s[14:15], 0, v[136:137]
	global_load_lds_dwordx4 v[202:203], off
	s_mov_b32 m0, s75
	s_nop 0
	global_load_lds_dwordx4 v[204:205], off
	ds_read_b128 v[172:175], v179 offset:16384
	ds_read_b128 v[180:183], v179 offset:17408
	ds_read_b128 v[184:187], v179 offset:18432
	ds_read_b128 v[188:191], v179 offset:19456
	ds_read_b128 v[206:209], v179 offset:20480
	ds_read_b128 v[210:213], v179 offset:21504
	ds_read_b128 v[214:217], v179 offset:22528
	ds_read_b128 v[218:221], v179 offset:23552
	s_waitcnt vmcnt(8)
	s_waitcnt lgkmcnt(0)
	s_barrier
	s_setprio 1
	s_waitcnt lgkmcnt(0)
	v_mfma_f32_16x16x32_bf16 v[60:63], v[128:131], v[172:175], v[60:63]
	v_mfma_f32_16x16x32_bf16 v[56:59], v[148:151], v[172:175], v[56:59]
	v_mfma_f32_16x16x32_bf16 v[44:47], v[128:131], v[184:187], v[44:47]
	v_mfma_f32_16x16x32_bf16 v[40:43], v[148:151], v[184:187], v[40:43]
	v_mfma_f32_16x16x32_bf16 v[28:31], v[128:131], v[206:209], v[28:31]
	v_mfma_f32_16x16x32_bf16 v[24:27], v[148:151], v[206:209], v[24:27]
	v_mfma_f32_16x16x32_bf16 v[12:15], v[128:131], v[214:217], v[12:15]
	v_mfma_f32_16x16x32_bf16 v[8:11], v[148:151], v[214:217], v[8:11]
	v_mfma_f32_16x16x32_bf16 v[60:63], v[132:135], v[180:183], v[60:63]
	v_mfma_f32_16x16x32_bf16 v[56:59], v[152:155], v[180:183], v[56:59]
	v_mfma_f32_16x16x32_bf16 v[44:47], v[132:135], v[188:191], v[44:47]
	v_mfma_f32_16x16x32_bf16 v[40:43], v[152:155], v[188:191], v[40:43]
	v_mfma_f32_16x16x32_bf16 v[28:31], v[132:135], v[210:213], v[28:31]
	v_mfma_f32_16x16x32_bf16 v[24:27], v[152:155], v[210:213], v[24:27]
	v_mfma_f32_16x16x32_bf16 v[12:15], v[132:135], v[218:221], v[12:15]
	v_mfma_f32_16x16x32_bf16 v[8:11], v[152:155], v[218:221], v[8:11]
	s_setprio 0
	s_setprio 1
	v_mfma_f32_16x16x32_bf16 v[52:55], v[156:159], v[172:175], v[52:55]
	v_mfma_f32_16x16x32_bf16 v[48:51], v[164:167], v[172:175], v[48:51]
	v_mfma_f32_16x16x32_bf16 v[36:39], v[156:159], v[184:187], v[36:39]
	v_mfma_f32_16x16x32_bf16 v[32:35], v[164:167], v[184:187], v[32:35]
	v_mfma_f32_16x16x32_bf16 v[20:23], v[156:159], v[206:209], v[20:23]
	v_mfma_f32_16x16x32_bf16 v[16:19], v[164:167], v[206:209], v[16:19]
	v_mfma_f32_16x16x32_bf16 v[4:7], v[156:159], v[214:217], v[4:7]
	v_mfma_f32_16x16x32_bf16 v[0:3], v[164:167], v[214:217], v[0:3]
	v_mfma_f32_16x16x32_bf16 v[52:55], v[160:163], v[180:183], v[52:55]
	v_mfma_f32_16x16x32_bf16 v[48:51], v[168:171], v[180:183], v[48:51]
	v_mfma_f32_16x16x32_bf16 v[36:39], v[160:163], v[188:191], v[36:39]
	v_mfma_f32_16x16x32_bf16 v[32:35], v[168:171], v[188:191], v[32:35]
	s_barrier
	s_setprio 2
	v_mfma_f32_16x16x32_bf16 v[20:23], v[160:163], v[210:213], v[20:23]
	v_mfma_f32_16x16x32_bf16 v[16:19], v[168:171], v[210:213], v[16:19]
	v_mfma_f32_16x16x32_bf16 v[4:7], v[160:163], v[218:221], v[4:7]
	v_mfma_f32_16x16x32_bf16 v[0:3], v[168:171], v[218:221], v[0:3]
	s_setprio 0
	s_add_i32 s43, 0, 0x18000
	s_add_i32 s65, 0, 0x1c000
	s_add_u32 s14, s14, 0x80000
	s_addc_u32 s15, s15, 0
	s_mov_b32 m0, s76
	v_lshl_add_u64 v[232:233], s[14:15], 0, v[136:137]
	global_load_lds_dwordx4 v[232:233], off
	s_mov_b32 m0, s77
	v_lshl_add_u64 v[232:233], s[14:15], 0, v[140:141]
	global_load_lds_dwordx4 v[232:233], off
	v_add_u32_e32 v152, 0x18000, v178
	v_add_u32_e32 v168, 0x1c000, v178
	ds_read_b128 v[128:131], v152
	ds_read_b128 v[132:135], v152 offset:1024
	ds_read_b128 v[148:151], v152 offset:2048
	ds_read_b128 v[152:155], v152 offset:3072
	ds_read_b128 v[156:159], v168
	ds_read_b128 v[160:163], v168 offset:1024
	ds_read_b128 v[164:167], v168 offset:2048
	ds_read_b128 v[168:171], v168 offset:3072
	ds_read_b128 v[172:175], v179 offset:32768
	ds_read_b128 v[180:183], v179 offset:33792
	ds_read_b128 v[184:187], v179 offset:34816
	ds_read_b128 v[188:191], v179 offset:35840
	ds_read_b128 v[206:209], v179 offset:36864
	ds_read_b128 v[210:213], v179 offset:37888
	ds_read_b128 v[214:217], v179 offset:38912
	ds_read_b128 v[218:221], v179 offset:39936
	s_waitcnt vmcnt(8)
	s_waitcnt lgkmcnt(0)
	s_barrier
; #define PG8_STAGE(bufoff, gbase, voff) do { _Pragma("unroll") for (int _i = 0; _i < 2; ++_i) \
;         __builtin_amdgcn_global_load_lds((const unsigned*)((const char*)(gbase) + (voff)[_i]), (PG8_LAS unsigned*)(lds + (bufoff) + ldsw + _i * 8192), 16, 0, 0); } while (0)
; #define PG8_LDA(dst, b, h) do { _Pragma("unroll") for (int m = 0; m < 4; ++m) _Pragma("unroll") for (int k = 0; k < 2; ++k) dst[m][k] = *(const PG8_LAS bf16x8*)(lds + PG8_SA(b, h) + aoff + m * 2048 + k * 1024); } while (0)
; #define PG8_MMA(ai, bj, At, Bt) do { __builtin_amdgcn_s_setprio(1); _Pragma("unroll") for (int m = 0; m < 4; ++m) _Pragma("unroll") for (int n = 0; n < 2; ++n) _Pragma("unroll") for (int k = 0; k < 2; ++k) \
;         acc[ai][bj][m][n] = __builtin_amdgcn_mfma_f32_16x16x32_bf16(Bt[n][k], At[m][k], acc[ai][bj][m][n], 0, 0, 0); __builtin_amdgcn_s_setprio(0); } while (0)
; #define PG8_WAIT_V(n) asm volatile("s_waitcnt vmcnt(" #n ")" ::: "memory")
; #define PG8_WAIT_L(n) asm volatile("s_waitcnt lgkmcnt(" #n ")" ::: "memory")
; #define PG8_BAR __builtin_amdgcn_s_barrier()
; #define PG8_SCHED __builtin_amdgcn_sched_barrier(0)
; template <class Epi, class Sched, bool ALIGN_EPI = false, bool SP2 = false>
; __device__ __forceinline__ void gemm_phase(PG8_LAS unsigned char* lds, const Gemm g, const Sched& S, const Epi& E) {
;     ...
;             PG8_WAIT_V(8); PG8_WAIT_L(0); PG8_BAR; PG8_MMA(0, 0, At, B0); PG8_MMA(0, 1, At, B1); PG8_BAR; PG8_SCHED;
;             PG8_LDA(At, 1, 1); PG8_STAGE(PG8_SB(1, 0), b3, voffB); PG8_STAGE(PG8_SB(1, 1), b3 + hstep, voffB); PG8_STAGE(PG8_SA(1, 0), a3, voffA);
;             PG8_WAIT_V(8); PG8_WAIT_L(0); PG8_BAR; PG8_MMA(1, 0, At, B0); PG8_MMA(1, 1, At, B1); PG8_BAR; PG8_SCHED;
;     ...
;         if constexpr (ALIGN_EPI) { if (wr == 0) PG8_BAR; }
	s_setprio 1
	s_waitcnt lgkmcnt(0)
	v_mfma_f32_16x16x32_bf16 v[124:127], v[128:131], v[172:175], v[124:127]
	v_mfma_f32_16x16x32_bf16 v[120:123], v[148:151], v[172:175], v[120:123]
	v_mfma_f32_16x16x32_bf16 v[108:111], v[128:131], v[184:187], v[108:111]
	v_mfma_f32_16x16x32_bf16 v[104:107], v[148:151], v[184:187], v[104:107]
	v_mfma_f32_16x16x32_bf16 v[92:95], v[128:131], v[206:209], v[92:95]
	v_mfma_f32_16x16x32_bf16 v[88:91], v[148:151], v[206:209], v[88:91]
	v_mfma_f32_16x16x32_bf16 v[76:79], v[128:131], v[214:217], v[76:79]
	v_mfma_f32_16x16x32_bf16 v[72:75], v[148:151], v[214:217], v[72:75]
	v_mfma_f32_16x16x32_bf16 v[124:127], v[132:135], v[180:183], v[124:127]
	v_mfma_f32_16x16x32_bf16 v[120:123], v[152:155], v[180:183], v[120:123]
	v_mfma_f32_16x16x32_bf16 v[108:111], v[132:135], v[188:191], v[108:111]
	v_mfma_f32_16x16x32_bf16 v[104:107], v[152:155], v[188:191], v[104:107]
	v_mfma_f32_16x16x32_bf16 v[92:95], v[132:135], v[210:213], v[92:95]
	v_mfma_f32_16x16x32_bf16 v[88:91], v[152:155], v[210:213], v[88:91]
	v_mfma_f32_16x16x32_bf16 v[76:79], v[132:135], v[218:221], v[76:79]
	v_mfma_f32_16x16x32_bf16 v[72:75], v[152:155], v[218:221], v[72:75]
	s_setprio 0
	s_setprio 1
	v_mfma_f32_16x16x32_bf16 v[116:119], v[156:159], v[172:175], v[116:119]
	v_mfma_f32_16x16x32_bf16 v[112:115], v[164:167], v[172:175], v[112:115]
	v_mfma_f32_16x16x32_bf16 v[100:103], v[156:159], v[184:187], v[100:103]
	v_mfma_f32_16x16x32_bf16 v[96:99], v[164:167], v[184:187], v[96:99]
	v_mfma_f32_16x16x32_bf16 v[84:87], v[156:159], v[206:209], v[84:87]
	v_mfma_f32_16x16x32_bf16 v[80:83], v[164:167], v[206:209], v[80:83]
	v_mfma_f32_16x16x32_bf16 v[68:71], v[156:159], v[214:217], v[68:71]
	v_mfma_f32_16x16x32_bf16 v[64:67], v[164:167], v[214:217], v[64:67]
	v_mfma_f32_16x16x32_bf16 v[116:119], v[160:163], v[180:183], v[116:119]
	v_mfma_f32_16x16x32_bf16 v[112:115], v[168:171], v[180:183], v[112:115]
	v_mfma_f32_16x16x32_bf16 v[100:103], v[160:163], v[188:191], v[100:103]
	v_mfma_f32_16x16x32_bf16 v[96:99], v[168:171], v[188:191], v[96:99]
	s_barrier
	s_setprio 2
	v_mfma_f32_16x16x32_bf16 v[84:87], v[160:163], v[210:213], v[84:87]
	v_mfma_f32_16x16x32_bf16 v[80:83], v[168:171], v[210:213], v[80:83]
	v_mfma_f32_16x16x32_bf16 v[68:71], v[160:163], v[218:221], v[68:71]
	v_mfma_f32_16x16x32_bf16 v[64:67], v[168:171], v[218:221], v[64:67]
	s_setprio 0
	s_add_i32 s14, s43, s39
	v_lshl_add_u64 v[194:195], v[194:195], 0, s[16:17]
	s_mov_b32 m0, s14
	s_nop 0
	global_load_lds_dwordx4 v[194:195], off
	s_add_i32 m0, s14, 0x2000
	s_add_u32 s12, s12, 0x80080
	v_lshl_add_u64 v[194:195], v[196:197], 0, s[16:17]
	s_addc_u32 s13, s13, 0
	s_add_i32 s14, s65, s39
	global_load_lds_dwordx4 v[194:195], off
	s_mov_b32 m0, s14
	v_lshl_add_u64 v[194:195], s[12:13], 0, v[138:139]
	global_load_lds_dwordx4 v[194:195], off
	s_add_i32 m0, s14, 0x2000
	v_lshl_add_u64 v[194:195], s[12:13], 0, v[142:143]
	global_load_lds_dwordx4 v[194:195], off
	s_mov_b32 m0, s80
	v_lshl_add_u64 v[194:195], v[202:203], 0, s[16:17]
	global_load_lds_dwordx4 v[194:195], off
	s_mov_b32 m0, s81
	v_lshl_add_u64 v[194:195], v[204:205], 0, s[16:17]
	global_load_lds_dwordx4 v[194:195], off
	ds_read_b128 v[172:175], v179 offset:49152
	ds_read_b128 v[180:183], v179 offset:50176
	ds_read_b128 v[184:187], v179 offset:51200
	ds_read_b128 v[188:191], v179 offset:52224
	ds_read_b128 v[206:209], v179 offset:53248
	ds_read_b128 v[210:213], v179 offset:54272
	ds_read_b128 v[214:217], v179 offset:55296
	ds_read_b128 v[218:221], v179 offset:56320
	s_waitcnt vmcnt(8)
	s_waitcnt lgkmcnt(0)
	s_barrier
	s_setprio 1
	s_waitcnt lgkmcnt(0)
	v_mfma_f32_16x16x32_bf16 v[60:63], v[128:131], v[172:175], v[60:63]
	v_mfma_f32_16x16x32_bf16 v[56:59], v[148:151], v[172:175], v[56:59]
	v_mfma_f32_16x16x32_bf16 v[44:47], v[128:131], v[184:187], v[44:47]
	v_mfma_f32_16x16x32_bf16 v[40:43], v[148:151], v[184:187], v[40:43]
	v_mfma_f32_16x16x32_bf16 v[28:31], v[128:131], v[206:209], v[28:31]
	v_mfma_f32_16x16x32_bf16 v[24:27], v[148:151], v[206:209], v[24:27]
	v_mfma_f32_16x16x32_bf16 v[12:15], v[128:131], v[214:217], v[12:15]
	v_mfma_f32_16x16x32_bf16 v[8:11], v[148:151], v[214:217], v[8:11]
	v_mfma_f32_16x16x32_bf16 v[60:63], v[132:135], v[180:183], v[60:63]
	v_mfma_f32_16x16x32_bf16 v[56:59], v[152:155], v[180:183], v[56:59]
	v_mfma_f32_16x16x32_bf16 v[44:47], v[132:135], v[188:191], v[44:47]
	v_mfma_f32_16x16x32_bf16 v[40:43], v[152:155], v[188:191], v[40:43]
	v_mfma_f32_16x16x32_bf16 v[28:31], v[132:135], v[210:213], v[28:31]
	v_mfma_f32_16x16x32_bf16 v[24:27], v[152:155], v[210:213], v[24:27]
	v_mfma_f32_16x16x32_bf16 v[12:15], v[132:135], v[218:221], v[12:15]
	v_mfma_f32_16x16x32_bf16 v[8:11], v[152:155], v[218:221], v[8:11]
	s_setprio 0
	s_setprio 1
	v_mfma_f32_16x16x32_bf16 v[52:55], v[156:159], v[172:175], v[52:55]
	v_mfma_f32_16x16x32_bf16 v[48:51], v[164:167], v[172:175], v[48:51]
	v_mfma_f32_16x16x32_bf16 v[36:39], v[156:159], v[184:187], v[36:39]
	v_mfma_f32_16x16x32_bf16 v[32:35], v[164:167], v[184:187], v[32:35]
	v_mfma_f32_16x16x32_bf16 v[20:23], v[156:159], v[206:209], v[20:23]
	v_mfma_f32_16x16x32_bf16 v[16:19], v[164:167], v[206:209], v[16:19]
	v_mfma_f32_16x16x32_bf16 v[4:7], v[156:159], v[214:217], v[4:7]
	v_mfma_f32_16x16x32_bf16 v[0:3], v[164:167], v[214:217], v[0:3]
	v_mfma_f32_16x16x32_bf16 v[52:55], v[160:163], v[180:183], v[52:55]
	v_mfma_f32_16x16x32_bf16 v[48:51], v[168:171], v[180:183], v[48:51]
	v_mfma_f32_16x16x32_bf16 v[36:39], v[160:163], v[188:191], v[36:39]
	v_mfma_f32_16x16x32_bf16 v[32:35], v[168:171], v[188:191], v[32:35]
	s_barrier
	s_setprio 2
	v_mfma_f32_16x16x32_bf16 v[20:23], v[160:163], v[210:213], v[20:23]
	v_mfma_f32_16x16x32_bf16 v[16:19], v[168:171], v[210:213], v[16:19]
	v_mfma_f32_16x16x32_bf16 v[4:7], v[160:163], v[218:221], v[4:7]
	v_mfma_f32_16x16x32_bf16 v[0:3], v[168:171], v[218:221], v[0:3]
	s_setprio 0
	s_add_i32 s42, s42, 2
	s_add_u32 s0, s0, 0x100
	s_addc_u32 s1, s1, 0
	s_add_u32 s34, s34, 0x100
	s_addc_u32 s41, s41, 0
	s_cmp_gt_u32 s42, 29
	s_cbranch_scc0 .LBB0_129
	s_and_b64 vcc, exec, s[62:63]
	s_cbranch_vccz .LBB0_132
	s_barrier

; #define PG8_STAGE(bufoff, gbase, voff) do { _Pragma("unroll") for (int _i = 0; _i < 2; ++_i) \
;         __builtin_amdgcn_global_load_lds((const unsigned*)((const char*)(gbase) + (voff)[_i]), (PG8_LAS unsigned*)(lds + (bufoff) + ldsw + _i * 8192), 16, 0, 0); } while (0)
; #define PG8_LDA(dst, b, h) do { _Pragma("unroll") for (int m = 0; m < 4; ++m) _Pragma("unroll") for (int k = 0; k < 2; ++k) dst[m][k] = *(const PG8_LAS bf16x8*)(lds + PG8_SA(b, h) + aoff + m * 2048 + k * 1024); } while (0)
; #define PG8_LDB(dst, b, h) do { _Pragma("unroll") for (int n = 0; n < 2; ++n) _Pragma("unroll") for (int k = 0; k < 2; ++k) dst[n][k] = *(const PG8_LAS bf16x8*)(lds + PG8_SB(b, h) + boff + n * 2048 + k * 1024); } while (0)
; #define PG8_WAIT_V(n) asm volatile("s_waitcnt vmcnt(" #n ")" ::: "memory")
; #define PG8_WAIT_L(n) asm volatile("s_waitcnt lgkmcnt(" #n ")" ::: "memory")
; #define PG8_BAR __builtin_amdgcn_s_barrier()
; template <class Epi, class Sched, bool ALIGN_EPI = false, bool SP2 = false>
; __device__ __forceinline__ void gemm_phase(PG8_LAS unsigned char* lds, const Gemm g, const Sched& S, const Epi& E) {
;     ...
;         const bool has_next = S.next(ui + 1, nxt);
;         const char* nA = has_next ? (const char*)g.A + (size_t)nxt.pm * tstep : cA; const char* nB = has_next ? (const char*)g.Bt + (size_t)nxt.pn * tstep : cB;
;         for (int t = 0; t < nt; t += 2) {
;             if constexpr (Epi::MID_HOOK) { if (t == Epi::MID_T) E.mid(acc, cur, wr, wc, fr, fq); }
;             const bool last = (t == nt - 2);
;             const char* a1 = cA + (size_t)(t + 1) * kstep;
;             const char* a2 = last ? nA : cA + (size_t)(t + 2) * kstep; const char* b2 = last ? nB : cB + (size_t)(t + 2) * kstep;
;             const char* a3 = a2 + kstep; const char* b3 = b2 + kstep;
;             if (last && has_next) S.a_ready(nxt);
;             if constexpr (SP2) {
;             PG8_LDB(B0, 0, 0); PG8_LDB(B1, 0, 1); PG8_SCHED; PG8_LDA(At, 0, 0); PG8_STAGE(PG8_SA(1, 1), a1 + hstep, voffA);
;             PG8_WAIT_V(8); PG8_WAIT_L(0); PG8_BAR; PG8_MMA(0, 0, At, B0); PG8_MMA(0, 1, At, B1); PG8_BAR; PG8_SCHED;
;             PG8_LDA(At, 0, 1); PG8_STAGE(PG8_SB(0, 0), b2, voffB); PG8_STAGE(PG8_SB(0, 1), b2 + hstep, voffB); PG8_STAGE(PG8_SA(0, 0), a2, voffA);
;             PG8_WAIT_V(8); PG8_WAIT_L(0); PG8_BAR; PG8_MMA(1, 0, At, B0); PG8_MMA(1, 1, At, B1); PG8_BAR; PG8_SCHED;
.LBB0_634:
	s_ashr_i32 s15, s14, 31
	s_lshl_b64 s[18:19], s[14:15], 20
	s_add_u32 s18, s45, s18
	s_addc_u32 s19, s46, s19
	s_and_b64 s[30:31], s[0:1], exec
	s_cselect_b32 s15, s19, s37
	s_cselect_b32 s61, s18, s36
	s_ashr_i32 s13, s12, 31
	s_lshl_b64 s[30:31], s[12:13], 20
	s_add_u32 s30, s34, s30
	s_addc_u32 s31, s44, s31
	s_and_b64 s[42:43], s[0:1], exec
	s_cselect_b32 s13, s31, s39
	s_cselect_b32 s62, s30, s38
	s_add_u32 s36, s36, 0x80080
	s_addc_u32 s37, s37, 0
	s_add_u32 s63, s38, 0x100
	s_addc_u32 s64, s39, 0
	s_mov_b32 s65, -2
	s_waitcnt lgkmcnt(0)
	v_lshl_add_u64 v[168:169], s[36:37], 0, v[160:161]
	s_add_i32 m0, s2, 0xc000
	global_load_lds_dwordx4 v[168:169], off
	s_add_i32 m0, s2, 0xe000
	v_lshl_add_u64 v[168:169], s[36:37], 0, v[162:163]
	global_load_lds_dwordx4 v[168:169], off
	s_add_u32 s24, s36, 0xfff80080
	s_addc_u32 s25, s37, -1
	s_add_i32 s33, 0, 0x10000
	s_cmp_eq_u32 s65, 28
	s_cselect_b32 s43, s15, s25
	s_cselect_b32 s42, s61, s24
	s_cselect_b32 s39, s13, s64
	s_cselect_b32 s38, s62, s63
	s_add_i32 s24, 0, 0x14000
	s_waitcnt vmcnt(8)
	s_waitcnt lgkmcnt(0)
	s_barrier
	s_setprio 1
	s_waitcnt lgkmcnt(0)
	v_mfma_f32_16x16x32_bf16 v[124:127], v[128:131], v[178:181], 0
	v_mfma_f32_16x16x32_bf16 v[120:123], v[136:139], v[178:181], 0
	v_mfma_f32_16x16x32_bf16 v[108:111], v[128:131], v[186:189], 0
	v_mfma_f32_16x16x32_bf16 v[104:107], v[136:139], v[186:189], 0
	v_mfma_f32_16x16x32_bf16 v[92:95], v[128:131], v[202:205], 0
	v_mfma_f32_16x16x32_bf16 v[88:91], v[136:139], v[202:205], 0
	v_mfma_f32_16x16x32_bf16 v[76:79], v[128:131], v[210:213], 0
	v_mfma_f32_16x16x32_bf16 v[72:75], v[136:139], v[210:213], 0
	v_mfma_f32_16x16x32_bf16 v[124:127], v[132:135], v[182:185], v[124:127]
	v_mfma_f32_16x16x32_bf16 v[120:123], v[140:143], v[182:185], v[120:123]
	v_mfma_f32_16x16x32_bf16 v[108:111], v[132:135], v[194:197], v[108:111]
	v_mfma_f32_16x16x32_bf16 v[104:107], v[140:143], v[194:197], v[104:107]
	v_mfma_f32_16x16x32_bf16 v[92:95], v[132:135], v[206:209], v[92:95]
	v_mfma_f32_16x16x32_bf16 v[88:91], v[140:143], v[206:209], v[88:91]
	v_mfma_f32_16x16x32_bf16 v[76:79], v[132:135], v[214:217], v[76:79]
	v_mfma_f32_16x16x32_bf16 v[72:75], v[140:143], v[214:217], v[72:75]
	s_setprio 0
	s_setprio 1
	v_mfma_f32_16x16x32_bf16 v[116:119], v[144:147], v[178:181], 0
	v_mfma_f32_16x16x32_bf16 v[112:115], v[164:167], v[178:181], 0
	v_mfma_f32_16x16x32_bf16 v[100:103], v[144:147], v[186:189], 0
	v_mfma_f32_16x16x32_bf16 v[96:99], v[164:167], v[186:189], 0
	v_mfma_f32_16x16x32_bf16 v[84:87], v[144:147], v[202:205], 0
	v_mfma_f32_16x16x32_bf16 v[80:83], v[164:167], v[202:205], 0
	v_mfma_f32_16x16x32_bf16 v[68:71], v[144:147], v[210:213], 0
	v_mfma_f32_16x16x32_bf16 v[64:67], v[164:167], v[210:213], 0
	v_mfma_f32_16x16x32_bf16 v[116:119], v[148:151], v[182:185], v[116:119]
	v_mfma_f32_16x16x32_bf16 v[112:115], v[174:177], v[182:185], v[112:115]
	v_mfma_f32_16x16x32_bf16 v[100:103], v[148:151], v[194:197], v[100:103]
	v_mfma_f32_16x16x32_bf16 v[96:99], v[174:177], v[194:197], v[96:99]
	s_barrier
	s_setprio 2
	v_mfma_f32_16x16x32_bf16 v[84:87], v[148:151], v[206:209], v[84:87]
	v_mfma_f32_16x16x32_bf16 v[80:83], v[174:177], v[206:209], v[80:83]
	v_mfma_f32_16x16x32_bf16 v[68:71], v[148:151], v[214:217], v[68:71]
	v_mfma_f32_16x16x32_bf16 v[64:67], v[174:177], v[214:217], v[64:67]
	s_setprio 0
	s_add_i32 s25, s33, s47
	v_lshl_add_u64 v[168:169], s[38:39], 0, v[156:157]
	s_mov_b32 m0, s25
	s_nop 0
	global_load_lds_dwordx4 v[168:169], off
	s_add_i32 m0, s25, 0x2000
	s_add_u32 s66, s38, 0x80000
	v_lshl_add_u64 v[190:191], s[38:39], 0, v[152:153]
	s_addc_u32 s67, s39, 0
	s_add_i32 s24, s24, s47
	global_load_lds_dwordx4 v[190:191], off
	v_lshl_add_u64 v[218:219], s[66:67], 0, v[156:157]
	s_mov_b32 m0, s24
	v_lshl_add_u64 v[220:221], s[42:43], 0, v[154:155]
	global_load_lds_dwordx4 v[218:219], off
	s_add_i32 m0, s24, 0x2000
	v_lshl_add_u64 v[218:219], s[66:67], 0, v[152:153]
	global_load_lds_dwordx4 v[218:219], off
	s_mov_b32 m0, s2
	v_lshl_add_u64 v[218:219], s[42:43], 0, v[158:159]
	global_load_lds_dwordx4 v[218:219], off
	s_mov_b32 m0, s48
	s_nop 0
	global_load_lds_dwordx4 v[220:221], off
	ds_read_b128 v[178:181], v173 offset:16384
	ds_read_b128 v[182:185], v173 offset:17408
	ds_read_b128 v[186:189], v173 offset:18432
	ds_read_b128 v[194:197], v173 offset:19456
	ds_read_b128 v[202:205], v173 offset:20480
	ds_read_b128 v[206:209], v173 offset:21504
	ds_read_b128 v[210:213], v173 offset:22528
	ds_read_b128 v[214:217], v173 offset:23552
	s_waitcnt vmcnt(8)
	s_waitcnt lgkmcnt(0)
	s_barrier
	s_setprio 1
	s_waitcnt lgkmcnt(0)
	v_mfma_f32_16x16x32_bf16 v[60:63], v[128:131], v[178:181], 0
	v_mfma_f32_16x16x32_bf16 v[56:59], v[136:139], v[178:181], 0
	v_mfma_f32_16x16x32_bf16 v[44:47], v[128:131], v[186:189], 0
	v_mfma_f32_16x16x32_bf16 v[40:43], v[136:139], v[186:189], 0
	v_mfma_f32_16x16x32_bf16 v[28:31], v[128:131], v[202:205], 0
	v_mfma_f32_16x16x32_bf16 v[24:27], v[136:139], v[202:205], 0
	v_mfma_f32_16x16x32_bf16 v[12:15], v[128:131], v[210:213], 0
	v_mfma_f32_16x16x32_bf16 v[8:11], v[136:139], v[210:213], 0
	v_mfma_f32_16x16x32_bf16 v[60:63], v[132:135], v[182:185], v[60:63]
	v_mfma_f32_16x16x32_bf16 v[56:59], v[140:143], v[182:185], v[56:59]
	v_mfma_f32_16x16x32_bf16 v[44:47], v[132:135], v[194:197], v[44:47]
	v_mfma_f32_16x16x32_bf16 v[40:43], v[140:143], v[194:197], v[40:43]
	v_mfma_f32_16x16x32_bf16 v[28:31], v[132:135], v[206:209], v[28:31]
	v_mfma_f32_16x16x32_bf16 v[24:27], v[140:143], v[206:209], v[24:27]
	v_mfma_f32_16x16x32_bf16 v[12:15], v[132:135], v[214:217], v[12:15]
	v_mfma_f32_16x16x32_bf16 v[8:11], v[140:143], v[214:217], v[8:11]
	s_setprio 0
	s_setprio 1
	v_mfma_f32_16x16x32_bf16 v[52:55], v[144:147], v[178:181], 0
	v_mfma_f32_16x16x32_bf16 v[48:51], v[164:167], v[178:181], 0
	v_mfma_f32_16x16x32_bf16 v[36:39], v[144:147], v[186:189], 0
	v_mfma_f32_16x16x32_bf16 v[32:35], v[164:167], v[186:189], 0
	v_mfma_f32_16x16x32_bf16 v[20:23], v[144:147], v[202:205], 0
	v_mfma_f32_16x16x32_bf16 v[16:19], v[164:167], v[202:205], 0
	v_mfma_f32_16x16x32_bf16 v[4:7], v[144:147], v[210:213], 0
	v_mfma_f32_16x16x32_bf16 v[0:3], v[164:167], v[210:213], 0
	v_mfma_f32_16x16x32_bf16 v[52:55], v[148:151], v[182:185], v[52:55]
	v_mfma_f32_16x16x32_bf16 v[48:51], v[174:177], v[182:185], v[48:51]
	v_mfma_f32_16x16x32_bf16 v[36:39], v[148:151], v[194:197], v[36:39]
	v_mfma_f32_16x16x32_bf16 v[32:35], v[174:177], v[194:197], v[32:35]
	s_barrier
; #define PG8_STAGE(bufoff, gbase, voff) do { _Pragma("unroll") for (int _i = 0; _i < 2; ++_i) \
;         __builtin_amdgcn_global_load_lds((const unsigned*)((const char*)(gbase) + (voff)[_i]), (PG8_LAS unsigned*)(lds + (bufoff) + ldsw + _i * 8192), 16, 0, 0); } while (0)
; #define PG8_LDA(dst, b, h) do { _Pragma("unroll") for (int m = 0; m < 4; ++m) _Pragma("unroll") for (int k = 0; k < 2; ++k) dst[m][k] = *(const PG8_LAS bf16x8*)(lds + PG8_SA(b, h) + aoff + m * 2048 + k * 1024); } while (0)
; #define PG8_LDB(dst, b, h) do { _Pragma("unroll") for (int n = 0; n < 2; ++n) _Pragma("unroll") for (int k = 0; k < 2; ++k) dst[n][k] = *(const PG8_LAS bf16x8*)(lds + PG8_SB(b, h) + boff + n * 2048 + k * 1024); } while (0)
; #define PG8_MMA(ai, bj, At, Bt) do { __builtin_amdgcn_s_setprio(1); _Pragma("unroll") for (int m = 0; m < 4; ++m) _Pragma("unroll") for (int n = 0; n < 2; ++n) _Pragma("unroll") for (int k = 0; k < 2; ++k) \
;         acc[ai][bj][m][n] = __builtin_amdgcn_mfma_f32_16x16x32_bf16(Bt[n][k], At[m][k], acc[ai][bj][m][n], 0, 0, 0); __builtin_amdgcn_s_setprio(0); } while (0)
; #define PG8_WAIT_V(n) asm volatile("s_waitcnt vmcnt(" #n ")" ::: "memory")
; #define PG8_WAIT_L(n) asm volatile("s_waitcnt lgkmcnt(" #n ")" ::: "memory")
; #define PG8_BAR __builtin_amdgcn_s_barrier()
; #define PG8_SCHED __builtin_amdgcn_sched_barrier(0)
; template <class Epi, class Sched, bool ALIGN_EPI = false, bool SP2 = false>
; __device__ __forceinline__ void gemm_phase(PG8_LAS unsigned char* lds, const Gemm g, const Sched& S, const Epi& E) {
;     ...
;             PG8_WAIT_V(8); PG8_WAIT_L(0); PG8_BAR; PG8_MMA(1, 0, At, B0); PG8_MMA(1, 1, At, B1); PG8_BAR; PG8_SCHED;
;             PG8_LDB(B0, 1, 0); PG8_LDB(B1, 1, 1); PG8_SCHED; PG8_LDA(At, 1, 0); PG8_STAGE(PG8_SA(0, 1), a2 + hstep, voffA);
;             PG8_WAIT_V(8); PG8_WAIT_L(0); PG8_BAR; PG8_MMA(0, 0, At, B0); PG8_MMA(0, 1, At, B1); PG8_BAR; PG8_SCHED;
;             PG8_LDA(At, 1, 1); PG8_STAGE(PG8_SB(1, 0), b3, voffB); PG8_STAGE(PG8_SB(1, 1), b3 + hstep, voffB); PG8_STAGE(PG8_SA(1, 0), a3, voffA);
	s_setprio 2
	v_mfma_f32_16x16x32_bf16 v[20:23], v[148:151], v[206:209], v[20:23]
	v_mfma_f32_16x16x32_bf16 v[16:19], v[174:177], v[206:209], v[16:19]
	v_mfma_f32_16x16x32_bf16 v[4:7], v[148:151], v[214:217], v[4:7]
	v_mfma_f32_16x16x32_bf16 v[0:3], v[174:177], v[214:217], v[0:3]
	s_setprio 0
	s_add_i32 s24, 0, 0x18000
	s_add_i32 s25, 0, 0x1c000
	s_add_u32 s42, s42, 0x80000
	s_addc_u32 s43, s43, 0
	s_mov_b32 m0, s49
	v_lshl_add_u64 v[230:231], s[42:43], 0, v[158:159]
	global_load_lds_dwordx4 v[230:231], off
	s_mov_b32 m0, s50
	v_lshl_add_u64 v[230:231], s[42:43], 0, v[154:155]
	global_load_lds_dwordx4 v[230:231], off
	v_add_u32_e32 v140, 0x18000, v172
	v_add_u32_e32 v174, 0x1c000, v172
	ds_read_b128 v[128:131], v140
	ds_read_b128 v[132:135], v140 offset:1024
	ds_read_b128 v[136:139], v140 offset:2048
	ds_read_b128 v[140:143], v140 offset:3072
	ds_read_b128 v[144:147], v174
	ds_read_b128 v[148:151], v174 offset:1024
	ds_read_b128 v[164:167], v174 offset:2048
	ds_read_b128 v[174:177], v174 offset:3072
	ds_read_b128 v[178:181], v173 offset:32768
	ds_read_b128 v[182:185], v173 offset:33792
	ds_read_b128 v[186:189], v173 offset:34816
	ds_read_b128 v[194:197], v173 offset:35840
	ds_read_b128 v[202:205], v173 offset:36864
	ds_read_b128 v[206:209], v173 offset:37888
	ds_read_b128 v[210:213], v173 offset:38912
	ds_read_b128 v[214:217], v173 offset:39936
	s_waitcnt vmcnt(8)
	s_waitcnt lgkmcnt(0)
	s_barrier
	s_setprio 1
	s_waitcnt lgkmcnt(0)
	v_mfma_f32_16x16x32_bf16 v[124:127], v[128:131], v[178:181], v[124:127]
	v_mfma_f32_16x16x32_bf16 v[120:123], v[136:139], v[178:181], v[120:123]
	v_mfma_f32_16x16x32_bf16 v[108:111], v[128:131], v[186:189], v[108:111]
	v_mfma_f32_16x16x32_bf16 v[104:107], v[136:139], v[186:189], v[104:107]
	v_mfma_f32_16x16x32_bf16 v[92:95], v[128:131], v[202:205], v[92:95]
	v_mfma_f32_16x16x32_bf16 v[88:91], v[136:139], v[202:205], v[88:91]
	v_mfma_f32_16x16x32_bf16 v[76:79], v[128:131], v[210:213], v[76:79]
	v_mfma_f32_16x16x32_bf16 v[72:75], v[136:139], v[210:213], v[72:75]
	v_mfma_f32_16x16x32_bf16 v[124:127], v[132:135], v[182:185], v[124:127]
	v_mfma_f32_16x16x32_bf16 v[120:123], v[140:143], v[182:185], v[120:123]
	v_mfma_f32_16x16x32_bf16 v[108:111], v[132:135], v[194:197], v[108:111]
	v_mfma_f32_16x16x32_bf16 v[104:107], v[140:143], v[194:197], v[104:107]
	v_mfma_f32_16x16x32_bf16 v[92:95], v[132:135], v[206:209], v[92:95]
	v_mfma_f32_16x16x32_bf16 v[88:91], v[140:143], v[206:209], v[88:91]
	v_mfma_f32_16x16x32_bf16 v[76:79], v[132:135], v[214:217], v[76:79]
	v_mfma_f32_16x16x32_bf16 v[72:75], v[140:143], v[214:217], v[72:75]
	s_setprio 0
	s_setprio 1
	v_mfma_f32_16x16x32_bf16 v[116:119], v[144:147], v[178:181], v[116:119]
	v_mfma_f32_16x16x32_bf16 v[112:115], v[164:167], v[178:181], v[112:115]
	v_mfma_f32_16x16x32_bf16 v[100:103], v[144:147], v[186:189], v[100:103]
	v_mfma_f32_16x16x32_bf16 v[96:99], v[164:167], v[186:189], v[96:99]
	v_mfma_f32_16x16x32_bf16 v[84:87], v[144:147], v[202:205], v[84:87]
	v_mfma_f32_16x16x32_bf16 v[80:83], v[164:167], v[202:205], v[80:83]
	v_mfma_f32_16x16x32_bf16 v[68:71], v[144:147], v[210:213], v[68:71]
	v_mfma_f32_16x16x32_bf16 v[64:67], v[164:167], v[210:213], v[64:67]
	v_mfma_f32_16x16x32_bf16 v[116:119], v[148:151], v[182:185], v[116:119]
	v_mfma_f32_16x16x32_bf16 v[112:115], v[174:177], v[182:185], v[112:115]
	v_mfma_f32_16x16x32_bf16 v[100:103], v[148:151], v[194:197], v[100:103]
	v_mfma_f32_16x16x32_bf16 v[96:99], v[174:177], v[194:197], v[96:99]
	s_barrier
	s_setprio 2
	v_mfma_f32_16x16x32_bf16 v[84:87], v[148:151], v[206:209], v[84:87]
	v_mfma_f32_16x16x32_bf16 v[80:83], v[174:177], v[206:209], v[80:83]
	v_mfma_f32_16x16x32_bf16 v[68:71], v[148:151], v[214:217], v[68:71]
	v_mfma_f32_16x16x32_bf16 v[64:67], v[174:177], v[214:217], v[64:67]
	s_setprio 0
	s_add_i32 s24, s24, s47
	v_lshl_add_u64 v[168:169], v[168:169], 0, s[16:17]
	s_mov_b32 m0, s24
	s_nop 0
	global_load_lds_dwordx4 v[168:169], off
	s_add_i32 m0, s24, 0x2000
	s_add_u32 s38, s38, 0x80080
	v_lshl_add_u64 v[168:169], v[190:191], 0, s[16:17]
	s_addc_u32 s39, s39, 0
	s_add_i32 s24, s25, s47
	global_load_lds_dwordx4 v[168:169], off
	s_mov_b32 m0, s24
	v_lshl_add_u64 v[168:169], s[38:39], 0, v[156:157]
	global_load_lds_dwordx4 v[168:169], off
	s_add_i32 m0, s24, 0x2000
	v_lshl_add_u64 v[168:169], s[38:39], 0, v[152:153]
	global_load_lds_dwordx4 v[168:169], off
	s_mov_b32 m0, s55
	v_lshl_add_u64 v[168:169], v[218:219], 0, s[16:17]
	global_load_lds_dwordx4 v[168:169], off
	s_mov_b32 m0, s56
	v_lshl_add_u64 v[168:169], v[220:221], 0, s[16:17]
	global_load_lds_dwordx4 v[168:169], off
	ds_read_b128 v[178:181], v173 offset:49152
	ds_read_b128 v[182:185], v173 offset:50176
	ds_read_b128 v[186:189], v173 offset:51200
	ds_read_b128 v[194:197], v173 offset:52224
	ds_read_b128 v[202:205], v173 offset:53248
	ds_read_b128 v[206:209], v173 offset:54272
	ds_read_b128 v[210:213], v173 offset:55296
	ds_read_b128 v[214:217], v173 offset:56320
	s_waitcnt vmcnt(8)
	s_waitcnt lgkmcnt(0)
	s_barrier
; #define PG8_STAGE(bufoff, gbase, voff) do { _Pragma("unroll") for (int _i = 0; _i < 2; ++_i) \
;         __builtin_amdgcn_global_load_lds((const unsigned*)((const char*)(gbase) + (voff)[_i]), (PG8_LAS unsigned*)(lds + (bufoff) + ldsw + _i * 8192), 16, 0, 0); } while (0)
; #define PG8_LDA(dst, b, h) do { _Pragma("unroll") for (int m = 0; m < 4; ++m) _Pragma("unroll") for (int k = 0; k < 2; ++k) dst[m][k] = *(const PG8_LAS bf16x8*)(lds + PG8_SA(b, h) + aoff + m * 2048 + k * 1024); } while (0)
; #define PG8_LDB(dst, b, h) do { _Pragma("unroll") for (int n = 0; n < 2; ++n) _Pragma("unroll") for (int k = 0; k < 2; ++k) dst[n][k] = *(const PG8_LAS bf16x8*)(lds + PG8_SB(b, h) + boff + n * 2048 + k * 1024); } while (0)
; #define PG8_MMA(ai, bj, At, Bt) do { __builtin_amdgcn_s_setprio(1); _Pragma("unroll") for (int m = 0; m < 4; ++m) _Pragma("unroll") for (int n = 0; n < 2; ++n) _Pragma("unroll") for (int k = 0; k < 2; ++k) \
;         acc[ai][bj][m][n] = __builtin_amdgcn_mfma_f32_16x16x32_bf16(Bt[n][k], At[m][k], acc[ai][bj][m][n], 0, 0, 0); __builtin_amdgcn_s_setprio(0); } while (0)
; #define PG8_WAIT_V(n) asm volatile("s_waitcnt vmcnt(" #n ")" ::: "memory")
; #define PG8_WAIT_L(n) asm volatile("s_waitcnt lgkmcnt(" #n ")" ::: "memory")
; #define PG8_BAR __builtin_amdgcn_s_barrier()
; #define PG8_SCHED __builtin_amdgcn_sched_barrier(0)
; template <class Epi, class Sched, bool ALIGN_EPI = false, bool SP2 = false>
; __device__ __forceinline__ void gemm_phase(PG8_LAS unsigned char* lds, const Gemm g, const Sched& S, const Epi& E) {
;     ...
;         for (int t = 0; t < nt; t += 2) {
;             if constexpr (Epi::MID_HOOK) { if (t == Epi::MID_T) E.mid(acc, cur, wr, wc, fr, fq); }
;             const bool last = (t == nt - 2);
;             const char* a1 = cA + (size_t)(t + 1) * kstep;
;             const char* a2 = last ? nA : cA + (size_t)(t + 2) * kstep; const char* b2 = last ? nB : cB + (size_t)(t + 2) * kstep;
;             const char* a3 = a2 + kstep; const char* b3 = b2 + kstep;
;             if (last && has_next) S.a_ready(nxt);
;             if constexpr (SP2) {
;             PG8_LDB(B0, 0, 0); PG8_LDB(B1, 0, 1); PG8_SCHED; PG8_LDA(At, 0, 0); PG8_STAGE(PG8_SA(1, 1), a1 + hstep, voffA);
;             PG8_WAIT_V(8); PG8_WAIT_L(0); PG8_BAR; PG8_MMA(0, 0, At, B0); PG8_MMA(0, 1, At, B1); PG8_BAR; PG8_SCHED;
	s_setprio 1
	s_waitcnt lgkmcnt(0)
	v_mfma_f32_16x16x32_bf16 v[60:63], v[128:131], v[178:181], v[60:63]
	v_mfma_f32_16x16x32_bf16 v[56:59], v[136:139], v[178:181], v[56:59]
	v_mfma_f32_16x16x32_bf16 v[44:47], v[128:131], v[186:189], v[44:47]
	v_mfma_f32_16x16x32_bf16 v[40:43], v[136:139], v[186:189], v[40:43]
	v_mfma_f32_16x16x32_bf16 v[28:31], v[128:131], v[202:205], v[28:31]
	v_mfma_f32_16x16x32_bf16 v[24:27], v[136:139], v[202:205], v[24:27]
	v_mfma_f32_16x16x32_bf16 v[12:15], v[128:131], v[210:213], v[12:15]
	v_mfma_f32_16x16x32_bf16 v[8:11], v[136:139], v[210:213], v[8:11]
	v_mfma_f32_16x16x32_bf16 v[60:63], v[132:135], v[182:185], v[60:63]
	v_mfma_f32_16x16x32_bf16 v[56:59], v[140:143], v[182:185], v[56:59]
	v_mfma_f32_16x16x32_bf16 v[44:47], v[132:135], v[194:197], v[44:47]
	v_mfma_f32_16x16x32_bf16 v[40:43], v[140:143], v[194:197], v[40:43]
	v_mfma_f32_16x16x32_bf16 v[28:31], v[132:135], v[206:209], v[28:31]
	v_mfma_f32_16x16x32_bf16 v[24:27], v[140:143], v[206:209], v[24:27]
	v_mfma_f32_16x16x32_bf16 v[12:15], v[132:135], v[214:217], v[12:15]
	v_mfma_f32_16x16x32_bf16 v[8:11], v[140:143], v[214:217], v[8:11]
	s_setprio 0
	s_setprio 1
	v_mfma_f32_16x16x32_bf16 v[52:55], v[144:147], v[178:181], v[52:55]
	v_mfma_f32_16x16x32_bf16 v[48:51], v[164:167], v[178:181], v[48:51]
	v_mfma_f32_16x16x32_bf16 v[36:39], v[144:147], v[186:189], v[36:39]
	v_mfma_f32_16x16x32_bf16 v[32:35], v[164:167], v[186:189], v[32:35]
	v_mfma_f32_16x16x32_bf16 v[20:23], v[144:147], v[202:205], v[20:23]
	v_mfma_f32_16x16x32_bf16 v[16:19], v[164:167], v[202:205], v[16:19]
	v_mfma_f32_16x16x32_bf16 v[4:7], v[144:147], v[210:213], v[4:7]
	v_mfma_f32_16x16x32_bf16 v[0:3], v[164:167], v[210:213], v[0:3]
	v_mfma_f32_16x16x32_bf16 v[52:55], v[148:151], v[182:185], v[52:55]
	v_mfma_f32_16x16x32_bf16 v[48:51], v[174:177], v[182:185], v[48:51]
	v_mfma_f32_16x16x32_bf16 v[36:39], v[148:151], v[194:197], v[36:39]
	v_mfma_f32_16x16x32_bf16 v[32:35], v[174:177], v[194:197], v[32:35]
	s_barrier
	s_setprio 2
	v_mfma_f32_16x16x32_bf16 v[20:23], v[148:151], v[206:209], v[20:23]
	v_mfma_f32_16x16x32_bf16 v[16:19], v[174:177], v[206:209], v[16:19]
	v_mfma_f32_16x16x32_bf16 v[4:7], v[148:151], v[214:217], v[4:7]
	v_mfma_f32_16x16x32_bf16 v[0:3], v[174:177], v[214:217], v[0:3]
	s_setprio 0
	s_add_i32 s65, s65, 2
	s_add_u32 s36, s36, 0x100
	s_addc_u32 s37, s37, 0
	s_add_u32 s63, s63, 0x100
	s_addc_u32 s64, s64, 0
	s_cmp_gt_u32 s65, 29
	s_branch .LBB0_635
.LBB0_635:
	v_add_u32_e32 v140, 0x10000, v172
	v_add_u32_e32 v168, 0x14000, v172
	ds_read_b128 v[128:131], v140
	ds_read_b128 v[132:135], v140 offset:1024
	ds_read_b128 v[136:139], v140 offset:2048
	ds_read_b128 v[140:143], v140 offset:3072
	ds_read_b128 v[144:147], v168
	ds_read_b128 v[148:151], v168 offset:1024
	ds_read_b128 v[164:167], v168 offset:2048
	ds_read_b128 v[174:177], v168 offset:3072
	v_lshl_add_u64 v[168:169], s[36:37], 0, v[160:161]
	s_add_i32 m0, s2, 0xc000
	ds_read_b128 v[178:181], v173
	ds_read_b128 v[182:185], v173 offset:1024
	ds_read_b128 v[186:189], v173 offset:2048
	ds_read_b128 v[194:197], v173 offset:3072
	ds_read_b128 v[202:205], v173 offset:4096
	ds_read_b128 v[206:209], v173 offset:5120
	ds_read_b128 v[210:213], v173 offset:6144
	ds_read_b128 v[214:217], v173 offset:7168
	global_load_lds_dwordx4 v[168:169], off
	s_add_i32 m0, s2, 0xe000
	v_lshl_add_u64 v[168:169], s[36:37], 0, v[162:163]
	global_load_lds_dwordx4 v[168:169], off
	s_add_u32 s24, s36, 0xfff80080
	s_addc_u32 s25, s37, -1
	s_add_i32 s33, 0, 0x10000
	s_cmp_eq_u32 s65, 28
	s_cselect_b32 s43, s15, s25
	s_cselect_b32 s42, s61, s24
	s_cselect_b32 s39, s13, s64
	s_cselect_b32 s38, s62, s63
	s_add_i32 s24, 0, 0x14000
	s_waitcnt vmcnt(8)
	s_waitcnt lgkmcnt(0)
	s_barrier
	s_setprio 1
	s_waitcnt lgkmcnt(0)
	v_mfma_f32_16x16x32_bf16 v[124:127], v[128:131], v[178:181], v[124:127]
	v_mfma_f32_16x16x32_bf16 v[120:123], v[136:139], v[178:181], v[120:123]
	v_mfma_f32_16x16x32_bf16 v[108:111], v[128:131], v[186:189], v[108:111]
	v_mfma_f32_16x16x32_bf16 v[104:107], v[136:139], v[186:189], v[104:107]
	v_mfma_f32_16x16x32_bf16 v[92:95], v[128:131], v[202:205], v[92:95]
	v_mfma_f32_16x16x32_bf16 v[88:91], v[136:139], v[202:205], v[88:91]
	v_mfma_f32_16x16x32_bf16 v[76:79], v[128:131], v[210:213], v[76:79]
	v_mfma_f32_16x16x32_bf16 v[72:75], v[136:139], v[210:213], v[72:75]
	v_mfma_f32_16x16x32_bf16 v[124:127], v[132:135], v[182:185], v[124:127]
	v_mfma_f32_16x16x32_bf16 v[120:123], v[140:143], v[182:185], v[120:123]
	v_mfma_f32_16x16x32_bf16 v[108:111], v[132:135], v[194:197], v[108:111]
	v_mfma_f32_16x16x32_bf16 v[104:107], v[140:143], v[194:197], v[104:107]
	v_mfma_f32_16x16x32_bf16 v[92:95], v[132:135], v[206:209], v[92:95]
	v_mfma_f32_16x16x32_bf16 v[88:91], v[140:143], v[206:209], v[88:91]
	v_mfma_f32_16x16x32_bf16 v[76:79], v[132:135], v[214:217], v[76:79]
	v_mfma_f32_16x16x32_bf16 v[72:75], v[140:143], v[214:217], v[72:75]
	s_setprio 0
	s_setprio 1
	v_mfma_f32_16x16x32_bf16 v[116:119], v[144:147], v[178:181], v[116:119]
	v_mfma_f32_16x16x32_bf16 v[112:115], v[164:167], v[178:181], v[112:115]
	v_mfma_f32_16x16x32_bf16 v[100:103], v[144:147], v[186:189], v[100:103]
	v_mfma_f32_16x16x32_bf16 v[96:99], v[164:167], v[186:189], v[96:99]
	v_mfma_f32_16x16x32_bf16 v[84:87], v[144:147], v[202:205], v[84:87]
	v_mfma_f32_16x16x32_bf16 v[80:83], v[164:167], v[202:205], v[80:83]
	v_mfma_f32_16x16x32_bf16 v[68:71], v[144:147], v[210:213], v[68:71]
	v_mfma_f32_16x16x32_bf16 v[64:67], v[164:167], v[210:213], v[64:67]
	v_mfma_f32_16x16x32_bf16 v[116:119], v[148:151], v[182:185], v[116:119]
	v_mfma_f32_16x16x32_bf16 v[112:115], v[174:177], v[182:185], v[112:115]
	v_mfma_f32_16x16x32_bf16 v[100:103], v[148:151], v[194:197], v[100:103]
	v_mfma_f32_16x16x32_bf16 v[96:99], v[174:177], v[194:197], v[96:99]
	s_barrier
; #define PG8_STAGE(bufoff, gbase, voff) do { _Pragma("unroll") for (int _i = 0; _i < 2; ++_i) \
;         __builtin_amdgcn_global_load_lds((const unsigned*)((const char*)(gbase) + (voff)[_i]), (PG8_LAS unsigned*)(lds + (bufoff) + ldsw + _i * 8192), 16, 0, 0); } while (0)
; #define PG8_LDA(dst, b, h) do { _Pragma("unroll") for (int m = 0; m < 4; ++m) _Pragma("unroll") for (int k = 0; k < 2; ++k) dst[m][k] = *(const PG8_LAS bf16x8*)(lds + PG8_SA(b, h) + aoff + m * 2048 + k * 1024); } while (0)
; #define PG8_LDB(dst, b, h) do { _Pragma("unroll") for (int n = 0; n < 2; ++n) _Pragma("unroll") for (int k = 0; k < 2; ++k) dst[n][k] = *(const PG8_LAS bf16x8*)(lds + PG8_SB(b, h) + boff + n * 2048 + k * 1024); } while (0)
; #define PG8_MMA(ai, bj, At, Bt) do { __builtin_amdgcn_s_setprio(1); _Pragma("unroll") for (int m = 0; m < 4; ++m) _Pragma("unroll") for (int n = 0; n < 2; ++n) _Pragma("unroll") for (int k = 0; k < 2; ++k) \
;         acc[ai][bj][m][n] = __builtin_amdgcn_mfma_f32_16x16x32_bf16(Bt[n][k], At[m][k], acc[ai][bj][m][n], 0, 0, 0); __builtin_amdgcn_s_setprio(0); } while (0)
; #define PG8_WAIT_V(n) asm volatile("s_waitcnt vmcnt(" #n ")" ::: "memory")
; #define PG8_WAIT_L(n) asm volatile("s_waitcnt lgkmcnt(" #n ")" ::: "memory")
; #define PG8_BAR __builtin_amdgcn_s_barrier()
; #define PG8_SCHED __builtin_amdgcn_sched_barrier(0)
; template <class Epi, class Sched, bool ALIGN_EPI = false, bool SP2 = false>
; __device__ __forceinline__ void gemm_phase(PG8_LAS unsigned char* lds, const Gemm g, const Sched& S, const Epi& E) {
;     ...
;             PG8_WAIT_V(8); PG8_WAIT_L(0); PG8_BAR; PG8_MMA(0, 0, At, B0); PG8_MMA(0, 1, At, B1); PG8_BAR; PG8_SCHED;
;             PG8_LDA(At, 0, 1); PG8_STAGE(PG8_SB(0, 0), b2, voffB); PG8_STAGE(PG8_SB(0, 1), b2 + hstep, voffB); PG8_STAGE(PG8_SA(0, 0), a2, voffA);
;             PG8_WAIT_V(8); PG8_WAIT_L(0); PG8_BAR; PG8_MMA(1, 0, At, B0); PG8_MMA(1, 1, At, B1); PG8_BAR; PG8_SCHED;
;             PG8_LDB(B0, 1, 0); PG8_LDB(B1, 1, 1); PG8_SCHED; PG8_LDA(At, 1, 0); PG8_STAGE(PG8_SA(0, 1), a2 + hstep, voffA);
	s_setprio 2
	v_mfma_f32_16x16x32_bf16 v[84:87], v[148:151], v[206:209], v[84:87]
	v_mfma_f32_16x16x32_bf16 v[80:83], v[174:177], v[206:209], v[80:83]
	v_mfma_f32_16x16x32_bf16 v[68:71], v[148:151], v[214:217], v[68:71]
	v_mfma_f32_16x16x32_bf16 v[64:67], v[174:177], v[214:217], v[64:67]
	s_setprio 0
	s_add_i32 s25, s33, s47
	v_lshl_add_u64 v[168:169], s[38:39], 0, v[156:157]
	s_mov_b32 m0, s25
	s_nop 0
	global_load_lds_dwordx4 v[168:169], off
	s_add_i32 m0, s25, 0x2000
	s_add_u32 s66, s38, 0x80000
	v_lshl_add_u64 v[190:191], s[38:39], 0, v[152:153]
	s_addc_u32 s67, s39, 0
	s_add_i32 s24, s24, s47
	global_load_lds_dwordx4 v[190:191], off
	v_lshl_add_u64 v[218:219], s[66:67], 0, v[156:157]
	s_mov_b32 m0, s24
	v_lshl_add_u64 v[220:221], s[42:43], 0, v[154:155]
	global_load_lds_dwordx4 v[218:219], off
	s_add_i32 m0, s24, 0x2000
	v_lshl_add_u64 v[218:219], s[66:67], 0, v[152:153]
	global_load_lds_dwordx4 v[218:219], off
	s_mov_b32 m0, s2
	v_lshl_add_u64 v[218:219], s[42:43], 0, v[158:159]
	global_load_lds_dwordx4 v[218:219], off
	s_mov_b32 m0, s48
	s_nop 0
	global_load_lds_dwordx4 v[220:221], off
	ds_read_b128 v[178:181], v173 offset:16384
	ds_read_b128 v[182:185], v173 offset:17408
	ds_read_b128 v[186:189], v173 offset:18432
	ds_read_b128 v[194:197], v173 offset:19456
	ds_read_b128 v[202:205], v173 offset:20480
	ds_read_b128 v[206:209], v173 offset:21504
	ds_read_b128 v[210:213], v173 offset:22528
	ds_read_b128 v[214:217], v173 offset:23552
	s_waitcnt vmcnt(8)
	s_waitcnt lgkmcnt(0)
	s_barrier
	s_setprio 1
	s_waitcnt lgkmcnt(0)
	v_mfma_f32_16x16x32_bf16 v[60:63], v[128:131], v[178:181], v[60:63]
	v_mfma_f32_16x16x32_bf16 v[56:59], v[136:139], v[178:181], v[56:59]
	v_mfma_f32_16x16x32_bf16 v[44:47], v[128:131], v[186:189], v[44:47]
	v_mfma_f32_16x16x32_bf16 v[40:43], v[136:139], v[186:189], v[40:43]
	v_mfma_f32_16x16x32_bf16 v[28:31], v[128:131], v[202:205], v[28:31]
	v_mfma_f32_16x16x32_bf16 v[24:27], v[136:139], v[202:205], v[24:27]
	v_mfma_f32_16x16x32_bf16 v[12:15], v[128:131], v[210:213], v[12:15]
	v_mfma_f32_16x16x32_bf16 v[8:11], v[136:139], v[210:213], v[8:11]
	v_mfma_f32_16x16x32_bf16 v[60:63], v[132:135], v[182:185], v[60:63]
	v_mfma_f32_16x16x32_bf16 v[56:59], v[140:143], v[182:185], v[56:59]
	v_mfma_f32_16x16x32_bf16 v[44:47], v[132:135], v[194:197], v[44:47]
	v_mfma_f32_16x16x32_bf16 v[40:43], v[140:143], v[194:197], v[40:43]
	v_mfma_f32_16x16x32_bf16 v[28:31], v[132:135], v[206:209], v[28:31]
	v_mfma_f32_16x16x32_bf16 v[24:27], v[140:143], v[206:209], v[24:27]
	v_mfma_f32_16x16x32_bf16 v[12:15], v[132:135], v[214:217], v[12:15]
	v_mfma_f32_16x16x32_bf16 v[8:11], v[140:143], v[214:217], v[8:11]
	s_setprio 0
	s_setprio 1
	v_mfma_f32_16x16x32_bf16 v[52:55], v[144:147], v[178:181], v[52:55]
	v_mfma_f32_16x16x32_bf16 v[48:51], v[164:167], v[178:181], v[48:51]
	v_mfma_f32_16x16x32_bf16 v[36:39], v[144:147], v[186:189], v[36:39]
	v_mfma_f32_16x16x32_bf16 v[32:35], v[164:167], v[186:189], v[32:35]
	v_mfma_f32_16x16x32_bf16 v[20:23], v[144:147], v[202:205], v[20:23]
	v_mfma_f32_16x16x32_bf16 v[16:19], v[164:167], v[202:205], v[16:19]
	v_mfma_f32_16x16x32_bf16 v[4:7], v[144:147], v[210:213], v[4:7]
	v_mfma_f32_16x16x32_bf16 v[0:3], v[164:167], v[210:213], v[0:3]
	v_mfma_f32_16x16x32_bf16 v[52:55], v[148:151], v[182:185], v[52:55]
	v_mfma_f32_16x16x32_bf16 v[48:51], v[174:177], v[182:185], v[48:51]
	v_mfma_f32_16x16x32_bf16 v[36:39], v[148:151], v[194:197], v[36:39]
	v_mfma_f32_16x16x32_bf16 v[32:35], v[174:177], v[194:197], v[32:35]
	s_barrier
	s_setprio 2
	v_mfma_f32_16x16x32_bf16 v[20:23], v[148:151], v[206:209], v[20:23]
	v_mfma_f32_16x16x32_bf16 v[16:19], v[174:177], v[206:209], v[16:19]
	v_mfma_f32_16x16x32_bf16 v[4:7], v[148:151], v[214:217], v[4:7]
	v_mfma_f32_16x16x32_bf16 v[0:3], v[174:177], v[214:217], v[0:3]
	s_setprio 0
	s_add_i32 s24, 0, 0x18000
	s_add_i32 s25, 0, 0x1c000
	s_add_u32 s42, s42, 0x80000
	s_addc_u32 s43, s43, 0
	s_mov_b32 m0, s49
	v_lshl_add_u64 v[230:231], s[42:43], 0, v[158:159]
	global_load_lds_dwordx4 v[230:231], off
	s_mov_b32 m0, s50
	v_lshl_add_u64 v[230:231], s[42:43], 0, v[154:155]
	global_load_lds_dwordx4 v[230:231], off
	v_add_u32_e32 v140, 0x18000, v172
	v_add_u32_e32 v174, 0x1c000, v172
	ds_read_b128 v[128:131], v140
	ds_read_b128 v[132:135], v140 offset:1024
	ds_read_b128 v[136:139], v140 offset:2048
	ds_read_b128 v[140:143], v140 offset:3072
	ds_read_b128 v[144:147], v174
	ds_read_b128 v[148:151], v174 offset:1024
	ds_read_b128 v[164:167], v174 offset:2048
	ds_read_b128 v[174:177], v174 offset:3072
	ds_read_b128 v[178:181], v173 offset:32768
	ds_read_b128 v[182:185], v173 offset:33792
	ds_read_b128 v[186:189], v173 offset:34816
	ds_read_b128 v[194:197], v173 offset:35840
	ds_read_b128 v[202:205], v173 offset:36864
	ds_read_b128 v[206:209], v173 offset:37888
	ds_read_b128 v[210:213], v173 offset:38912
	ds_read_b128 v[214:217], v173 offset:39936
	s_waitcnt vmcnt(8)
	s_waitcnt lgkmcnt(0)
	s_barrier
; #define PG8_STAGE(bufoff, gbase, voff) do { _Pragma("unroll") for (int _i = 0; _i < 2; ++_i) \
;         __builtin_amdgcn_global_load_lds((const unsigned*)((const char*)(gbase) + (voff)[_i]), (PG8_LAS unsigned*)(lds + (bufoff) + ldsw + _i * 8192), 16, 0, 0); } while (0)
; #define PG8_LDA(dst, b, h) do { _Pragma("unroll") for (int m = 0; m < 4; ++m) _Pragma("unroll") for (int k = 0; k < 2; ++k) dst[m][k] = *(const PG8_LAS bf16x8*)(lds + PG8_SA(b, h) + aoff + m * 2048 + k * 1024); } while (0)
; #define PG8_MMA(ai, bj, At, Bt) do { __builtin_amdgcn_s_setprio(1); _Pragma("unroll") for (int m = 0; m < 4; ++m) _Pragma("unroll") for (int n = 0; n < 2; ++n) _Pragma("unroll") for (int k = 0; k < 2; ++k) \
;         acc[ai][bj][m][n] = __builtin_amdgcn_mfma_f32_16x16x32_bf16(Bt[n][k], At[m][k], acc[ai][bj][m][n], 0, 0, 0); __builtin_amdgcn_s_setprio(0); } while (0)
; #define PG8_WAIT_V(n) asm volatile("s_waitcnt vmcnt(" #n ")" ::: "memory")
; #define PG8_WAIT_L(n) asm volatile("s_waitcnt lgkmcnt(" #n ")" ::: "memory")
; #define PG8_BAR __builtin_amdgcn_s_barrier()
; #define PG8_SCHED __builtin_amdgcn_sched_barrier(0)
; template <class Epi, class Sched, bool ALIGN_EPI = false, bool SP2 = false>
; __device__ __forceinline__ void gemm_phase(PG8_LAS unsigned char* lds, const Gemm g, const Sched& S, const Epi& E) {
;     ...
;             PG8_WAIT_V(8); PG8_WAIT_L(0); PG8_BAR; PG8_MMA(0, 0, At, B0); PG8_MMA(0, 1, At, B1); PG8_BAR; PG8_SCHED;
;             PG8_LDA(At, 1, 1); PG8_STAGE(PG8_SB(1, 0), b3, voffB); PG8_STAGE(PG8_SB(1, 1), b3 + hstep, voffB); PG8_STAGE(PG8_SA(1, 0), a3, voffA);
;             PG8_WAIT_V(8); PG8_WAIT_L(0); PG8_BAR; PG8_MMA(1, 0, At, B0); PG8_MMA(1, 1, At, B1); PG8_BAR; PG8_SCHED;
;     ...
;         if constexpr (ALIGN_EPI) { if (wr == 0) PG8_BAR; }
	s_setprio 1
	s_waitcnt lgkmcnt(0)
	v_mfma_f32_16x16x32_bf16 v[124:127], v[128:131], v[178:181], v[124:127]
	v_mfma_f32_16x16x32_bf16 v[120:123], v[136:139], v[178:181], v[120:123]
	v_mfma_f32_16x16x32_bf16 v[108:111], v[128:131], v[186:189], v[108:111]
	v_mfma_f32_16x16x32_bf16 v[104:107], v[136:139], v[186:189], v[104:107]
	v_mfma_f32_16x16x32_bf16 v[92:95], v[128:131], v[202:205], v[92:95]
	v_mfma_f32_16x16x32_bf16 v[88:91], v[136:139], v[202:205], v[88:91]
	v_mfma_f32_16x16x32_bf16 v[76:79], v[128:131], v[210:213], v[76:79]
	v_mfma_f32_16x16x32_bf16 v[72:75], v[136:139], v[210:213], v[72:75]
	v_mfma_f32_16x16x32_bf16 v[124:127], v[132:135], v[182:185], v[124:127]
	v_mfma_f32_16x16x32_bf16 v[120:123], v[140:143], v[182:185], v[120:123]
	v_mfma_f32_16x16x32_bf16 v[108:111], v[132:135], v[194:197], v[108:111]
	v_mfma_f32_16x16x32_bf16 v[104:107], v[140:143], v[194:197], v[104:107]
	v_mfma_f32_16x16x32_bf16 v[92:95], v[132:135], v[206:209], v[92:95]
	v_mfma_f32_16x16x32_bf16 v[88:91], v[140:143], v[206:209], v[88:91]
	v_mfma_f32_16x16x32_bf16 v[76:79], v[132:135], v[214:217], v[76:79]
	v_mfma_f32_16x16x32_bf16 v[72:75], v[140:143], v[214:217], v[72:75]
	s_setprio 0
	s_setprio 1
	v_mfma_f32_16x16x32_bf16 v[116:119], v[144:147], v[178:181], v[116:119]
	v_mfma_f32_16x16x32_bf16 v[112:115], v[164:167], v[178:181], v[112:115]
	v_mfma_f32_16x16x32_bf16 v[100:103], v[144:147], v[186:189], v[100:103]
	v_mfma_f32_16x16x32_bf16 v[96:99], v[164:167], v[186:189], v[96:99]
	v_mfma_f32_16x16x32_bf16 v[84:87], v[144:147], v[202:205], v[84:87]
	v_mfma_f32_16x16x32_bf16 v[80:83], v[164:167], v[202:205], v[80:83]
	v_mfma_f32_16x16x32_bf16 v[68:71], v[144:147], v[210:213], v[68:71]
	v_mfma_f32_16x16x32_bf16 v[64:67], v[164:167], v[210:213], v[64:67]
	v_mfma_f32_16x16x32_bf16 v[116:119], v[148:151], v[182:185], v[116:119]
	v_mfma_f32_16x16x32_bf16 v[112:115], v[174:177], v[182:185], v[112:115]
	v_mfma_f32_16x16x32_bf16 v[100:103], v[148:151], v[194:197], v[100:103]
	v_mfma_f32_16x16x32_bf16 v[96:99], v[174:177], v[194:197], v[96:99]
	s_barrier
	s_setprio 2
	v_mfma_f32_16x16x32_bf16 v[84:87], v[148:151], v[206:209], v[84:87]
	v_mfma_f32_16x16x32_bf16 v[80:83], v[174:177], v[206:209], v[80:83]
	v_mfma_f32_16x16x32_bf16 v[68:71], v[148:151], v[214:217], v[68:71]
	v_mfma_f32_16x16x32_bf16 v[64:67], v[174:177], v[214:217], v[64:67]
	s_setprio 0
	s_add_i32 s24, s24, s47
	v_lshl_add_u64 v[168:169], v[168:169], 0, s[16:17]
	s_mov_b32 m0, s24
	s_nop 0
	global_load_lds_dwordx4 v[168:169], off
	s_add_i32 m0, s24, 0x2000
	s_add_u32 s38, s38, 0x80080
	v_lshl_add_u64 v[168:169], v[190:191], 0, s[16:17]
	s_addc_u32 s39, s39, 0
	s_add_i32 s24, s25, s47
	global_load_lds_dwordx4 v[168:169], off
	s_mov_b32 m0, s24
	v_lshl_add_u64 v[168:169], s[38:39], 0, v[156:157]
	global_load_lds_dwordx4 v[168:169], off
	s_add_i32 m0, s24, 0x2000
	v_lshl_add_u64 v[168:169], s[38:39], 0, v[152:153]
	global_load_lds_dwordx4 v[168:169], off
	s_mov_b32 m0, s55
	v_lshl_add_u64 v[168:169], v[218:219], 0, s[16:17]
	global_load_lds_dwordx4 v[168:169], off
	s_mov_b32 m0, s56
	v_lshl_add_u64 v[168:169], v[220:221], 0, s[16:17]
	global_load_lds_dwordx4 v[168:169], off
	ds_read_b128 v[178:181], v173 offset:49152
	ds_read_b128 v[182:185], v173 offset:50176
	ds_read_b128 v[186:189], v173 offset:51200
	ds_read_b128 v[194:197], v173 offset:52224
	ds_read_b128 v[202:205], v173 offset:53248
	ds_read_b128 v[206:209], v173 offset:54272
	ds_read_b128 v[210:213], v173 offset:55296
	ds_read_b128 v[214:217], v173 offset:56320
	s_waitcnt vmcnt(8)
	s_waitcnt lgkmcnt(0)
	s_barrier
	s_setprio 1
	s_waitcnt lgkmcnt(0)
	v_mfma_f32_16x16x32_bf16 v[60:63], v[128:131], v[178:181], v[60:63]
	v_mfma_f32_16x16x32_bf16 v[56:59], v[136:139], v[178:181], v[56:59]
	v_mfma_f32_16x16x32_bf16 v[44:47], v[128:131], v[186:189], v[44:47]
	v_mfma_f32_16x16x32_bf16 v[40:43], v[136:139], v[186:189], v[40:43]
	v_mfma_f32_16x16x32_bf16 v[28:31], v[128:131], v[202:205], v[28:31]
	v_mfma_f32_16x16x32_bf16 v[24:27], v[136:139], v[202:205], v[24:27]
	v_mfma_f32_16x16x32_bf16 v[12:15], v[128:131], v[210:213], v[12:15]
	v_mfma_f32_16x16x32_bf16 v[8:11], v[136:139], v[210:213], v[8:11]
	v_mfma_f32_16x16x32_bf16 v[60:63], v[132:135], v[182:185], v[60:63]
	v_mfma_f32_16x16x32_bf16 v[56:59], v[140:143], v[182:185], v[56:59]
	v_mfma_f32_16x16x32_bf16 v[44:47], v[132:135], v[194:197], v[44:47]
	v_mfma_f32_16x16x32_bf16 v[40:43], v[140:143], v[194:197], v[40:43]
	v_mfma_f32_16x16x32_bf16 v[28:31], v[132:135], v[206:209], v[28:31]
	v_mfma_f32_16x16x32_bf16 v[24:27], v[140:143], v[206:209], v[24:27]
	v_mfma_f32_16x16x32_bf16 v[12:15], v[132:135], v[214:217], v[12:15]
	v_mfma_f32_16x16x32_bf16 v[8:11], v[140:143], v[214:217], v[8:11]
	s_setprio 0
	s_setprio 1
	v_mfma_f32_16x16x32_bf16 v[52:55], v[144:147], v[178:181], v[52:55]
	v_mfma_f32_16x16x32_bf16 v[48:51], v[164:167], v[178:181], v[48:51]
	v_mfma_f32_16x16x32_bf16 v[36:39], v[144:147], v[186:189], v[36:39]
	v_mfma_f32_16x16x32_bf16 v[32:35], v[164:167], v[186:189], v[32:35]
	v_mfma_f32_16x16x32_bf16 v[20:23], v[144:147], v[202:205], v[20:23]
	v_mfma_f32_16x16x32_bf16 v[16:19], v[164:167], v[202:205], v[16:19]
	v_mfma_f32_16x16x32_bf16 v[4:7], v[144:147], v[210:213], v[4:7]
	v_mfma_f32_16x16x32_bf16 v[0:3], v[164:167], v[210:213], v[0:3]
	v_mfma_f32_16x16x32_bf16 v[52:55], v[148:151], v[182:185], v[52:55]
	v_mfma_f32_16x16x32_bf16 v[48:51], v[174:177], v[182:185], v[48:51]
	v_mfma_f32_16x16x32_bf16 v[36:39], v[148:151], v[194:197], v[36:39]
	v_mfma_f32_16x16x32_bf16 v[32:35], v[174:177], v[194:197], v[32:35]
	s_barrier
	s_setprio 2
	v_mfma_f32_16x16x32_bf16 v[20:23], v[148:151], v[206:209], v[20:23]
	v_mfma_f32_16x16x32_bf16 v[16:19], v[174:177], v[206:209], v[16:19]
	v_mfma_f32_16x16x32_bf16 v[4:7], v[148:151], v[214:217], v[4:7]
	v_mfma_f32_16x16x32_bf16 v[0:3], v[174:177], v[214:217], v[0:3]
	s_setprio 0
	s_add_i32 s65, s65, 2
	s_add_u32 s36, s36, 0x100
	s_addc_u32 s37, s37, 0
	s_add_u32 s63, s63, 0x100
	s_addc_u32 s64, s64, 0
	s_cmp_gt_u32 s65, 29
	s_cbranch_scc0 .LBB0_635
	s_and_b64 vcc, exec, s[10:11]
	s_cbranch_vccz .LBB0_638
	s_barrier

; #define PG8_STAGE(bufoff, gbase, voff) do { _Pragma("unroll") for (int _i = 0; _i < 2; ++_i) \
;         __builtin_amdgcn_global_load_lds((const unsigned*)((const char*)(gbase) + (voff)[_i]), (PG8_LAS unsigned*)(lds + (bufoff) + ldsw + _i * 8192), 16, 0, 0); } while (0)
; #define PG8_LDA(dst, b, h) do { _Pragma("unroll") for (int m = 0; m < 4; ++m) _Pragma("unroll") for (int k = 0; k < 2; ++k) dst[m][k] = *(const PG8_LAS bf16x8*)(lds + PG8_SA(b, h) + aoff + m * 2048 + k * 1024); } while (0)
; #define PG8_LDB(dst, b, h) do { _Pragma("unroll") for (int n = 0; n < 2; ++n) _Pragma("unroll") for (int k = 0; k < 2; ++k) dst[n][k] = *(const PG8_LAS bf16x8*)(lds + PG8_SB(b, h) + boff + n * 2048 + k * 1024); } while (0)
; #define PG8_WAIT_V(n) asm volatile("s_waitcnt vmcnt(" #n ")" ::: "memory")
; #define PG8_WAIT_L(n) asm volatile("s_waitcnt lgkmcnt(" #n ")" ::: "memory")
; #define PG8_BAR __builtin_amdgcn_s_barrier()
; template <class Epi, class Sched, bool ALIGN_EPI = false, bool SP2 = false>
; __device__ __forceinline__ void gemm_phase(PG8_LAS unsigned char* lds, const Gemm g, const Sched& S, const Epi& E) {
;     ...
;         const bool has_next = S.next(ui + 1, nxt);
;         const char* nA = has_next ? (const char*)g.A + (size_t)nxt.pm * tstep : cA; const char* nB = has_next ? (const char*)g.Bt + (size_t)nxt.pn * tstep : cB;
;         for (int t = 0; t < nt; t += 2) {
;             if constexpr (Epi::MID_HOOK) { if (t == Epi::MID_T) E.mid(acc, cur, wr, wc, fr, fq); }
;             const bool last = (t == nt - 2);
;             const char* a1 = cA + (size_t)(t + 1) * kstep;
;             const char* a2 = last ? nA : cA + (size_t)(t + 2) * kstep; const char* b2 = last ? nB : cB + (size_t)(t + 2) * kstep;
;             const char* a3 = a2 + kstep; const char* b3 = b2 + kstep;
;             if (last && has_next) S.a_ready(nxt);
;             if constexpr (SP2) {
;             PG8_LDB(B0, 0, 0); PG8_LDB(B1, 0, 1); PG8_SCHED; PG8_LDA(At, 0, 0); PG8_STAGE(PG8_SA(1, 1), a1 + hstep, voffA);
;             PG8_WAIT_V(8); PG8_WAIT_L(0); PG8_BAR; PG8_MMA(0, 0, At, B0); PG8_MMA(0, 1, At, B1); PG8_BAR; PG8_SCHED;
;             PG8_LDA(At, 0, 1); PG8_STAGE(PG8_SB(0, 0), b2, voffB); PG8_STAGE(PG8_SB(0, 1), b2 + hstep, voffB); PG8_STAGE(PG8_SA(0, 0), a2, voffA);
;             PG8_WAIT_V(8); PG8_WAIT_L(0); PG8_BAR; PG8_MMA(1, 0, At, B0); PG8_MMA(1, 1, At, B1); PG8_BAR; PG8_SCHED;
.LBB0_729:
	s_ashr_i32 s49, s48, 31
	s_lshl_b64 s[12:13], s[48:49], 20
	s_add_u32 s50, s18, s12
	s_addc_u32 s51, s19, s13
	s_and_b64 s[12:13], s[42:43], exec
	s_cselect_b32 s49, s51, s1
	s_cselect_b32 s60, s50, s0
	s_ashr_i32 s47, s46, 31
	s_lshl_b64 s[12:13], s[46:47], 20
	s_add_u32 s52, s14, s12
	s_addc_u32 s53, s15, s13
	s_and_b64 s[12:13], s[42:43], exec
	s_cselect_b32 s47, s53, s11
	s_cselect_b32 s61, s52, s10
	s_add_u32 s0, s0, 0x80080
	s_addc_u32 s1, s1, 0
	s_add_u32 s62, s10, 0x100
	s_addc_u32 s63, s11, 0
	s_mov_b32 s64, -2
	v_lshl_add_u64 v[190:191], s[0:1], 0, v[136:137]
	s_add_i32 m0, s31, 0xc000
	global_load_lds_dwordx4 v[190:191], off
	s_add_i32 m0, s31, 0xe000
	v_lshl_add_u64 v[190:191], s[0:1], 0, v[138:139]
	global_load_lds_dwordx4 v[190:191], off
	s_add_u32 s10, s0, 0xfff80080
	s_addc_u32 s11, s1, -1
	s_add_i32 s24, 0, 0x10000
	s_cmp_eq_u32 s64, 28
	s_cselect_b32 s13, s49, s11
	s_cselect_b32 s12, s60, s10
	s_cselect_b32 s11, s47, s63
	s_cselect_b32 s10, s61, s62
	s_add_i32 s25, 0, 0x14000
	s_waitcnt vmcnt(8)
	s_waitcnt lgkmcnt(0)
	s_barrier
	s_setprio 1
	s_waitcnt lgkmcnt(0)
	v_mfma_f32_16x16x32_bf16 v[124:127], v[140:143], v[178:181], 0
	v_mfma_f32_16x16x32_bf16 v[112:115], v[154:157], v[178:181], 0
	v_mfma_f32_16x16x32_bf16 v[108:111], v[140:143], v[186:189], 0
	v_mfma_f32_16x16x32_bf16 v[100:103], v[154:157], v[186:189], 0
	v_mfma_f32_16x16x32_bf16 v[92:95], v[140:143], v[202:205], 0
	v_mfma_f32_16x16x32_bf16 v[84:87], v[154:157], v[202:205], 0
	v_mfma_f32_16x16x32_bf16 v[76:79], v[140:143], v[210:213], 0
	v_mfma_f32_16x16x32_bf16 v[68:71], v[154:157], v[210:213], 0
	v_mfma_f32_16x16x32_bf16 v[124:127], v[144:147], v[182:185], v[124:127]
	v_mfma_f32_16x16x32_bf16 v[112:115], v[158:161], v[182:185], v[112:115]
	v_mfma_f32_16x16x32_bf16 v[108:111], v[144:147], v[194:197], v[108:111]
	v_mfma_f32_16x16x32_bf16 v[100:103], v[158:161], v[194:197], v[100:103]
	v_mfma_f32_16x16x32_bf16 v[92:95], v[144:147], v[206:209], v[92:95]
	v_mfma_f32_16x16x32_bf16 v[84:87], v[158:161], v[206:209], v[84:87]
	v_mfma_f32_16x16x32_bf16 v[76:79], v[144:147], v[214:217], v[76:79]
	v_mfma_f32_16x16x32_bf16 v[68:71], v[158:161], v[214:217], v[68:71]
	s_setprio 0
	s_setprio 1
	v_mfma_f32_16x16x32_bf16 v[120:123], v[162:165], v[178:181], 0
	v_mfma_f32_16x16x32_bf16 v[116:119], v[170:173], v[178:181], 0
	v_mfma_f32_16x16x32_bf16 v[104:107], v[162:165], v[186:189], 0
	v_mfma_f32_16x16x32_bf16 v[96:99], v[170:173], v[186:189], 0
	v_mfma_f32_16x16x32_bf16 v[88:91], v[162:165], v[202:205], 0
	v_mfma_f32_16x16x32_bf16 v[80:83], v[170:173], v[202:205], 0
	v_mfma_f32_16x16x32_bf16 v[72:75], v[162:165], v[210:213], 0
	v_mfma_f32_16x16x32_bf16 v[64:67], v[170:173], v[210:213], 0
	v_mfma_f32_16x16x32_bf16 v[120:123], v[166:169], v[182:185], v[120:123]
	v_mfma_f32_16x16x32_bf16 v[116:119], v[174:177], v[182:185], v[116:119]
	v_mfma_f32_16x16x32_bf16 v[104:107], v[166:169], v[194:197], v[104:107]
	v_mfma_f32_16x16x32_bf16 v[96:99], v[174:177], v[194:197], v[96:99]
	s_barrier
	s_setprio 2
	v_mfma_f32_16x16x32_bf16 v[88:91], v[166:169], v[206:209], v[88:91]
	v_mfma_f32_16x16x32_bf16 v[80:83], v[174:177], v[206:209], v[80:83]
	v_mfma_f32_16x16x32_bf16 v[72:75], v[166:169], v[214:217], v[72:75]
	v_mfma_f32_16x16x32_bf16 v[64:67], v[174:177], v[214:217], v[64:67]
	s_setprio 0
	s_add_i32 s24, s24, s30
	v_lshl_add_u64 v[190:191], s[10:11], 0, v[132:133]
	s_mov_b32 m0, s24
	s_nop 0
	global_load_lds_dwordx4 v[190:191], off
	s_add_i32 m0, s24, 0x2000
	s_add_u32 s66, s10, 0x80000
	v_lshl_add_u64 v[218:219], s[10:11], 0, v[128:129]
	s_addc_u32 s67, s11, 0
	s_add_i32 s24, s25, s30
	global_load_lds_dwordx4 v[218:219], off
	v_lshl_add_u64 v[220:221], s[66:67], 0, v[132:133]
	s_mov_b32 m0, s24
	v_lshl_add_u64 v[230:231], s[12:13], 0, v[130:131]
	global_load_lds_dwordx4 v[220:221], off
	s_add_i32 m0, s24, 0x2000
	v_lshl_add_u64 v[220:221], s[66:67], 0, v[128:129]
	global_load_lds_dwordx4 v[220:221], off
	s_mov_b32 m0, s31
	v_lshl_add_u64 v[220:221], s[12:13], 0, v[134:135]
	global_load_lds_dwordx4 v[220:221], off
	s_mov_b32 m0, s34
	s_nop 0
	global_load_lds_dwordx4 v[230:231], off
	ds_read_b128 v[178:181], v152 offset:16384
	ds_read_b128 v[182:185], v152 offset:17408
	ds_read_b128 v[186:189], v152 offset:18432
	ds_read_b128 v[194:197], v152 offset:19456
	ds_read_b128 v[202:205], v152 offset:20480
	ds_read_b128 v[206:209], v152 offset:21504
	ds_read_b128 v[210:213], v152 offset:22528
	ds_read_b128 v[214:217], v152 offset:23552
	s_waitcnt vmcnt(8)
	s_waitcnt lgkmcnt(0)
	s_barrier
	s_setprio 1
	s_waitcnt lgkmcnt(0)
	v_mfma_f32_16x16x32_bf16 v[60:63], v[140:143], v[178:181], 0
	v_mfma_f32_16x16x32_bf16 v[52:55], v[154:157], v[178:181], 0
	v_mfma_f32_16x16x32_bf16 v[44:47], v[140:143], v[186:189], 0
	v_mfma_f32_16x16x32_bf16 v[36:39], v[154:157], v[186:189], 0
	v_mfma_f32_16x16x32_bf16 v[28:31], v[140:143], v[202:205], 0
	v_mfma_f32_16x16x32_bf16 v[20:23], v[154:157], v[202:205], 0
	v_mfma_f32_16x16x32_bf16 v[12:15], v[140:143], v[210:213], 0
	v_mfma_f32_16x16x32_bf16 v[4:7], v[154:157], v[210:213], 0
	v_mfma_f32_16x16x32_bf16 v[60:63], v[144:147], v[182:185], v[60:63]
	v_mfma_f32_16x16x32_bf16 v[52:55], v[158:161], v[182:185], v[52:55]
	v_mfma_f32_16x16x32_bf16 v[44:47], v[144:147], v[194:197], v[44:47]
	v_mfma_f32_16x16x32_bf16 v[36:39], v[158:161], v[194:197], v[36:39]
	v_mfma_f32_16x16x32_bf16 v[28:31], v[144:147], v[206:209], v[28:31]
	v_mfma_f32_16x16x32_bf16 v[20:23], v[158:161], v[206:209], v[20:23]
	v_mfma_f32_16x16x32_bf16 v[12:15], v[144:147], v[214:217], v[12:15]
	v_mfma_f32_16x16x32_bf16 v[4:7], v[158:161], v[214:217], v[4:7]
	s_setprio 0
	s_setprio 1
	v_mfma_f32_16x16x32_bf16 v[56:59], v[162:165], v[178:181], 0
	v_mfma_f32_16x16x32_bf16 v[48:51], v[170:173], v[178:181], 0
	v_mfma_f32_16x16x32_bf16 v[40:43], v[162:165], v[186:189], 0
	v_mfma_f32_16x16x32_bf16 v[32:35], v[170:173], v[186:189], 0
	v_mfma_f32_16x16x32_bf16 v[24:27], v[162:165], v[202:205], 0
	v_mfma_f32_16x16x32_bf16 v[16:19], v[170:173], v[202:205], 0
	v_mfma_f32_16x16x32_bf16 v[8:11], v[162:165], v[210:213], 0
	v_mfma_f32_16x16x32_bf16 v[0:3], v[170:173], v[210:213], 0
	v_mfma_f32_16x16x32_bf16 v[56:59], v[166:169], v[182:185], v[56:59]
	v_mfma_f32_16x16x32_bf16 v[48:51], v[174:177], v[182:185], v[48:51]
	v_mfma_f32_16x16x32_bf16 v[40:43], v[166:169], v[194:197], v[40:43]
	v_mfma_f32_16x16x32_bf16 v[32:35], v[174:177], v[194:197], v[32:35]
	s_barrier
; #define PG8_STAGE(bufoff, gbase, voff) do { _Pragma("unroll") for (int _i = 0; _i < 2; ++_i) \
;         __builtin_amdgcn_global_load_lds((const unsigned*)((const char*)(gbase) + (voff)[_i]), (PG8_LAS unsigned*)(lds + (bufoff) + ldsw + _i * 8192), 16, 0, 0); } while (0)
; #define PG8_LDA(dst, b, h) do { _Pragma("unroll") for (int m = 0; m < 4; ++m) _Pragma("unroll") for (int k = 0; k < 2; ++k) dst[m][k] = *(const PG8_LAS bf16x8*)(lds + PG8_SA(b, h) + aoff + m * 2048 + k * 1024); } while (0)
; #define PG8_LDB(dst, b, h) do { _Pragma("unroll") for (int n = 0; n < 2; ++n) _Pragma("unroll") for (int k = 0; k < 2; ++k) dst[n][k] = *(const PG8_LAS bf16x8*)(lds + PG8_SB(b, h) + boff + n * 2048 + k * 1024); } while (0)
; #define PG8_MMA(ai, bj, At, Bt) do { __builtin_amdgcn_s_setprio(1); _Pragma("unroll") for (int m = 0; m < 4; ++m) _Pragma("unroll") for (int n = 0; n < 2; ++n) _Pragma("unroll") for (int k = 0; k < 2; ++k) \
;         acc[ai][bj][m][n] = __builtin_amdgcn_mfma_f32_16x16x32_bf16(Bt[n][k], At[m][k], acc[ai][bj][m][n], 0, 0, 0); __builtin_amdgcn_s_setprio(0); } while (0)
; #define PG8_WAIT_V(n) asm volatile("s_waitcnt vmcnt(" #n ")" ::: "memory")
; #define PG8_WAIT_L(n) asm volatile("s_waitcnt lgkmcnt(" #n ")" ::: "memory")
; #define PG8_BAR __builtin_amdgcn_s_barrier()
; #define PG8_SCHED __builtin_amdgcn_sched_barrier(0)
; template <class Epi, class Sched, bool ALIGN_EPI = false, bool SP2 = false>
; __device__ __forceinline__ void gemm_phase(PG8_LAS unsigned char* lds, const Gemm g, const Sched& S, const Epi& E) {
;     ...
;             PG8_WAIT_V(8); PG8_WAIT_L(0); PG8_BAR; PG8_MMA(1, 0, At, B0); PG8_MMA(1, 1, At, B1); PG8_BAR; PG8_SCHED;
;             PG8_LDB(B0, 1, 0); PG8_LDB(B1, 1, 1); PG8_SCHED; PG8_LDA(At, 1, 0); PG8_STAGE(PG8_SA(0, 1), a2 + hstep, voffA);
;             PG8_WAIT_V(8); PG8_WAIT_L(0); PG8_BAR; PG8_MMA(0, 0, At, B0); PG8_MMA(0, 1, At, B1); PG8_BAR; PG8_SCHED;
;             PG8_LDA(At, 1, 1); PG8_STAGE(PG8_SB(1, 0), b3, voffB); PG8_STAGE(PG8_SB(1, 1), b3 + hstep, voffB); PG8_STAGE(PG8_SA(1, 0), a3, voffA);
	s_setprio 2
	v_mfma_f32_16x16x32_bf16 v[24:27], v[166:169], v[206:209], v[24:27]
	v_mfma_f32_16x16x32_bf16 v[16:19], v[174:177], v[206:209], v[16:19]
	v_mfma_f32_16x16x32_bf16 v[8:11], v[166:169], v[214:217], v[8:11]
	v_mfma_f32_16x16x32_bf16 v[0:3], v[174:177], v[214:217], v[0:3]
	s_setprio 0
	s_add_i32 s24, 0, 0x18000
	s_add_i32 s25, 0, 0x1c000
	s_add_u32 s12, s12, 0x80000
	s_addc_u32 s13, s13, 0
	s_mov_b32 m0, s36
	v_lshl_add_u64 v[232:233], s[12:13], 0, v[134:135]
	global_load_lds_dwordx4 v[232:233], off
	s_mov_b32 m0, s37
	v_lshl_add_u64 v[232:233], s[12:13], 0, v[130:131]
	global_load_lds_dwordx4 v[232:233], off
	v_add_u32_e32 v148, 0x18000, v151
	ds_read_b128 v[140:143], v148
	ds_read_b128 v[144:147], v148 offset:1024
	ds_read_b128 v[154:157], v148 offset:2048
	ds_read_b128 v[158:161], v148 offset:3072
	v_add_u32_e32 v148, 0x1c000, v151
	ds_read_b128 v[162:165], v148
	ds_read_b128 v[166:169], v148 offset:1024
	ds_read_b128 v[170:173], v148 offset:2048
	ds_read_b128 v[174:177], v148 offset:3072
	ds_read_b128 v[178:181], v152 offset:32768
	ds_read_b128 v[182:185], v152 offset:33792
	ds_read_b128 v[186:189], v152 offset:34816
	ds_read_b128 v[194:197], v152 offset:35840
	ds_read_b128 v[202:205], v152 offset:36864
	ds_read_b128 v[206:209], v152 offset:37888
	ds_read_b128 v[210:213], v152 offset:38912
	ds_read_b128 v[214:217], v152 offset:39936
	s_waitcnt vmcnt(8)
	s_waitcnt lgkmcnt(0)
	s_barrier
	s_setprio 1
	s_waitcnt lgkmcnt(0)
	v_mfma_f32_16x16x32_bf16 v[124:127], v[140:143], v[178:181], v[124:127]
	v_mfma_f32_16x16x32_bf16 v[112:115], v[154:157], v[178:181], v[112:115]
	v_mfma_f32_16x16x32_bf16 v[108:111], v[140:143], v[186:189], v[108:111]
	v_mfma_f32_16x16x32_bf16 v[100:103], v[154:157], v[186:189], v[100:103]
	v_mfma_f32_16x16x32_bf16 v[92:95], v[140:143], v[202:205], v[92:95]
	v_mfma_f32_16x16x32_bf16 v[84:87], v[154:157], v[202:205], v[84:87]
	v_mfma_f32_16x16x32_bf16 v[76:79], v[140:143], v[210:213], v[76:79]
	v_mfma_f32_16x16x32_bf16 v[68:71], v[154:157], v[210:213], v[68:71]
	v_mfma_f32_16x16x32_bf16 v[124:127], v[144:147], v[182:185], v[124:127]
	v_mfma_f32_16x16x32_bf16 v[112:115], v[158:161], v[182:185], v[112:115]
	v_mfma_f32_16x16x32_bf16 v[108:111], v[144:147], v[194:197], v[108:111]
	v_mfma_f32_16x16x32_bf16 v[100:103], v[158:161], v[194:197], v[100:103]
	v_mfma_f32_16x16x32_bf16 v[92:95], v[144:147], v[206:209], v[92:95]
	v_mfma_f32_16x16x32_bf16 v[84:87], v[158:161], v[206:209], v[84:87]
	v_mfma_f32_16x16x32_bf16 v[76:79], v[144:147], v[214:217], v[76:79]
	v_mfma_f32_16x16x32_bf16 v[68:71], v[158:161], v[214:217], v[68:71]
	s_setprio 0
	s_setprio 1
	v_mfma_f32_16x16x32_bf16 v[120:123], v[162:165], v[178:181], v[120:123]
	v_mfma_f32_16x16x32_bf16 v[116:119], v[170:173], v[178:181], v[116:119]
	v_mfma_f32_16x16x32_bf16 v[104:107], v[162:165], v[186:189], v[104:107]
	v_mfma_f32_16x16x32_bf16 v[96:99], v[170:173], v[186:189], v[96:99]
	v_mfma_f32_16x16x32_bf16 v[88:91], v[162:165], v[202:205], v[88:91]
	v_mfma_f32_16x16x32_bf16 v[80:83], v[170:173], v[202:205], v[80:83]
	v_mfma_f32_16x16x32_bf16 v[72:75], v[162:165], v[210:213], v[72:75]
	v_mfma_f32_16x16x32_bf16 v[64:67], v[170:173], v[210:213], v[64:67]
	v_mfma_f32_16x16x32_bf16 v[120:123], v[166:169], v[182:185], v[120:123]
	v_mfma_f32_16x16x32_bf16 v[116:119], v[174:177], v[182:185], v[116:119]
	v_mfma_f32_16x16x32_bf16 v[104:107], v[166:169], v[194:197], v[104:107]
	v_mfma_f32_16x16x32_bf16 v[96:99], v[174:177], v[194:197], v[96:99]
	s_barrier
	s_setprio 2
	v_mfma_f32_16x16x32_bf16 v[88:91], v[166:169], v[206:209], v[88:91]
	v_mfma_f32_16x16x32_bf16 v[80:83], v[174:177], v[206:209], v[80:83]
	v_mfma_f32_16x16x32_bf16 v[72:75], v[166:169], v[214:217], v[72:75]
	v_mfma_f32_16x16x32_bf16 v[64:67], v[174:177], v[214:217], v[64:67]
	s_setprio 0
	s_add_i32 s12, s24, s30
	v_lshl_add_u64 v[190:191], v[190:191], 0, s[16:17]
	s_mov_b32 m0, s12
	s_nop 0
	global_load_lds_dwordx4 v[190:191], off
	s_add_i32 m0, s12, 0x2000
	s_add_u32 s10, s10, 0x80080
	v_lshl_add_u64 v[190:191], v[218:219], 0, s[16:17]
	s_addc_u32 s11, s11, 0
	s_add_i32 s12, s25, s30
	global_load_lds_dwordx4 v[190:191], off
	s_mov_b32 m0, s12
	v_lshl_add_u64 v[190:191], s[10:11], 0, v[132:133]
	global_load_lds_dwordx4 v[190:191], off
	s_add_i32 m0, s12, 0x2000
	v_lshl_add_u64 v[190:191], s[10:11], 0, v[128:129]
	global_load_lds_dwordx4 v[190:191], off
	s_mov_b32 m0, s56
	v_lshl_add_u64 v[190:191], v[220:221], 0, s[16:17]
	global_load_lds_dwordx4 v[190:191], off
	s_mov_b32 m0, s57
	v_lshl_add_u64 v[190:191], v[230:231], 0, s[16:17]
	global_load_lds_dwordx4 v[190:191], off
	ds_read_b128 v[178:181], v152 offset:49152
	ds_read_b128 v[182:185], v152 offset:50176
	ds_read_b128 v[186:189], v152 offset:51200
	ds_read_b128 v[194:197], v152 offset:52224
	ds_read_b128 v[202:205], v152 offset:53248
	ds_read_b128 v[206:209], v152 offset:54272
	ds_read_b128 v[210:213], v152 offset:55296
	ds_read_b128 v[214:217], v152 offset:56320
	s_waitcnt vmcnt(8)
	s_waitcnt lgkmcnt(0)
	s_barrier
; #define PG8_STAGE(bufoff, gbase, voff) do { _Pragma("unroll") for (int _i = 0; _i < 2; ++_i) \
;         __builtin_amdgcn_global_load_lds((const unsigned*)((const char*)(gbase) + (voff)[_i]), (PG8_LAS unsigned*)(lds + (bufoff) + ldsw + _i * 8192), 16, 0, 0); } while (0)
; #define PG8_LDA(dst, b, h) do { _Pragma("unroll") for (int m = 0; m < 4; ++m) _Pragma("unroll") for (int k = 0; k < 2; ++k) dst[m][k] = *(const PG8_LAS bf16x8*)(lds + PG8_SA(b, h) + aoff + m * 2048 + k * 1024); } while (0)
; #define PG8_LDB(dst, b, h) do { _Pragma("unroll") for (int n = 0; n < 2; ++n) _Pragma("unroll") for (int k = 0; k < 2; ++k) dst[n][k] = *(const PG8_LAS bf16x8*)(lds + PG8_SB(b, h) + boff + n * 2048 + k * 1024); } while (0)
; #define PG8_MMA(ai, bj, At, Bt) do { __builtin_amdgcn_s_setprio(1); _Pragma("unroll") for (int m = 0; m < 4; ++m) _Pragma("unroll") for (int n = 0; n < 2; ++n) _Pragma("unroll") for (int k = 0; k < 2; ++k) \
;         acc[ai][bj][m][n] = __builtin_amdgcn_mfma_f32_16x16x32_bf16(Bt[n][k], At[m][k], acc[ai][bj][m][n], 0, 0, 0); __builtin_amdgcn_s_setprio(0); } while (0)
; #define PG8_WAIT_V(n) asm volatile("s_waitcnt vmcnt(" #n ")" ::: "memory")
; #define PG8_WAIT_L(n) asm volatile("s_waitcnt lgkmcnt(" #n ")" ::: "memory")
; #define PG8_BAR __builtin_amdgcn_s_barrier()
; #define PG8_SCHED __builtin_amdgcn_sched_barrier(0)
; template <class Epi, class Sched, bool ALIGN_EPI = false, bool SP2 = false>
; __device__ __forceinline__ void gemm_phase(PG8_LAS unsigned char* lds, const Gemm g, const Sched& S, const Epi& E) {
;     ...
;         for (int t = 0; t < nt; t += 2) {
;             if constexpr (Epi::MID_HOOK) { if (t == Epi::MID_T) E.mid(acc, cur, wr, wc, fr, fq); }
;             const bool last = (t == nt - 2);
;             const char* a1 = cA + (size_t)(t + 1) * kstep;
;             const char* a2 = last ? nA : cA + (size_t)(t + 2) * kstep; const char* b2 = last ? nB : cB + (size_t)(t + 2) * kstep;
;             const char* a3 = a2 + kstep; const char* b3 = b2 + kstep;
;             if (last && has_next) S.a_ready(nxt);
;             if constexpr (SP2) {
;             PG8_LDB(B0, 0, 0); PG8_LDB(B1, 0, 1); PG8_SCHED; PG8_LDA(At, 0, 0); PG8_STAGE(PG8_SA(1, 1), a1 + hstep, voffA);
;             PG8_WAIT_V(8); PG8_WAIT_L(0); PG8_BAR; PG8_MMA(0, 0, At, B0); PG8_MMA(0, 1, At, B1); PG8_BAR; PG8_SCHED;
	s_setprio 1
	s_waitcnt lgkmcnt(0)
	v_mfma_f32_16x16x32_bf16 v[60:63], v[140:143], v[178:181], v[60:63]
	v_mfma_f32_16x16x32_bf16 v[52:55], v[154:157], v[178:181], v[52:55]
	v_mfma_f32_16x16x32_bf16 v[44:47], v[140:143], v[186:189], v[44:47]
	v_mfma_f32_16x16x32_bf16 v[36:39], v[154:157], v[186:189], v[36:39]
	v_mfma_f32_16x16x32_bf16 v[28:31], v[140:143], v[202:205], v[28:31]
	v_mfma_f32_16x16x32_bf16 v[20:23], v[154:157], v[202:205], v[20:23]
	v_mfma_f32_16x16x32_bf16 v[12:15], v[140:143], v[210:213], v[12:15]
	v_mfma_f32_16x16x32_bf16 v[4:7], v[154:157], v[210:213], v[4:7]
	v_mfma_f32_16x16x32_bf16 v[60:63], v[144:147], v[182:185], v[60:63]
	v_mfma_f32_16x16x32_bf16 v[52:55], v[158:161], v[182:185], v[52:55]
	v_mfma_f32_16x16x32_bf16 v[44:47], v[144:147], v[194:197], v[44:47]
	v_mfma_f32_16x16x32_bf16 v[36:39], v[158:161], v[194:197], v[36:39]
	v_mfma_f32_16x16x32_bf16 v[28:31], v[144:147], v[206:209], v[28:31]
	v_mfma_f32_16x16x32_bf16 v[20:23], v[158:161], v[206:209], v[20:23]
	v_mfma_f32_16x16x32_bf16 v[12:15], v[144:147], v[214:217], v[12:15]
	v_mfma_f32_16x16x32_bf16 v[4:7], v[158:161], v[214:217], v[4:7]
	s_setprio 0
	s_setprio 1
	v_mfma_f32_16x16x32_bf16 v[56:59], v[162:165], v[178:181], v[56:59]
	v_mfma_f32_16x16x32_bf16 v[48:51], v[170:173], v[178:181], v[48:51]
	v_mfma_f32_16x16x32_bf16 v[40:43], v[162:165], v[186:189], v[40:43]
	v_mfma_f32_16x16x32_bf16 v[32:35], v[170:173], v[186:189], v[32:35]
	v_mfma_f32_16x16x32_bf16 v[24:27], v[162:165], v[202:205], v[24:27]
	v_mfma_f32_16x16x32_bf16 v[16:19], v[170:173], v[202:205], v[16:19]
	v_mfma_f32_16x16x32_bf16 v[8:11], v[162:165], v[210:213], v[8:11]
	v_mfma_f32_16x16x32_bf16 v[0:3], v[170:173], v[210:213], v[0:3]
	v_mfma_f32_16x16x32_bf16 v[56:59], v[166:169], v[182:185], v[56:59]
	v_mfma_f32_16x16x32_bf16 v[48:51], v[174:177], v[182:185], v[48:51]
	v_mfma_f32_16x16x32_bf16 v[40:43], v[166:169], v[194:197], v[40:43]
	v_mfma_f32_16x16x32_bf16 v[32:35], v[174:177], v[194:197], v[32:35]
	s_barrier
	s_setprio 2
	v_mfma_f32_16x16x32_bf16 v[24:27], v[166:169], v[206:209], v[24:27]
	v_mfma_f32_16x16x32_bf16 v[16:19], v[174:177], v[206:209], v[16:19]
	v_mfma_f32_16x16x32_bf16 v[8:11], v[166:169], v[214:217], v[8:11]
	v_mfma_f32_16x16x32_bf16 v[0:3], v[174:177], v[214:217], v[0:3]
	s_setprio 0
	s_add_i32 s64, s64, 2
	s_add_u32 s0, s0, 0x100
	s_addc_u32 s1, s1, 0
	s_add_u32 s62, s62, 0x100
	s_addc_u32 s63, s63, 0
	s_cmp_gt_u32 s64, 29
	s_branch .LBB0_730
.LBB0_730:
	v_lshl_add_u64 v[190:191], s[0:1], 0, v[136:137]
	s_add_i32 m0, s31, 0xc000
	s_nop 0
	global_load_lds_dwordx4 v[190:191], off
	s_add_i32 m0, s31, 0xe000
	v_lshl_add_u64 v[190:191], s[0:1], 0, v[138:139]
	global_load_lds_dwordx4 v[190:191], off
	s_add_u32 s10, s0, 0xfff80080
	s_addc_u32 s11, s1, -1
	s_add_i32 s24, 0, 0x10000
	s_cmp_eq_u32 s64, 28
	s_cselect_b32 s13, s49, s11
	s_cselect_b32 s12, s60, s10
	s_cselect_b32 s11, s47, s63
	s_cselect_b32 s10, s61, s62
	s_add_i32 s25, 0, 0x14000
	v_add_u32_e32 v148, 0x10000, v151
	ds_read_b128 v[140:143], v148
	ds_read_b128 v[144:147], v148 offset:1024
	ds_read_b128 v[154:157], v148 offset:2048
	ds_read_b128 v[158:161], v148 offset:3072
	v_add_u32_e32 v148, 0x14000, v151
	ds_read_b128 v[162:165], v148
	ds_read_b128 v[166:169], v148 offset:1024
	ds_read_b128 v[170:173], v148 offset:2048
	ds_read_b128 v[174:177], v148 offset:3072
	ds_read_b128 v[178:181], v152
	ds_read_b128 v[182:185], v152 offset:1024
	ds_read_b128 v[186:189], v152 offset:2048
	ds_read_b128 v[194:197], v152 offset:3072
	ds_read_b128 v[202:205], v152 offset:4096
	ds_read_b128 v[206:209], v152 offset:5120
	ds_read_b128 v[210:213], v152 offset:6144
	ds_read_b128 v[214:217], v152 offset:7168
	s_waitcnt vmcnt(8)
	s_waitcnt lgkmcnt(0)
	s_barrier
	s_setprio 1
	s_waitcnt lgkmcnt(0)
	v_mfma_f32_16x16x32_bf16 v[124:127], v[140:143], v[178:181], v[124:127]
	v_mfma_f32_16x16x32_bf16 v[112:115], v[154:157], v[178:181], v[112:115]
	v_mfma_f32_16x16x32_bf16 v[108:111], v[140:143], v[186:189], v[108:111]
	v_mfma_f32_16x16x32_bf16 v[100:103], v[154:157], v[186:189], v[100:103]
	v_mfma_f32_16x16x32_bf16 v[92:95], v[140:143], v[202:205], v[92:95]
	v_mfma_f32_16x16x32_bf16 v[84:87], v[154:157], v[202:205], v[84:87]
	v_mfma_f32_16x16x32_bf16 v[76:79], v[140:143], v[210:213], v[76:79]
	v_mfma_f32_16x16x32_bf16 v[68:71], v[154:157], v[210:213], v[68:71]
	v_mfma_f32_16x16x32_bf16 v[124:127], v[144:147], v[182:185], v[124:127]
	v_mfma_f32_16x16x32_bf16 v[112:115], v[158:161], v[182:185], v[112:115]
	v_mfma_f32_16x16x32_bf16 v[108:111], v[144:147], v[194:197], v[108:111]
	v_mfma_f32_16x16x32_bf16 v[100:103], v[158:161], v[194:197], v[100:103]
	v_mfma_f32_16x16x32_bf16 v[92:95], v[144:147], v[206:209], v[92:95]
	v_mfma_f32_16x16x32_bf16 v[84:87], v[158:161], v[206:209], v[84:87]
	v_mfma_f32_16x16x32_bf16 v[76:79], v[144:147], v[214:217], v[76:79]
	v_mfma_f32_16x16x32_bf16 v[68:71], v[158:161], v[214:217], v[68:71]
	s_setprio 0
	s_setprio 1
	v_mfma_f32_16x16x32_bf16 v[120:123], v[162:165], v[178:181], v[120:123]
	v_mfma_f32_16x16x32_bf16 v[116:119], v[170:173], v[178:181], v[116:119]
	v_mfma_f32_16x16x32_bf16 v[104:107], v[162:165], v[186:189], v[104:107]
	v_mfma_f32_16x16x32_bf16 v[96:99], v[170:173], v[186:189], v[96:99]
	v_mfma_f32_16x16x32_bf16 v[88:91], v[162:165], v[202:205], v[88:91]
	v_mfma_f32_16x16x32_bf16 v[80:83], v[170:173], v[202:205], v[80:83]
	v_mfma_f32_16x16x32_bf16 v[72:75], v[162:165], v[210:213], v[72:75]
	v_mfma_f32_16x16x32_bf16 v[64:67], v[170:173], v[210:213], v[64:67]
	v_mfma_f32_16x16x32_bf16 v[120:123], v[166:169], v[182:185], v[120:123]
	v_mfma_f32_16x16x32_bf16 v[116:119], v[174:177], v[182:185], v[116:119]
	v_mfma_f32_16x16x32_bf16 v[104:107], v[166:169], v[194:197], v[104:107]
	v_mfma_f32_16x16x32_bf16 v[96:99], v[174:177], v[194:197], v[96:99]
	s_barrier
; #define PG8_STAGE(bufoff, gbase, voff) do { _Pragma("unroll") for (int _i = 0; _i < 2; ++_i) \
;         __builtin_amdgcn_global_load_lds((const unsigned*)((const char*)(gbase) + (voff)[_i]), (PG8_LAS unsigned*)(lds + (bufoff) + ldsw + _i * 8192), 16, 0, 0); } while (0)
; #define PG8_LDA(dst, b, h) do { _Pragma("unroll") for (int m = 0; m < 4; ++m) _Pragma("unroll") for (int k = 0; k < 2; ++k) dst[m][k] = *(const PG8_LAS bf16x8*)(lds + PG8_SA(b, h) + aoff + m * 2048 + k * 1024); } while (0)
; #define PG8_LDB(dst, b, h) do { _Pragma("unroll") for (int n = 0; n < 2; ++n) _Pragma("unroll") for (int k = 0; k < 2; ++k) dst[n][k] = *(const PG8_LAS bf16x8*)(lds + PG8_SB(b, h) + boff + n * 2048 + k * 1024); } while (0)
; #define PG8_MMA(ai, bj, At, Bt) do { __builtin_amdgcn_s_setprio(1); _Pragma("unroll") for (int m = 0; m < 4; ++m) _Pragma("unroll") for (int n = 0; n < 2; ++n) _Pragma("unroll") for (int k = 0; k < 2; ++k) \
;         acc[ai][bj][m][n] = __builtin_amdgcn_mfma_f32_16x16x32_bf16(Bt[n][k], At[m][k], acc[ai][bj][m][n], 0, 0, 0); __builtin_amdgcn_s_setprio(0); } while (0)
; #define PG8_WAIT_V(n) asm volatile("s_waitcnt vmcnt(" #n ")" ::: "memory")
; #define PG8_WAIT_L(n) asm volatile("s_waitcnt lgkmcnt(" #n ")" ::: "memory")
; #define PG8_BAR __builtin_amdgcn_s_barrier()
; #define PG8_SCHED __builtin_amdgcn_sched_barrier(0)
; template <class Epi, class Sched, bool ALIGN_EPI = false, bool SP2 = false>
; __device__ __forceinline__ void gemm_phase(PG8_LAS unsigned char* lds, const Gemm g, const Sched& S, const Epi& E) {
;     ...
;             PG8_WAIT_V(8); PG8_WAIT_L(0); PG8_BAR; PG8_MMA(0, 0, At, B0); PG8_MMA(0, 1, At, B1); PG8_BAR; PG8_SCHED;
;             PG8_LDA(At, 0, 1); PG8_STAGE(PG8_SB(0, 0), b2, voffB); PG8_STAGE(PG8_SB(0, 1), b2 + hstep, voffB); PG8_STAGE(PG8_SA(0, 0), a2, voffA);
;             PG8_WAIT_V(8); PG8_WAIT_L(0); PG8_BAR; PG8_MMA(1, 0, At, B0); PG8_MMA(1, 1, At, B1); PG8_BAR; PG8_SCHED;
;             PG8_LDB(B0, 1, 0); PG8_LDB(B1, 1, 1); PG8_SCHED; PG8_LDA(At, 1, 0); PG8_STAGE(PG8_SA(0, 1), a2 + hstep, voffA);
	s_setprio 2
	v_mfma_f32_16x16x32_bf16 v[88:91], v[166:169], v[206:209], v[88:91]
	v_mfma_f32_16x16x32_bf16 v[80:83], v[174:177], v[206:209], v[80:83]
	v_mfma_f32_16x16x32_bf16 v[72:75], v[166:169], v[214:217], v[72:75]
	v_mfma_f32_16x16x32_bf16 v[64:67], v[174:177], v[214:217], v[64:67]
	s_setprio 0
	s_add_i32 s24, s24, s30
	v_lshl_add_u64 v[190:191], s[10:11], 0, v[132:133]
	s_mov_b32 m0, s24
	s_nop 0
	global_load_lds_dwordx4 v[190:191], off
	s_add_i32 m0, s24, 0x2000
	s_add_u32 s66, s10, 0x80000
	v_lshl_add_u64 v[218:219], s[10:11], 0, v[128:129]
	s_addc_u32 s67, s11, 0
	s_add_i32 s24, s25, s30
	global_load_lds_dwordx4 v[218:219], off
	v_lshl_add_u64 v[220:221], s[66:67], 0, v[132:133]
	s_mov_b32 m0, s24
	v_lshl_add_u64 v[230:231], s[12:13], 0, v[130:131]
	global_load_lds_dwordx4 v[220:221], off
	s_add_i32 m0, s24, 0x2000
	v_lshl_add_u64 v[220:221], s[66:67], 0, v[128:129]
	global_load_lds_dwordx4 v[220:221], off
	s_mov_b32 m0, s31
	v_lshl_add_u64 v[220:221], s[12:13], 0, v[134:135]
	global_load_lds_dwordx4 v[220:221], off
	s_mov_b32 m0, s34
	s_nop 0
	global_load_lds_dwordx4 v[230:231], off
	ds_read_b128 v[178:181], v152 offset:16384
	ds_read_b128 v[182:185], v152 offset:17408
	ds_read_b128 v[186:189], v152 offset:18432
	ds_read_b128 v[194:197], v152 offset:19456
	ds_read_b128 v[202:205], v152 offset:20480
	ds_read_b128 v[206:209], v152 offset:21504
	ds_read_b128 v[210:213], v152 offset:22528
	ds_read_b128 v[214:217], v152 offset:23552
	s_waitcnt vmcnt(8)
	s_waitcnt lgkmcnt(0)
	s_barrier
	s_setprio 1
	s_waitcnt lgkmcnt(0)
	v_mfma_f32_16x16x32_bf16 v[60:63], v[140:143], v[178:181], v[60:63]
	v_mfma_f32_16x16x32_bf16 v[52:55], v[154:157], v[178:181], v[52:55]
	v_mfma_f32_16x16x32_bf16 v[44:47], v[140:143], v[186:189], v[44:47]
	v_mfma_f32_16x16x32_bf16 v[36:39], v[154:157], v[186:189], v[36:39]
	v_mfma_f32_16x16x32_bf16 v[28:31], v[140:143], v[202:205], v[28:31]
	v_mfma_f32_16x16x32_bf16 v[20:23], v[154:157], v[202:205], v[20:23]
	v_mfma_f32_16x16x32_bf16 v[12:15], v[140:143], v[210:213], v[12:15]
	v_mfma_f32_16x16x32_bf16 v[4:7], v[154:157], v[210:213], v[4:7]
	v_mfma_f32_16x16x32_bf16 v[60:63], v[144:147], v[182:185], v[60:63]
	v_mfma_f32_16x16x32_bf16 v[52:55], v[158:161], v[182:185], v[52:55]
	v_mfma_f32_16x16x32_bf16 v[44:47], v[144:147], v[194:197], v[44:47]
	v_mfma_f32_16x16x32_bf16 v[36:39], v[158:161], v[194:197], v[36:39]
	v_mfma_f32_16x16x32_bf16 v[28:31], v[144:147], v[206:209], v[28:31]
	v_mfma_f32_16x16x32_bf16 v[20:23], v[158:161], v[206:209], v[20:23]
	v_mfma_f32_16x16x32_bf16 v[12:15], v[144:147], v[214:217], v[12:15]
	v_mfma_f32_16x16x32_bf16 v[4:7], v[158:161], v[214:217], v[4:7]
	s_setprio 0
	s_setprio 1
	v_mfma_f32_16x16x32_bf16 v[56:59], v[162:165], v[178:181], v[56:59]
	v_mfma_f32_16x16x32_bf16 v[48:51], v[170:173], v[178:181], v[48:51]
	v_mfma_f32_16x16x32_bf16 v[40:43], v[162:165], v[186:189], v[40:43]
	v_mfma_f32_16x16x32_bf16 v[32:35], v[170:173], v[186:189], v[32:35]
	v_mfma_f32_16x16x32_bf16 v[24:27], v[162:165], v[202:205], v[24:27]
	v_mfma_f32_16x16x32_bf16 v[16:19], v[170:173], v[202:205], v[16:19]
	v_mfma_f32_16x16x32_bf16 v[8:11], v[162:165], v[210:213], v[8:11]
	v_mfma_f32_16x16x32_bf16 v[0:3], v[170:173], v[210:213], v[0:3]
	v_mfma_f32_16x16x32_bf16 v[56:59], v[166:169], v[182:185], v[56:59]
	v_mfma_f32_16x16x32_bf16 v[48:51], v[174:177], v[182:185], v[48:51]
	v_mfma_f32_16x16x32_bf16 v[40:43], v[166:169], v[194:197], v[40:43]
	v_mfma_f32_16x16x32_bf16 v[32:35], v[174:177], v[194:197], v[32:35]
	s_barrier
	s_setprio 2
	v_mfma_f32_16x16x32_bf16 v[24:27], v[166:169], v[206:209], v[24:27]
	v_mfma_f32_16x16x32_bf16 v[16:19], v[174:177], v[206:209], v[16:19]
	v_mfma_f32_16x16x32_bf16 v[8:11], v[166:169], v[214:217], v[8:11]
	v_mfma_f32_16x16x32_bf16 v[0:3], v[174:177], v[214:217], v[0:3]
	s_setprio 0
	s_add_i32 s24, 0, 0x18000
	s_add_i32 s25, 0, 0x1c000
	s_add_u32 s12, s12, 0x80000
	s_addc_u32 s13, s13, 0
	s_mov_b32 m0, s36
	v_lshl_add_u64 v[232:233], s[12:13], 0, v[134:135]
	global_load_lds_dwordx4 v[232:233], off
	s_mov_b32 m0, s37
	v_lshl_add_u64 v[232:233], s[12:13], 0, v[130:131]
	global_load_lds_dwordx4 v[232:233], off
	v_add_u32_e32 v148, 0x18000, v151
	ds_read_b128 v[140:143], v148
	ds_read_b128 v[144:147], v148 offset:1024
	ds_read_b128 v[154:157], v148 offset:2048
	ds_read_b128 v[158:161], v148 offset:3072
	v_add_u32_e32 v148, 0x1c000, v151
	ds_read_b128 v[162:165], v148
	ds_read_b128 v[166:169], v148 offset:1024
	ds_read_b128 v[170:173], v148 offset:2048
	ds_read_b128 v[174:177], v148 offset:3072
	ds_read_b128 v[178:181], v152 offset:32768
	ds_read_b128 v[182:185], v152 offset:33792
	ds_read_b128 v[186:189], v152 offset:34816
	ds_read_b128 v[194:197], v152 offset:35840
	ds_read_b128 v[202:205], v152 offset:36864
	ds_read_b128 v[206:209], v152 offset:37888
	ds_read_b128 v[210:213], v152 offset:38912
	ds_read_b128 v[214:217], v152 offset:39936
	s_waitcnt vmcnt(8)
	s_waitcnt lgkmcnt(0)
	s_barrier
; #define PG8_STAGE(bufoff, gbase, voff) do { _Pragma("unroll") for (int _i = 0; _i < 2; ++_i) \
;         __builtin_amdgcn_global_load_lds((const unsigned*)((const char*)(gbase) + (voff)[_i]), (PG8_LAS unsigned*)(lds + (bufoff) + ldsw + _i * 8192), 16, 0, 0); } while (0)
; #define PG8_LDA(dst, b, h) do { _Pragma("unroll") for (int m = 0; m < 4; ++m) _Pragma("unroll") for (int k = 0; k < 2; ++k) dst[m][k] = *(const PG8_LAS bf16x8*)(lds + PG8_SA(b, h) + aoff + m * 2048 + k * 1024); } while (0)
; #define PG8_MMA(ai, bj, At, Bt) do { __builtin_amdgcn_s_setprio(1); _Pragma("unroll") for (int m = 0; m < 4; ++m) _Pragma("unroll") for (int n = 0; n < 2; ++n) _Pragma("unroll") for (int k = 0; k < 2; ++k) \
;         acc[ai][bj][m][n] = __builtin_amdgcn_mfma_f32_16x16x32_bf16(Bt[n][k], At[m][k], acc[ai][bj][m][n], 0, 0, 0); __builtin_amdgcn_s_setprio(0); } while (0)
; #define PG8_WAIT_V(n) asm volatile("s_waitcnt vmcnt(" #n ")" ::: "memory")
; #define PG8_WAIT_L(n) asm volatile("s_waitcnt lgkmcnt(" #n ")" ::: "memory")
; #define PG8_BAR __builtin_amdgcn_s_barrier()
; #define PG8_SCHED __builtin_amdgcn_sched_barrier(0)
; template <class Epi, class Sched, bool ALIGN_EPI = false, bool SP2 = false>
; __device__ __forceinline__ void gemm_phase(PG8_LAS unsigned char* lds, const Gemm g, const Sched& S, const Epi& E) {
;     ...
;             PG8_WAIT_V(8); PG8_WAIT_L(0); PG8_BAR; PG8_MMA(0, 0, At, B0); PG8_MMA(0, 1, At, B1); PG8_BAR; PG8_SCHED;
;             PG8_LDA(At, 1, 1); PG8_STAGE(PG8_SB(1, 0), b3, voffB); PG8_STAGE(PG8_SB(1, 1), b3 + hstep, voffB); PG8_STAGE(PG8_SA(1, 0), a3, voffA);
;             PG8_WAIT_V(8); PG8_WAIT_L(0); PG8_BAR; PG8_MMA(1, 0, At, B0); PG8_MMA(1, 1, At, B1); PG8_BAR; PG8_SCHED;
;     ...
;         if constexpr (ALIGN_EPI) { if (wr == 0) PG8_BAR; }
	s_setprio 1
	s_waitcnt lgkmcnt(0)
	v_mfma_f32_16x16x32_bf16 v[124:127], v[140:143], v[178:181], v[124:127]
	v_mfma_f32_16x16x32_bf16 v[112:115], v[154:157], v[178:181], v[112:115]
	v_mfma_f32_16x16x32_bf16 v[108:111], v[140:143], v[186:189], v[108:111]
	v_mfma_f32_16x16x32_bf16 v[100:103], v[154:157], v[186:189], v[100:103]
	v_mfma_f32_16x16x32_bf16 v[92:95], v[140:143], v[202:205], v[92:95]
	v_mfma_f32_16x16x32_bf16 v[84:87], v[154:157], v[202:205], v[84:87]
	v_mfma_f32_16x16x32_bf16 v[76:79], v[140:143], v[210:213], v[76:79]
	v_mfma_f32_16x16x32_bf16 v[68:71], v[154:157], v[210:213], v[68:71]
	v_mfma_f32_16x16x32_bf16 v[124:127], v[144:147], v[182:185], v[124:127]
	v_mfma_f32_16x16x32_bf16 v[112:115], v[158:161], v[182:185], v[112:115]
	v_mfma_f32_16x16x32_bf16 v[108:111], v[144:147], v[194:197], v[108:111]
	v_mfma_f32_16x16x32_bf16 v[100:103], v[158:161], v[194:197], v[100:103]
	v_mfma_f32_16x16x32_bf16 v[92:95], v[144:147], v[206:209], v[92:95]
	v_mfma_f32_16x16x32_bf16 v[84:87], v[158:161], v[206:209], v[84:87]
	v_mfma_f32_16x16x32_bf16 v[76:79], v[144:147], v[214:217], v[76:79]
	v_mfma_f32_16x16x32_bf16 v[68:71], v[158:161], v[214:217], v[68:71]
	s_setprio 0
	s_setprio 1
	v_mfma_f32_16x16x32_bf16 v[120:123], v[162:165], v[178:181], v[120:123]
	v_mfma_f32_16x16x32_bf16 v[116:119], v[170:173], v[178:181], v[116:119]
	v_mfma_f32_16x16x32_bf16 v[104:107], v[162:165], v[186:189], v[104:107]
	v_mfma_f32_16x16x32_bf16 v[96:99], v[170:173], v[186:189], v[96:99]
	v_mfma_f32_16x16x32_bf16 v[88:91], v[162:165], v[202:205], v[88:91]
	v_mfma_f32_16x16x32_bf16 v[80:83], v[170:173], v[202:205], v[80:83]
	v_mfma_f32_16x16x32_bf16 v[72:75], v[162:165], v[210:213], v[72:75]
	v_mfma_f32_16x16x32_bf16 v[64:67], v[170:173], v[210:213], v[64:67]
	v_mfma_f32_16x16x32_bf16 v[120:123], v[166:169], v[182:185], v[120:123]
	v_mfma_f32_16x16x32_bf16 v[116:119], v[174:177], v[182:185], v[116:119]
	v_mfma_f32_16x16x32_bf16 v[104:107], v[166:169], v[194:197], v[104:107]
	v_mfma_f32_16x16x32_bf16 v[96:99], v[174:177], v[194:197], v[96:99]
	s_barrier
	s_setprio 2
	v_mfma_f32_16x16x32_bf16 v[88:91], v[166:169], v[206:209], v[88:91]
	v_mfma_f32_16x16x32_bf16 v[80:83], v[174:177], v[206:209], v[80:83]
	v_mfma_f32_16x16x32_bf16 v[72:75], v[166:169], v[214:217], v[72:75]
	v_mfma_f32_16x16x32_bf16 v[64:67], v[174:177], v[214:217], v[64:67]
	s_setprio 0
	s_add_i32 s12, s24, s30
	v_lshl_add_u64 v[190:191], v[190:191], 0, s[16:17]
	s_mov_b32 m0, s12
	s_nop 0
	global_load_lds_dwordx4 v[190:191], off
	s_add_i32 m0, s12, 0x2000
	s_add_u32 s10, s10, 0x80080
	v_lshl_add_u64 v[190:191], v[218:219], 0, s[16:17]
	s_addc_u32 s11, s11, 0
	s_add_i32 s12, s25, s30
	global_load_lds_dwordx4 v[190:191], off
	s_mov_b32 m0, s12
	v_lshl_add_u64 v[190:191], s[10:11], 0, v[132:133]
	global_load_lds_dwordx4 v[190:191], off
	s_add_i32 m0, s12, 0x2000
	v_lshl_add_u64 v[190:191], s[10:11], 0, v[128:129]
	global_load_lds_dwordx4 v[190:191], off
	s_mov_b32 m0, s56
	v_lshl_add_u64 v[190:191], v[220:221], 0, s[16:17]
	global_load_lds_dwordx4 v[190:191], off
	s_mov_b32 m0, s57
	v_lshl_add_u64 v[190:191], v[230:231], 0, s[16:17]
	global_load_lds_dwordx4 v[190:191], off
	ds_read_b128 v[178:181], v152 offset:49152
	ds_read_b128 v[182:185], v152 offset:50176
	ds_read_b128 v[186:189], v152 offset:51200
	ds_read_b128 v[194:197], v152 offset:52224
	ds_read_b128 v[202:205], v152 offset:53248
	ds_read_b128 v[206:209], v152 offset:54272
	ds_read_b128 v[210:213], v152 offset:55296
	ds_read_b128 v[214:217], v152 offset:56320
	s_waitcnt vmcnt(8)
	s_waitcnt lgkmcnt(0)
	s_barrier
	s_setprio 1
	s_waitcnt lgkmcnt(0)
	v_mfma_f32_16x16x32_bf16 v[60:63], v[140:143], v[178:181], v[60:63]
	v_mfma_f32_16x16x32_bf16 v[52:55], v[154:157], v[178:181], v[52:55]
	v_mfma_f32_16x16x32_bf16 v[44:47], v[140:143], v[186:189], v[44:47]
	v_mfma_f32_16x16x32_bf16 v[36:39], v[154:157], v[186:189], v[36:39]
	v_mfma_f32_16x16x32_bf16 v[28:31], v[140:143], v[202:205], v[28:31]
	v_mfma_f32_16x16x32_bf16 v[20:23], v[154:157], v[202:205], v[20:23]
	v_mfma_f32_16x16x32_bf16 v[12:15], v[140:143], v[210:213], v[12:15]
	v_mfma_f32_16x16x32_bf16 v[4:7], v[154:157], v[210:213], v[4:7]
	v_mfma_f32_16x16x32_bf16 v[60:63], v[144:147], v[182:185], v[60:63]
	v_mfma_f32_16x16x32_bf16 v[52:55], v[158:161], v[182:185], v[52:55]
	v_mfma_f32_16x16x32_bf16 v[44:47], v[144:147], v[194:197], v[44:47]
	v_mfma_f32_16x16x32_bf16 v[36:39], v[158:161], v[194:197], v[36:39]
	v_mfma_f32_16x16x32_bf16 v[28:31], v[144:147], v[206:209], v[28:31]
	v_mfma_f32_16x16x32_bf16 v[20:23], v[158:161], v[206:209], v[20:23]
	v_mfma_f32_16x16x32_bf16 v[12:15], v[144:147], v[214:217], v[12:15]
	v_mfma_f32_16x16x32_bf16 v[4:7], v[158:161], v[214:217], v[4:7]
	s_setprio 0
	s_setprio 1
	v_mfma_f32_16x16x32_bf16 v[56:59], v[162:165], v[178:181], v[56:59]
	v_mfma_f32_16x16x32_bf16 v[48:51], v[170:173], v[178:181], v[48:51]
	v_mfma_f32_16x16x32_bf16 v[40:43], v[162:165], v[186:189], v[40:43]
	v_mfma_f32_16x16x32_bf16 v[32:35], v[170:173], v[186:189], v[32:35]
	v_mfma_f32_16x16x32_bf16 v[24:27], v[162:165], v[202:205], v[24:27]
	v_mfma_f32_16x16x32_bf16 v[16:19], v[170:173], v[202:205], v[16:19]
	v_mfma_f32_16x16x32_bf16 v[8:11], v[162:165], v[210:213], v[8:11]
	v_mfma_f32_16x16x32_bf16 v[0:3], v[170:173], v[210:213], v[0:3]
	v_mfma_f32_16x16x32_bf16 v[56:59], v[166:169], v[182:185], v[56:59]
	v_mfma_f32_16x16x32_bf16 v[48:51], v[174:177], v[182:185], v[48:51]
	v_mfma_f32_16x16x32_bf16 v[40:43], v[166:169], v[194:197], v[40:43]
	v_mfma_f32_16x16x32_bf16 v[32:35], v[174:177], v[194:197], v[32:35]
	s_barrier
	s_setprio 2
	v_mfma_f32_16x16x32_bf16 v[24:27], v[166:169], v[206:209], v[24:27]
	v_mfma_f32_16x16x32_bf16 v[16:19], v[174:177], v[206:209], v[16:19]
	v_mfma_f32_16x16x32_bf16 v[8:11], v[166:169], v[214:217], v[8:11]
	v_mfma_f32_16x16x32_bf16 v[0:3], v[174:177], v[214:217], v[0:3]
	s_setprio 0
	s_add_i32 s64, s64, 2
	s_add_u32 s0, s0, 0x100
	s_addc_u32 s1, s1, 0
	s_add_u32 s62, s62, 0x100
	s_addc_u32 s63, s63, 0
	s_cmp_gt_u32 s64, 29
	s_cbranch_scc0 .LBB0_730
	s_and_b64 vcc, exec, s[44:45]
	s_cbranch_vccz .LBB0_733
	s_barrier

; #define PG8_STAGE(bufoff, gbase, voff) do { _Pragma("unroll") for (int _i = 0; _i < 2; ++_i) \
;         __builtin_amdgcn_global_load_lds((const unsigned*)((const char*)(gbase) + (voff)[_i]), (PG8_LAS unsigned*)(lds + (bufoff) + ldsw + _i * 8192), 16, 0, 0); } while (0)
; #define PG8_LDA(dst, b, h) do { _Pragma("unroll") for (int m = 0; m < 4; ++m) _Pragma("unroll") for (int k = 0; k < 2; ++k) dst[m][k] = *(const PG8_LAS bf16x8*)(lds + PG8_SA(b, h) + aoff + m * 2048 + k * 1024); } while (0)
; #define PG8_LDB(dst, b, h) do { _Pragma("unroll") for (int n = 0; n < 2; ++n) _Pragma("unroll") for (int k = 0; k < 2; ++k) dst[n][k] = *(const PG8_LAS bf16x8*)(lds + PG8_SB(b, h) + boff + n * 2048 + k * 1024); } while (0)
; #define PG8_MMA(ai, bj, At, Bt) do { __builtin_amdgcn_s_setprio(1); _Pragma("unroll") for (int m = 0; m < 4; ++m) _Pragma("unroll") for (int n = 0; n < 2; ++n) _Pragma("unroll") for (int k = 0; k < 2; ++k) \
;         acc[ai][bj][m][n] = __builtin_amdgcn_mfma_f32_16x16x32_bf16(Bt[n][k], At[m][k], acc[ai][bj][m][n], 0, 0, 0); __builtin_amdgcn_s_setprio(0); } while (0)
; #define PG8_BAR __builtin_amdgcn_s_barrier()
; template <class Epi, class Sched, bool ALIGN_EPI = false, bool SP2 = false>
; __device__ __forceinline__ void gemm_phase(PG8_LAS unsigned char* lds, const Gemm g, const Sched& S, const Epi& E) {
;     ...
;         for (int t = 0; t < nt; t += 2) {
;             if constexpr (Epi::MID_HOOK) { if (t == Epi::MID_T) E.mid(acc, cur, wr, wc, fr, fq); }
;             const bool last = (t == nt - 2);
;             const char* a1 = cA + (size_t)(t + 1) * kstep;
;             const char* a2 = last ? nA : cA + (size_t)(t + 2) * kstep; const char* b2 = last ? nB : cB + (size_t)(t + 2) * kstep;
;             const char* a3 = a2 + kstep; const char* b3 = b2 + kstep;
;             if (last && has_next) S.a_ready(nxt);
;             if constexpr (SP2) {
;             PG8_LDB(B0, 0, 0); PG8_LDB(B1, 0, 1); PG8_SCHED; PG8_LDA(At, 0, 0); PG8_STAGE(PG8_SA(1, 1), a1 + hstep, voffA);
;             PG8_WAIT_V(8); PG8_WAIT_L(0); PG8_BAR; PG8_MMA(0, 0, At, B0); PG8_MMA(0, 1, At, B1); PG8_BAR; PG8_SCHED;
;             PG8_LDA(At, 0, 1); PG8_STAGE(PG8_SB(0, 0), b2, voffB); PG8_STAGE(PG8_SB(0, 1), b2 + hstep, voffB); PG8_STAGE(PG8_SA(0, 0), a2, voffA);
;             PG8_WAIT_V(8); PG8_WAIT_L(0); PG8_BAR; PG8_MMA(1, 0, At, B0); PG8_MMA(1, 1, At, B1); PG8_BAR; PG8_SCHED;
.LBB0_816:
	s_add_u32 s59, s30, 0x100
	s_addc_u32 s60, s31, 0
	s_mov_b32 s61, -2
	s_waitcnt lgkmcnt(0)
	v_lshl_add_u64 v[168:169], s[18:19], 0, v[160:161]
	s_add_i32 m0, s2, 0xc000
	global_load_lds_dwordx4 v[168:169], off
	s_add_i32 m0, s2, 0xe000
	v_lshl_add_u64 v[168:169], s[18:19], 0, v[162:163]
	global_load_lds_dwordx4 v[168:169], off
	s_add_u32 s30, s18, 0x100
	s_addc_u32 s31, s19, 0
	s_add_i32 s24, 0, 0x10000
	s_cmpk_eq_i32 s61, 0x54
	s_cselect_b32 s39, s5, s31
	s_cselect_b32 s38, s4, s30
	s_cselect_b32 s37, s15, s60
	s_cselect_b32 s36, s14, s59
	s_add_i32 s25, 0, 0x14000
	s_waitcnt vmcnt(8)
	s_waitcnt lgkmcnt(0)
	s_barrier
	s_setprio 1
	s_waitcnt lgkmcnt(0)
	v_mfma_f32_16x16x32_bf16 v[124:127], v[128:131], v[178:181], 0
	v_mfma_f32_16x16x32_bf16 v[120:123], v[136:139], v[178:181], 0
	v_mfma_f32_16x16x32_bf16 v[108:111], v[128:131], v[186:189], 0
	v_mfma_f32_16x16x32_bf16 v[104:107], v[136:139], v[186:189], 0
	v_mfma_f32_16x16x32_bf16 v[92:95], v[128:131], v[202:205], 0
	v_mfma_f32_16x16x32_bf16 v[88:91], v[136:139], v[202:205], 0
	v_mfma_f32_16x16x32_bf16 v[76:79], v[128:131], v[210:213], 0
	v_mfma_f32_16x16x32_bf16 v[72:75], v[136:139], v[210:213], 0
	v_mfma_f32_16x16x32_bf16 v[124:127], v[132:135], v[182:185], v[124:127]
	v_mfma_f32_16x16x32_bf16 v[120:123], v[140:143], v[182:185], v[120:123]
	v_mfma_f32_16x16x32_bf16 v[108:111], v[132:135], v[194:197], v[108:111]
	v_mfma_f32_16x16x32_bf16 v[104:107], v[140:143], v[194:197], v[104:107]
	v_mfma_f32_16x16x32_bf16 v[92:95], v[132:135], v[206:209], v[92:95]
	v_mfma_f32_16x16x32_bf16 v[88:91], v[140:143], v[206:209], v[88:91]
	v_mfma_f32_16x16x32_bf16 v[76:79], v[132:135], v[214:217], v[76:79]
	v_mfma_f32_16x16x32_bf16 v[72:75], v[140:143], v[214:217], v[72:75]
	s_setprio 0
	s_setprio 1
	v_mfma_f32_16x16x32_bf16 v[116:119], v[144:147], v[178:181], 0
	v_mfma_f32_16x16x32_bf16 v[112:115], v[164:167], v[178:181], 0
	v_mfma_f32_16x16x32_bf16 v[100:103], v[144:147], v[186:189], 0
	v_mfma_f32_16x16x32_bf16 v[96:99], v[164:167], v[186:189], 0
	v_mfma_f32_16x16x32_bf16 v[84:87], v[144:147], v[202:205], 0
	v_mfma_f32_16x16x32_bf16 v[80:83], v[164:167], v[202:205], 0
	v_mfma_f32_16x16x32_bf16 v[68:71], v[144:147], v[210:213], 0
	v_mfma_f32_16x16x32_bf16 v[64:67], v[164:167], v[210:213], 0
	v_mfma_f32_16x16x32_bf16 v[116:119], v[148:151], v[182:185], v[116:119]
	v_mfma_f32_16x16x32_bf16 v[112:115], v[174:177], v[182:185], v[112:115]
	v_mfma_f32_16x16x32_bf16 v[100:103], v[148:151], v[194:197], v[100:103]
	v_mfma_f32_16x16x32_bf16 v[96:99], v[174:177], v[194:197], v[96:99]
	s_barrier
	s_setprio 2
	v_mfma_f32_16x16x32_bf16 v[84:87], v[148:151], v[206:209], v[84:87]
	v_mfma_f32_16x16x32_bf16 v[80:83], v[174:177], v[206:209], v[80:83]
	v_mfma_f32_16x16x32_bf16 v[68:71], v[148:151], v[214:217], v[68:71]
	v_mfma_f32_16x16x32_bf16 v[64:67], v[174:177], v[214:217], v[64:67]
	s_setprio 0
	s_add_i32 s18, s24, s43
	v_lshl_add_u64 v[168:169], s[36:37], 0, v[156:157]
	s_mov_b32 m0, s18
	s_nop 0
	global_load_lds_dwordx4 v[168:169], off
	s_add_i32 m0, s18, 0x2000
	s_add_u32 s18, s36, 0x160000
	v_lshl_add_u64 v[190:191], s[36:37], 0, v[152:153]
	s_addc_u32 s19, s37, 0
	s_add_i32 s24, s25, s43
	global_load_lds_dwordx4 v[190:191], off
	v_lshl_add_u64 v[218:219], s[18:19], 0, v[156:157]
	s_mov_b32 m0, s24
	v_lshl_add_u64 v[220:221], s[38:39], 0, v[154:155]
	global_load_lds_dwordx4 v[218:219], off
	s_add_i32 m0, s24, 0x2000
	v_lshl_add_u64 v[218:219], s[18:19], 0, v[152:153]
	global_load_lds_dwordx4 v[218:219], off
	s_mov_b32 m0, s2
	v_lshl_add_u64 v[218:219], s[38:39], 0, v[158:159]
	global_load_lds_dwordx4 v[218:219], off
	s_mov_b32 m0, s44
	s_nop 0
	global_load_lds_dwordx4 v[220:221], off
	ds_read_b128 v[178:181], v173 offset:16384
	ds_read_b128 v[182:185], v173 offset:17408
	ds_read_b128 v[186:189], v173 offset:18432
	ds_read_b128 v[194:197], v173 offset:19456
	ds_read_b128 v[202:205], v173 offset:20480
	ds_read_b128 v[206:209], v173 offset:21504
	ds_read_b128 v[210:213], v173 offset:22528
	ds_read_b128 v[214:217], v173 offset:23552
	s_waitcnt vmcnt(8)
	s_waitcnt lgkmcnt(0)
	s_barrier
	s_setprio 1
	s_waitcnt lgkmcnt(0)
	v_mfma_f32_16x16x32_bf16 v[60:63], v[128:131], v[178:181], 0
	v_mfma_f32_16x16x32_bf16 v[56:59], v[136:139], v[178:181], 0
	v_mfma_f32_16x16x32_bf16 v[44:47], v[128:131], v[186:189], 0
	v_mfma_f32_16x16x32_bf16 v[40:43], v[136:139], v[186:189], 0
	v_mfma_f32_16x16x32_bf16 v[28:31], v[128:131], v[202:205], 0
	v_mfma_f32_16x16x32_bf16 v[24:27], v[136:139], v[202:205], 0
	v_mfma_f32_16x16x32_bf16 v[12:15], v[128:131], v[210:213], 0
	v_mfma_f32_16x16x32_bf16 v[8:11], v[136:139], v[210:213], 0
	v_mfma_f32_16x16x32_bf16 v[60:63], v[132:135], v[182:185], v[60:63]
	v_mfma_f32_16x16x32_bf16 v[56:59], v[140:143], v[182:185], v[56:59]
	v_mfma_f32_16x16x32_bf16 v[44:47], v[132:135], v[194:197], v[44:47]
	v_mfma_f32_16x16x32_bf16 v[40:43], v[140:143], v[194:197], v[40:43]
	v_mfma_f32_16x16x32_bf16 v[28:31], v[132:135], v[206:209], v[28:31]
	v_mfma_f32_16x16x32_bf16 v[24:27], v[140:143], v[206:209], v[24:27]
	v_mfma_f32_16x16x32_bf16 v[12:15], v[132:135], v[214:217], v[12:15]
	v_mfma_f32_16x16x32_bf16 v[8:11], v[140:143], v[214:217], v[8:11]
	s_setprio 0
	s_setprio 1
	v_mfma_f32_16x16x32_bf16 v[52:55], v[144:147], v[178:181], 0
	v_mfma_f32_16x16x32_bf16 v[48:51], v[164:167], v[178:181], 0
	v_mfma_f32_16x16x32_bf16 v[36:39], v[144:147], v[186:189], 0
	v_mfma_f32_16x16x32_bf16 v[32:35], v[164:167], v[186:189], 0
	v_mfma_f32_16x16x32_bf16 v[20:23], v[144:147], v[202:205], 0
	v_mfma_f32_16x16x32_bf16 v[16:19], v[164:167], v[202:205], 0
	v_mfma_f32_16x16x32_bf16 v[4:7], v[144:147], v[210:213], 0
	v_mfma_f32_16x16x32_bf16 v[0:3], v[164:167], v[210:213], 0
	v_mfma_f32_16x16x32_bf16 v[52:55], v[148:151], v[182:185], v[52:55]
	v_mfma_f32_16x16x32_bf16 v[48:51], v[174:177], v[182:185], v[48:51]
	v_mfma_f32_16x16x32_bf16 v[36:39], v[148:151], v[194:197], v[36:39]
	v_mfma_f32_16x16x32_bf16 v[32:35], v[174:177], v[194:197], v[32:35]
	s_barrier
; #define PG8_STAGE(bufoff, gbase, voff) do { _Pragma("unroll") for (int _i = 0; _i < 2; ++_i) \
;         __builtin_amdgcn_global_load_lds((const unsigned*)((const char*)(gbase) + (voff)[_i]), (PG8_LAS unsigned*)(lds + (bufoff) + ldsw + _i * 8192), 16, 0, 0); } while (0)
; #define PG8_LDA(dst, b, h) do { _Pragma("unroll") for (int m = 0; m < 4; ++m) _Pragma("unroll") for (int k = 0; k < 2; ++k) dst[m][k] = *(const PG8_LAS bf16x8*)(lds + PG8_SA(b, h) + aoff + m * 2048 + k * 1024); } while (0)
; #define PG8_LDB(dst, b, h) do { _Pragma("unroll") for (int n = 0; n < 2; ++n) _Pragma("unroll") for (int k = 0; k < 2; ++k) dst[n][k] = *(const PG8_LAS bf16x8*)(lds + PG8_SB(b, h) + boff + n * 2048 + k * 1024); } while (0)
; #define PG8_MMA(ai, bj, At, Bt) do { __builtin_amdgcn_s_setprio(1); _Pragma("unroll") for (int m = 0; m < 4; ++m) _Pragma("unroll") for (int n = 0; n < 2; ++n) _Pragma("unroll") for (int k = 0; k < 2; ++k) \
;         acc[ai][bj][m][n] = __builtin_amdgcn_mfma_f32_16x16x32_bf16(Bt[n][k], At[m][k], acc[ai][bj][m][n], 0, 0, 0); __builtin_amdgcn_s_setprio(0); } while (0)
; #define PG8_WAIT_V(n) asm volatile("s_waitcnt vmcnt(" #n ")" ::: "memory")
; #define PG8_WAIT_L(n) asm volatile("s_waitcnt lgkmcnt(" #n ")" ::: "memory")
; #define PG8_BAR __builtin_amdgcn_s_barrier()
; #define PG8_SCHED __builtin_amdgcn_sched_barrier(0)
; template <class Epi, class Sched, bool ALIGN_EPI = false, bool SP2 = false>
; __device__ __forceinline__ void gemm_phase(PG8_LAS unsigned char* lds, const Gemm g, const Sched& S, const Epi& E) {
;     ...
;             PG8_WAIT_V(8); PG8_WAIT_L(0); PG8_BAR; PG8_MMA(1, 0, At, B0); PG8_MMA(1, 1, At, B1); PG8_BAR; PG8_SCHED;
;             PG8_LDB(B0, 1, 0); PG8_LDB(B1, 1, 1); PG8_SCHED; PG8_LDA(At, 1, 0); PG8_STAGE(PG8_SA(0, 1), a2 + hstep, voffA);
;             PG8_WAIT_V(8); PG8_WAIT_L(0); PG8_BAR; PG8_MMA(0, 0, At, B0); PG8_MMA(0, 1, At, B1); PG8_BAR; PG8_SCHED;
;             PG8_LDA(At, 1, 1); PG8_STAGE(PG8_SB(1, 0), b3, voffB); PG8_STAGE(PG8_SB(1, 1), b3 + hstep, voffB); PG8_STAGE(PG8_SA(1, 0), a3, voffA);
	s_setprio 2
	v_mfma_f32_16x16x32_bf16 v[20:23], v[148:151], v[206:209], v[20:23]
	v_mfma_f32_16x16x32_bf16 v[16:19], v[174:177], v[206:209], v[16:19]
	v_mfma_f32_16x16x32_bf16 v[4:7], v[148:151], v[214:217], v[4:7]
	v_mfma_f32_16x16x32_bf16 v[0:3], v[174:177], v[214:217], v[0:3]
	s_setprio 0
	s_add_i32 s24, 0, 0x18000
	s_add_i32 s25, 0, 0x1c000
	s_add_u32 s18, s38, 0x160000
	s_addc_u32 s19, s39, 0
	s_mov_b32 m0, s45
	v_lshl_add_u64 v[230:231], s[18:19], 0, v[158:159]
	global_load_lds_dwordx4 v[230:231], off
	s_mov_b32 m0, s46
	v_lshl_add_u64 v[230:231], s[18:19], 0, v[154:155]
	global_load_lds_dwordx4 v[230:231], off
	v_add_u32_e32 v140, 0x18000, v172
	v_add_u32_e32 v174, 0x1c000, v172
	ds_read_b128 v[128:131], v140
	ds_read_b128 v[132:135], v140 offset:1024
	ds_read_b128 v[136:139], v140 offset:2048
	ds_read_b128 v[140:143], v140 offset:3072
	ds_read_b128 v[144:147], v174
	ds_read_b128 v[148:151], v174 offset:1024
	ds_read_b128 v[164:167], v174 offset:2048
	ds_read_b128 v[174:177], v174 offset:3072
	ds_read_b128 v[178:181], v173 offset:32768
	ds_read_b128 v[182:185], v173 offset:33792
	ds_read_b128 v[186:189], v173 offset:34816
	ds_read_b128 v[194:197], v173 offset:35840
	ds_read_b128 v[202:205], v173 offset:36864
	ds_read_b128 v[206:209], v173 offset:37888
	ds_read_b128 v[210:213], v173 offset:38912
	ds_read_b128 v[214:217], v173 offset:39936
	s_waitcnt vmcnt(8)
	s_waitcnt lgkmcnt(0)
	s_barrier
	s_setprio 1
	s_waitcnt lgkmcnt(0)
	v_mfma_f32_16x16x32_bf16 v[124:127], v[128:131], v[178:181], v[124:127]
	v_mfma_f32_16x16x32_bf16 v[120:123], v[136:139], v[178:181], v[120:123]
	v_mfma_f32_16x16x32_bf16 v[108:111], v[128:131], v[186:189], v[108:111]
	v_mfma_f32_16x16x32_bf16 v[104:107], v[136:139], v[186:189], v[104:107]
	v_mfma_f32_16x16x32_bf16 v[92:95], v[128:131], v[202:205], v[92:95]
	v_mfma_f32_16x16x32_bf16 v[88:91], v[136:139], v[202:205], v[88:91]
	v_mfma_f32_16x16x32_bf16 v[76:79], v[128:131], v[210:213], v[76:79]
	v_mfma_f32_16x16x32_bf16 v[72:75], v[136:139], v[210:213], v[72:75]
	v_mfma_f32_16x16x32_bf16 v[124:127], v[132:135], v[182:185], v[124:127]
	v_mfma_f32_16x16x32_bf16 v[120:123], v[140:143], v[182:185], v[120:123]
	v_mfma_f32_16x16x32_bf16 v[108:111], v[132:135], v[194:197], v[108:111]
	v_mfma_f32_16x16x32_bf16 v[104:107], v[140:143], v[194:197], v[104:107]
	v_mfma_f32_16x16x32_bf16 v[92:95], v[132:135], v[206:209], v[92:95]
	v_mfma_f32_16x16x32_bf16 v[88:91], v[140:143], v[206:209], v[88:91]
	v_mfma_f32_16x16x32_bf16 v[76:79], v[132:135], v[214:217], v[76:79]
	v_mfma_f32_16x16x32_bf16 v[72:75], v[140:143], v[214:217], v[72:75]
	s_setprio 0
	s_setprio 1
	v_mfma_f32_16x16x32_bf16 v[116:119], v[144:147], v[178:181], v[116:119]
	v_mfma_f32_16x16x32_bf16 v[112:115], v[164:167], v[178:181], v[112:115]
	v_mfma_f32_16x16x32_bf16 v[100:103], v[144:147], v[186:189], v[100:103]
	v_mfma_f32_16x16x32_bf16 v[96:99], v[164:167], v[186:189], v[96:99]
	v_mfma_f32_16x16x32_bf16 v[84:87], v[144:147], v[202:205], v[84:87]
	v_mfma_f32_16x16x32_bf16 v[80:83], v[164:167], v[202:205], v[80:83]
	v_mfma_f32_16x16x32_bf16 v[68:71], v[144:147], v[210:213], v[68:71]
	v_mfma_f32_16x16x32_bf16 v[64:67], v[164:167], v[210:213], v[64:67]
	v_mfma_f32_16x16x32_bf16 v[116:119], v[148:151], v[182:185], v[116:119]
	v_mfma_f32_16x16x32_bf16 v[112:115], v[174:177], v[182:185], v[112:115]
	v_mfma_f32_16x16x32_bf16 v[100:103], v[148:151], v[194:197], v[100:103]
	v_mfma_f32_16x16x32_bf16 v[96:99], v[174:177], v[194:197], v[96:99]
	s_barrier
	s_setprio 2
	v_mfma_f32_16x16x32_bf16 v[84:87], v[148:151], v[206:209], v[84:87]
	v_mfma_f32_16x16x32_bf16 v[80:83], v[174:177], v[206:209], v[80:83]
	v_mfma_f32_16x16x32_bf16 v[68:71], v[148:151], v[214:217], v[68:71]
	v_mfma_f32_16x16x32_bf16 v[64:67], v[174:177], v[214:217], v[64:67]
	s_setprio 0
	s_add_i32 s18, s24, s43
	v_lshl_add_u64 v[168:169], v[168:169], 0, s[16:17]
	s_mov_b32 m0, s18
	s_nop 0
	global_load_lds_dwordx4 v[168:169], off
	s_add_i32 m0, s18, 0x2000
	s_add_u32 s18, s36, 0x160080
	v_lshl_add_u64 v[168:169], v[190:191], 0, s[16:17]
	s_addc_u32 s19, s37, 0
	s_add_i32 s24, s25, s43
	global_load_lds_dwordx4 v[168:169], off
	s_mov_b32 m0, s24
	v_lshl_add_u64 v[168:169], s[18:19], 0, v[156:157]
	global_load_lds_dwordx4 v[168:169], off
	s_add_i32 m0, s24, 0x2000
	v_lshl_add_u64 v[168:169], s[18:19], 0, v[152:153]
	global_load_lds_dwordx4 v[168:169], off
	s_mov_b32 m0, s51
	v_lshl_add_u64 v[168:169], v[218:219], 0, s[16:17]
	global_load_lds_dwordx4 v[168:169], off
	s_mov_b32 m0, s52
	v_lshl_add_u64 v[168:169], v[220:221], 0, s[16:17]
	global_load_lds_dwordx4 v[168:169], off
	ds_read_b128 v[178:181], v173 offset:49152
	ds_read_b128 v[182:185], v173 offset:50176
	ds_read_b128 v[186:189], v173 offset:51200
	ds_read_b128 v[194:197], v173 offset:52224
	ds_read_b128 v[202:205], v173 offset:53248
	ds_read_b128 v[206:209], v173 offset:54272
	ds_read_b128 v[210:213], v173 offset:55296
	ds_read_b128 v[214:217], v173 offset:56320
	s_waitcnt vmcnt(8)
	s_waitcnt lgkmcnt(0)
	s_barrier
; #define PG8_STAGE(bufoff, gbase, voff) do { _Pragma("unroll") for (int _i = 0; _i < 2; ++_i) \
;         __builtin_amdgcn_global_load_lds((const unsigned*)((const char*)(gbase) + (voff)[_i]), (PG8_LAS unsigned*)(lds + (bufoff) + ldsw + _i * 8192), 16, 0, 0); } while (0)
; #define PG8_LDA(dst, b, h) do { _Pragma("unroll") for (int m = 0; m < 4; ++m) _Pragma("unroll") for (int k = 0; k < 2; ++k) dst[m][k] = *(const PG8_LAS bf16x8*)(lds + PG8_SA(b, h) + aoff + m * 2048 + k * 1024); } while (0)
; #define PG8_LDB(dst, b, h) do { _Pragma("unroll") for (int n = 0; n < 2; ++n) _Pragma("unroll") for (int k = 0; k < 2; ++k) dst[n][k] = *(const PG8_LAS bf16x8*)(lds + PG8_SB(b, h) + boff + n * 2048 + k * 1024); } while (0)
; #define PG8_MMA(ai, bj, At, Bt) do { __builtin_amdgcn_s_setprio(1); _Pragma("unroll") for (int m = 0; m < 4; ++m) _Pragma("unroll") for (int n = 0; n < 2; ++n) _Pragma("unroll") for (int k = 0; k < 2; ++k) \
;         acc[ai][bj][m][n] = __builtin_amdgcn_mfma_f32_16x16x32_bf16(Bt[n][k], At[m][k], acc[ai][bj][m][n], 0, 0, 0); __builtin_amdgcn_s_setprio(0); } while (0)
; #define PG8_WAIT_V(n) asm volatile("s_waitcnt vmcnt(" #n ")" ::: "memory")
; #define PG8_WAIT_L(n) asm volatile("s_waitcnt lgkmcnt(" #n ")" ::: "memory")
; #define PG8_BAR __builtin_amdgcn_s_barrier()
; #define PG8_SCHED __builtin_amdgcn_sched_barrier(0)
; template <class Epi, class Sched, bool ALIGN_EPI = false, bool SP2 = false>
; __device__ __forceinline__ void gemm_phase(PG8_LAS unsigned char* lds, const Gemm g, const Sched& S, const Epi& E) {
;     ...
;         for (int t = 0; t < nt; t += 2) {
;             if constexpr (Epi::MID_HOOK) { if (t == Epi::MID_T) E.mid(acc, cur, wr, wc, fr, fq); }
;             const bool last = (t == nt - 2);
;             const char* a1 = cA + (size_t)(t + 1) * kstep;
;             const char* a2 = last ? nA : cA + (size_t)(t + 2) * kstep; const char* b2 = last ? nB : cB + (size_t)(t + 2) * kstep;
;             const char* a3 = a2 + kstep; const char* b3 = b2 + kstep;
;             if (last && has_next) S.a_ready(nxt);
;             if constexpr (SP2) {
;             PG8_LDB(B0, 0, 0); PG8_LDB(B1, 0, 1); PG8_SCHED; PG8_LDA(At, 0, 0); PG8_STAGE(PG8_SA(1, 1), a1 + hstep, voffA);
;             PG8_WAIT_V(8); PG8_WAIT_L(0); PG8_BAR; PG8_MMA(0, 0, At, B0); PG8_MMA(0, 1, At, B1); PG8_BAR; PG8_SCHED;
	s_setprio 1
	s_waitcnt lgkmcnt(0)
	v_mfma_f32_16x16x32_bf16 v[60:63], v[128:131], v[178:181], v[60:63]
	v_mfma_f32_16x16x32_bf16 v[56:59], v[136:139], v[178:181], v[56:59]
	v_mfma_f32_16x16x32_bf16 v[44:47], v[128:131], v[186:189], v[44:47]
	v_mfma_f32_16x16x32_bf16 v[40:43], v[136:139], v[186:189], v[40:43]
	v_mfma_f32_16x16x32_bf16 v[28:31], v[128:131], v[202:205], v[28:31]
	v_mfma_f32_16x16x32_bf16 v[24:27], v[136:139], v[202:205], v[24:27]
	v_mfma_f32_16x16x32_bf16 v[12:15], v[128:131], v[210:213], v[12:15]
	v_mfma_f32_16x16x32_bf16 v[8:11], v[136:139], v[210:213], v[8:11]
	v_mfma_f32_16x16x32_bf16 v[60:63], v[132:135], v[182:185], v[60:63]
	v_mfma_f32_16x16x32_bf16 v[56:59], v[140:143], v[182:185], v[56:59]
	v_mfma_f32_16x16x32_bf16 v[44:47], v[132:135], v[194:197], v[44:47]
	v_mfma_f32_16x16x32_bf16 v[40:43], v[140:143], v[194:197], v[40:43]
	v_mfma_f32_16x16x32_bf16 v[28:31], v[132:135], v[206:209], v[28:31]
	v_mfma_f32_16x16x32_bf16 v[24:27], v[140:143], v[206:209], v[24:27]
	v_mfma_f32_16x16x32_bf16 v[12:15], v[132:135], v[214:217], v[12:15]
	v_mfma_f32_16x16x32_bf16 v[8:11], v[140:143], v[214:217], v[8:11]
	s_setprio 0
	s_setprio 1
	v_mfma_f32_16x16x32_bf16 v[52:55], v[144:147], v[178:181], v[52:55]
	v_mfma_f32_16x16x32_bf16 v[48:51], v[164:167], v[178:181], v[48:51]
	v_mfma_f32_16x16x32_bf16 v[36:39], v[144:147], v[186:189], v[36:39]
	v_mfma_f32_16x16x32_bf16 v[32:35], v[164:167], v[186:189], v[32:35]
	v_mfma_f32_16x16x32_bf16 v[20:23], v[144:147], v[202:205], v[20:23]
	v_mfma_f32_16x16x32_bf16 v[16:19], v[164:167], v[202:205], v[16:19]
	v_mfma_f32_16x16x32_bf16 v[4:7], v[144:147], v[210:213], v[4:7]
	v_mfma_f32_16x16x32_bf16 v[0:3], v[164:167], v[210:213], v[0:3]
	v_mfma_f32_16x16x32_bf16 v[52:55], v[148:151], v[182:185], v[52:55]
	v_mfma_f32_16x16x32_bf16 v[48:51], v[174:177], v[182:185], v[48:51]
	v_mfma_f32_16x16x32_bf16 v[36:39], v[148:151], v[194:197], v[36:39]
	v_mfma_f32_16x16x32_bf16 v[32:35], v[174:177], v[194:197], v[32:35]
	s_barrier
	s_setprio 2
	v_mfma_f32_16x16x32_bf16 v[20:23], v[148:151], v[206:209], v[20:23]
	v_mfma_f32_16x16x32_bf16 v[16:19], v[174:177], v[206:209], v[16:19]
	v_mfma_f32_16x16x32_bf16 v[4:7], v[148:151], v[214:217], v[4:7]
	v_mfma_f32_16x16x32_bf16 v[0:3], v[174:177], v[214:217], v[0:3]
	s_setprio 0
	s_add_i32 s61, s61, 2
	s_add_u32 s59, s59, 0x100
	s_addc_u32 s60, s60, 0
	s_cmpk_gt_u32 s61, 0x55
	s_mov_b64 s[18:19], s[30:31]
	s_branch .LBB0_817
.LBB0_817:
	v_add_u32_e32 v140, 0x10000, v172
	v_add_u32_e32 v168, 0x14000, v172
	ds_read_b128 v[128:131], v140
	ds_read_b128 v[132:135], v140 offset:1024
	ds_read_b128 v[136:139], v140 offset:2048
	ds_read_b128 v[140:143], v140 offset:3072
	ds_read_b128 v[144:147], v168
	ds_read_b128 v[148:151], v168 offset:1024
	ds_read_b128 v[164:167], v168 offset:2048
	ds_read_b128 v[174:177], v168 offset:3072
	v_lshl_add_u64 v[168:169], s[18:19], 0, v[160:161]
	s_add_i32 m0, s2, 0xc000
	ds_read_b128 v[178:181], v173
	ds_read_b128 v[182:185], v173 offset:1024
	ds_read_b128 v[186:189], v173 offset:2048
	ds_read_b128 v[194:197], v173 offset:3072
	ds_read_b128 v[202:205], v173 offset:4096
	ds_read_b128 v[206:209], v173 offset:5120
	ds_read_b128 v[210:213], v173 offset:6144
	ds_read_b128 v[214:217], v173 offset:7168
	global_load_lds_dwordx4 v[168:169], off
	s_add_i32 m0, s2, 0xe000
	v_lshl_add_u64 v[168:169], s[18:19], 0, v[162:163]
	global_load_lds_dwordx4 v[168:169], off
	s_add_u32 s30, s18, 0x100
	s_addc_u32 s31, s19, 0
	s_add_i32 s24, 0, 0x10000
	s_cmpk_eq_i32 s61, 0x54
	s_cselect_b32 s39, s5, s31
	s_cselect_b32 s38, s4, s30
	s_cselect_b32 s37, s15, s60
	s_cselect_b32 s36, s14, s59
	s_add_i32 s25, 0, 0x14000
	s_waitcnt vmcnt(8)
	s_waitcnt lgkmcnt(0)
	s_barrier
	s_setprio 1
	s_waitcnt lgkmcnt(0)
	v_mfma_f32_16x16x32_bf16 v[124:127], v[128:131], v[178:181], v[124:127]
	v_mfma_f32_16x16x32_bf16 v[120:123], v[136:139], v[178:181], v[120:123]
	v_mfma_f32_16x16x32_bf16 v[108:111], v[128:131], v[186:189], v[108:111]
	v_mfma_f32_16x16x32_bf16 v[104:107], v[136:139], v[186:189], v[104:107]
	v_mfma_f32_16x16x32_bf16 v[92:95], v[128:131], v[202:205], v[92:95]
	v_mfma_f32_16x16x32_bf16 v[88:91], v[136:139], v[202:205], v[88:91]
	v_mfma_f32_16x16x32_bf16 v[76:79], v[128:131], v[210:213], v[76:79]
	v_mfma_f32_16x16x32_bf16 v[72:75], v[136:139], v[210:213], v[72:75]
	v_mfma_f32_16x16x32_bf16 v[124:127], v[132:135], v[182:185], v[124:127]
	v_mfma_f32_16x16x32_bf16 v[120:123], v[140:143], v[182:185], v[120:123]
	v_mfma_f32_16x16x32_bf16 v[108:111], v[132:135], v[194:197], v[108:111]
	v_mfma_f32_16x16x32_bf16 v[104:107], v[140:143], v[194:197], v[104:107]
	v_mfma_f32_16x16x32_bf16 v[92:95], v[132:135], v[206:209], v[92:95]
	v_mfma_f32_16x16x32_bf16 v[88:91], v[140:143], v[206:209], v[88:91]
	v_mfma_f32_16x16x32_bf16 v[76:79], v[132:135], v[214:217], v[76:79]
	v_mfma_f32_16x16x32_bf16 v[72:75], v[140:143], v[214:217], v[72:75]
	s_setprio 0
	s_setprio 1
	v_mfma_f32_16x16x32_bf16 v[116:119], v[144:147], v[178:181], v[116:119]
	v_mfma_f32_16x16x32_bf16 v[112:115], v[164:167], v[178:181], v[112:115]
	v_mfma_f32_16x16x32_bf16 v[100:103], v[144:147], v[186:189], v[100:103]
	v_mfma_f32_16x16x32_bf16 v[96:99], v[164:167], v[186:189], v[96:99]
	v_mfma_f32_16x16x32_bf16 v[84:87], v[144:147], v[202:205], v[84:87]
	v_mfma_f32_16x16x32_bf16 v[80:83], v[164:167], v[202:205], v[80:83]
	v_mfma_f32_16x16x32_bf16 v[68:71], v[144:147], v[210:213], v[68:71]
	v_mfma_f32_16x16x32_bf16 v[64:67], v[164:167], v[210:213], v[64:67]
	v_mfma_f32_16x16x32_bf16 v[116:119], v[148:151], v[182:185], v[116:119]
	v_mfma_f32_16x16x32_bf16 v[112:115], v[174:177], v[182:185], v[112:115]
	v_mfma_f32_16x16x32_bf16 v[100:103], v[148:151], v[194:197], v[100:103]
	v_mfma_f32_16x16x32_bf16 v[96:99], v[174:177], v[194:197], v[96:99]
	s_barrier
; #define PG8_STAGE(bufoff, gbase, voff) do { _Pragma("unroll") for (int _i = 0; _i < 2; ++_i) \
;         __builtin_amdgcn_global_load_lds((const unsigned*)((const char*)(gbase) + (voff)[_i]), (PG8_LAS unsigned*)(lds + (bufoff) + ldsw + _i * 8192), 16, 0, 0); } while (0)
; #define PG8_LDA(dst, b, h) do { _Pragma("unroll") for (int m = 0; m < 4; ++m) _Pragma("unroll") for (int k = 0; k < 2; ++k) dst[m][k] = *(const PG8_LAS bf16x8*)(lds + PG8_SA(b, h) + aoff + m * 2048 + k * 1024); } while (0)
; #define PG8_LDB(dst, b, h) do { _Pragma("unroll") for (int n = 0; n < 2; ++n) _Pragma("unroll") for (int k = 0; k < 2; ++k) dst[n][k] = *(const PG8_LAS bf16x8*)(lds + PG8_SB(b, h) + boff + n * 2048 + k * 1024); } while (0)
; #define PG8_MMA(ai, bj, At, Bt) do { __builtin_amdgcn_s_setprio(1); _Pragma("unroll") for (int m = 0; m < 4; ++m) _Pragma("unroll") for (int n = 0; n < 2; ++n) _Pragma("unroll") for (int k = 0; k < 2; ++k) \
;         acc[ai][bj][m][n] = __builtin_amdgcn_mfma_f32_16x16x32_bf16(Bt[n][k], At[m][k], acc[ai][bj][m][n], 0, 0, 0); __builtin_amdgcn_s_setprio(0); } while (0)
; #define PG8_WAIT_V(n) asm volatile("s_waitcnt vmcnt(" #n ")" ::: "memory")
; #define PG8_WAIT_L(n) asm volatile("s_waitcnt lgkmcnt(" #n ")" ::: "memory")
; #define PG8_BAR __builtin_amdgcn_s_barrier()
; #define PG8_SCHED __builtin_amdgcn_sched_barrier(0)
; template <class Epi, class Sched, bool ALIGN_EPI = false, bool SP2 = false>
; __device__ __forceinline__ void gemm_phase(PG8_LAS unsigned char* lds, const Gemm g, const Sched& S, const Epi& E) {
;     ...
;             PG8_WAIT_V(8); PG8_WAIT_L(0); PG8_BAR; PG8_MMA(0, 0, At, B0); PG8_MMA(0, 1, At, B1); PG8_BAR; PG8_SCHED;
;             PG8_LDA(At, 0, 1); PG8_STAGE(PG8_SB(0, 0), b2, voffB); PG8_STAGE(PG8_SB(0, 1), b2 + hstep, voffB); PG8_STAGE(PG8_SA(0, 0), a2, voffA);
;             PG8_WAIT_V(8); PG8_WAIT_L(0); PG8_BAR; PG8_MMA(1, 0, At, B0); PG8_MMA(1, 1, At, B1); PG8_BAR; PG8_SCHED;
;             PG8_LDB(B0, 1, 0); PG8_LDB(B1, 1, 1); PG8_SCHED; PG8_LDA(At, 1, 0); PG8_STAGE(PG8_SA(0, 1), a2 + hstep, voffA);
	s_setprio 2
	v_mfma_f32_16x16x32_bf16 v[84:87], v[148:151], v[206:209], v[84:87]
	v_mfma_f32_16x16x32_bf16 v[80:83], v[174:177], v[206:209], v[80:83]
	v_mfma_f32_16x16x32_bf16 v[68:71], v[148:151], v[214:217], v[68:71]
	v_mfma_f32_16x16x32_bf16 v[64:67], v[174:177], v[214:217], v[64:67]
	s_setprio 0
	s_add_i32 s18, s24, s43
	v_lshl_add_u64 v[168:169], s[36:37], 0, v[156:157]
	s_mov_b32 m0, s18
	s_nop 0
	global_load_lds_dwordx4 v[168:169], off
	s_add_i32 m0, s18, 0x2000
	s_add_u32 s18, s36, 0x160000
	v_lshl_add_u64 v[190:191], s[36:37], 0, v[152:153]
	s_addc_u32 s19, s37, 0
	s_add_i32 s24, s25, s43
	global_load_lds_dwordx4 v[190:191], off
	v_lshl_add_u64 v[218:219], s[18:19], 0, v[156:157]
	s_mov_b32 m0, s24
	v_lshl_add_u64 v[220:221], s[38:39], 0, v[154:155]
	global_load_lds_dwordx4 v[218:219], off
	s_add_i32 m0, s24, 0x2000
	v_lshl_add_u64 v[218:219], s[18:19], 0, v[152:153]
	global_load_lds_dwordx4 v[218:219], off
	s_mov_b32 m0, s2
	v_lshl_add_u64 v[218:219], s[38:39], 0, v[158:159]
	global_load_lds_dwordx4 v[218:219], off
	s_mov_b32 m0, s44
	s_nop 0
	global_load_lds_dwordx4 v[220:221], off
	ds_read_b128 v[178:181], v173 offset:16384
	ds_read_b128 v[182:185], v173 offset:17408
	ds_read_b128 v[186:189], v173 offset:18432
	ds_read_b128 v[194:197], v173 offset:19456
	ds_read_b128 v[202:205], v173 offset:20480
	ds_read_b128 v[206:209], v173 offset:21504
	ds_read_b128 v[210:213], v173 offset:22528
	ds_read_b128 v[214:217], v173 offset:23552
	s_waitcnt vmcnt(8)
	s_waitcnt lgkmcnt(0)
	s_barrier
	s_setprio 1
	s_waitcnt lgkmcnt(0)
	v_mfma_f32_16x16x32_bf16 v[60:63], v[128:131], v[178:181], v[60:63]
	v_mfma_f32_16x16x32_bf16 v[56:59], v[136:139], v[178:181], v[56:59]
	v_mfma_f32_16x16x32_bf16 v[44:47], v[128:131], v[186:189], v[44:47]
	v_mfma_f32_16x16x32_bf16 v[40:43], v[136:139], v[186:189], v[40:43]
	v_mfma_f32_16x16x32_bf16 v[28:31], v[128:131], v[202:205], v[28:31]
	v_mfma_f32_16x16x32_bf16 v[24:27], v[136:139], v[202:205], v[24:27]
	v_mfma_f32_16x16x32_bf16 v[12:15], v[128:131], v[210:213], v[12:15]
	v_mfma_f32_16x16x32_bf16 v[8:11], v[136:139], v[210:213], v[8:11]
	v_mfma_f32_16x16x32_bf16 v[60:63], v[132:135], v[182:185], v[60:63]
	v_mfma_f32_16x16x32_bf16 v[56:59], v[140:143], v[182:185], v[56:59]
	v_mfma_f32_16x16x32_bf16 v[44:47], v[132:135], v[194:197], v[44:47]
	v_mfma_f32_16x16x32_bf16 v[40:43], v[140:143], v[194:197], v[40:43]
	v_mfma_f32_16x16x32_bf16 v[28:31], v[132:135], v[206:209], v[28:31]
	v_mfma_f32_16x16x32_bf16 v[24:27], v[140:143], v[206:209], v[24:27]
	v_mfma_f32_16x16x32_bf16 v[12:15], v[132:135], v[214:217], v[12:15]
	v_mfma_f32_16x16x32_bf16 v[8:11], v[140:143], v[214:217], v[8:11]
	s_setprio 0
	s_setprio 1
	v_mfma_f32_16x16x32_bf16 v[52:55], v[144:147], v[178:181], v[52:55]
	v_mfma_f32_16x16x32_bf16 v[48:51], v[164:167], v[178:181], v[48:51]
	v_mfma_f32_16x16x32_bf16 v[36:39], v[144:147], v[186:189], v[36:39]
	v_mfma_f32_16x16x32_bf16 v[32:35], v[164:167], v[186:189], v[32:35]
	v_mfma_f32_16x16x32_bf16 v[20:23], v[144:147], v[202:205], v[20:23]
	v_mfma_f32_16x16x32_bf16 v[16:19], v[164:167], v[202:205], v[16:19]
	v_mfma_f32_16x16x32_bf16 v[4:7], v[144:147], v[210:213], v[4:7]
	v_mfma_f32_16x16x32_bf16 v[0:3], v[164:167], v[210:213], v[0:3]
	v_mfma_f32_16x16x32_bf16 v[52:55], v[148:151], v[182:185], v[52:55]
	v_mfma_f32_16x16x32_bf16 v[48:51], v[174:177], v[182:185], v[48:51]
	v_mfma_f32_16x16x32_bf16 v[36:39], v[148:151], v[194:197], v[36:39]
	v_mfma_f32_16x16x32_bf16 v[32:35], v[174:177], v[194:197], v[32:35]
	s_barrier
	s_setprio 2
	v_mfma_f32_16x16x32_bf16 v[20:23], v[148:151], v[206:209], v[20:23]
	v_mfma_f32_16x16x32_bf16 v[16:19], v[174:177], v[206:209], v[16:19]
	v_mfma_f32_16x16x32_bf16 v[4:7], v[148:151], v[214:217], v[4:7]
	v_mfma_f32_16x16x32_bf16 v[0:3], v[174:177], v[214:217], v[0:3]
	s_setprio 0
	s_add_i32 s24, 0, 0x18000
	s_add_i32 s25, 0, 0x1c000
	s_add_u32 s18, s38, 0x160000
	s_addc_u32 s19, s39, 0
	s_mov_b32 m0, s45
	v_lshl_add_u64 v[230:231], s[18:19], 0, v[158:159]
	global_load_lds_dwordx4 v[230:231], off
	s_mov_b32 m0, s46
	v_lshl_add_u64 v[230:231], s[18:19], 0, v[154:155]
	global_load_lds_dwordx4 v[230:231], off
	v_add_u32_e32 v140, 0x18000, v172
	v_add_u32_e32 v174, 0x1c000, v172
	ds_read_b128 v[128:131], v140
	ds_read_b128 v[132:135], v140 offset:1024
	ds_read_b128 v[136:139], v140 offset:2048
	ds_read_b128 v[140:143], v140 offset:3072
	ds_read_b128 v[144:147], v174
	ds_read_b128 v[148:151], v174 offset:1024
	ds_read_b128 v[164:167], v174 offset:2048
	ds_read_b128 v[174:177], v174 offset:3072
	ds_read_b128 v[178:181], v173 offset:32768
	ds_read_b128 v[182:185], v173 offset:33792
	ds_read_b128 v[186:189], v173 offset:34816
	ds_read_b128 v[194:197], v173 offset:35840
	ds_read_b128 v[202:205], v173 offset:36864
	ds_read_b128 v[206:209], v173 offset:37888
	ds_read_b128 v[210:213], v173 offset:38912
	ds_read_b128 v[214:217], v173 offset:39936
	s_waitcnt vmcnt(8)
	s_waitcnt lgkmcnt(0)
	s_barrier
; #define PG8_STAGE(bufoff, gbase, voff) do { _Pragma("unroll") for (int _i = 0; _i < 2; ++_i) \
;         __builtin_amdgcn_global_load_lds((const unsigned*)((const char*)(gbase) + (voff)[_i]), (PG8_LAS unsigned*)(lds + (bufoff) + ldsw + _i * 8192), 16, 0, 0); } while (0)
; #define PG8_LDA(dst, b, h) do { _Pragma("unroll") for (int m = 0; m < 4; ++m) _Pragma("unroll") for (int k = 0; k < 2; ++k) dst[m][k] = *(const PG8_LAS bf16x8*)(lds + PG8_SA(b, h) + aoff + m * 2048 + k * 1024); } while (0)
; #define PG8_MMA(ai, bj, At, Bt) do { __builtin_amdgcn_s_setprio(1); _Pragma("unroll") for (int m = 0; m < 4; ++m) _Pragma("unroll") for (int n = 0; n < 2; ++n) _Pragma("unroll") for (int k = 0; k < 2; ++k) \
;         acc[ai][bj][m][n] = __builtin_amdgcn_mfma_f32_16x16x32_bf16(Bt[n][k], At[m][k], acc[ai][bj][m][n], 0, 0, 0); __builtin_amdgcn_s_setprio(0); } while (0)
; #define PG8_WAIT_V(n) asm volatile("s_waitcnt vmcnt(" #n ")" ::: "memory")
; #define PG8_WAIT_L(n) asm volatile("s_waitcnt lgkmcnt(" #n ")" ::: "memory")
; #define PG8_BAR __builtin_amdgcn_s_barrier()
; #define PG8_SCHED __builtin_amdgcn_sched_barrier(0)
; template <class Epi, class Sched, bool ALIGN_EPI = false, bool SP2 = false>
; __device__ __forceinline__ void gemm_phase(PG8_LAS unsigned char* lds, const Gemm g, const Sched& S, const Epi& E) {
;     ...
;             PG8_WAIT_V(8); PG8_WAIT_L(0); PG8_BAR; PG8_MMA(0, 0, At, B0); PG8_MMA(0, 1, At, B1); PG8_BAR; PG8_SCHED;
;             PG8_LDA(At, 1, 1); PG8_STAGE(PG8_SB(1, 0), b3, voffB); PG8_STAGE(PG8_SB(1, 1), b3 + hstep, voffB); PG8_STAGE(PG8_SA(1, 0), a3, voffA);
;             PG8_WAIT_V(8); PG8_WAIT_L(0); PG8_BAR; PG8_MMA(1, 0, At, B0); PG8_MMA(1, 1, At, B1); PG8_BAR; PG8_SCHED;
	s_setprio 1
	s_waitcnt lgkmcnt(0)
	v_mfma_f32_16x16x32_bf16 v[124:127], v[128:131], v[178:181], v[124:127]
	v_mfma_f32_16x16x32_bf16 v[120:123], v[136:139], v[178:181], v[120:123]
	v_mfma_f32_16x16x32_bf16 v[108:111], v[128:131], v[186:189], v[108:111]
	v_mfma_f32_16x16x32_bf16 v[104:107], v[136:139], v[186:189], v[104:107]
	v_mfma_f32_16x16x32_bf16 v[92:95], v[128:131], v[202:205], v[92:95]
	v_mfma_f32_16x16x32_bf16 v[88:91], v[136:139], v[202:205], v[88:91]
	v_mfma_f32_16x16x32_bf16 v[76:79], v[128:131], v[210:213], v[76:79]
	v_mfma_f32_16x16x32_bf16 v[72:75], v[136:139], v[210:213], v[72:75]
	v_mfma_f32_16x16x32_bf16 v[124:127], v[132:135], v[182:185], v[124:127]
	v_mfma_f32_16x16x32_bf16 v[120:123], v[140:143], v[182:185], v[120:123]
	v_mfma_f32_16x16x32_bf16 v[108:111], v[132:135], v[194:197], v[108:111]
	v_mfma_f32_16x16x32_bf16 v[104:107], v[140:143], v[194:197], v[104:107]
	v_mfma_f32_16x16x32_bf16 v[92:95], v[132:135], v[206:209], v[92:95]
	v_mfma_f32_16x16x32_bf16 v[88:91], v[140:143], v[206:209], v[88:91]
	v_mfma_f32_16x16x32_bf16 v[76:79], v[132:135], v[214:217], v[76:79]
	v_mfma_f32_16x16x32_bf16 v[72:75], v[140:143], v[214:217], v[72:75]
	s_setprio 0
	s_setprio 1
	v_mfma_f32_16x16x32_bf16 v[116:119], v[144:147], v[178:181], v[116:119]
	v_mfma_f32_16x16x32_bf16 v[112:115], v[164:167], v[178:181], v[112:115]
	v_mfma_f32_16x16x32_bf16 v[100:103], v[144:147], v[186:189], v[100:103]
	v_mfma_f32_16x16x32_bf16 v[96:99], v[164:167], v[186:189], v[96:99]
	v_mfma_f32_16x16x32_bf16 v[84:87], v[144:147], v[202:205], v[84:87]
	v_mfma_f32_16x16x32_bf16 v[80:83], v[164:167], v[202:205], v[80:83]
	v_mfma_f32_16x16x32_bf16 v[68:71], v[144:147], v[210:213], v[68:71]
	v_mfma_f32_16x16x32_bf16 v[64:67], v[164:167], v[210:213], v[64:67]
	v_mfma_f32_16x16x32_bf16 v[116:119], v[148:151], v[182:185], v[116:119]
	v_mfma_f32_16x16x32_bf16 v[112:115], v[174:177], v[182:185], v[112:115]
	v_mfma_f32_16x16x32_bf16 v[100:103], v[148:151], v[194:197], v[100:103]
	v_mfma_f32_16x16x32_bf16 v[96:99], v[174:177], v[194:197], v[96:99]
	s_barrier
	s_setprio 2
	v_mfma_f32_16x16x32_bf16 v[84:87], v[148:151], v[206:209], v[84:87]
	v_mfma_f32_16x16x32_bf16 v[80:83], v[174:177], v[206:209], v[80:83]
	v_mfma_f32_16x16x32_bf16 v[68:71], v[148:151], v[214:217], v[68:71]
	v_mfma_f32_16x16x32_bf16 v[64:67], v[174:177], v[214:217], v[64:67]
	s_setprio 0
	s_add_i32 s18, s24, s43
	v_lshl_add_u64 v[168:169], v[168:169], 0, s[16:17]
	s_mov_b32 m0, s18
	s_nop 0
	global_load_lds_dwordx4 v[168:169], off
	s_add_i32 m0, s18, 0x2000
	s_add_u32 s18, s36, 0x160080
	v_lshl_add_u64 v[168:169], v[190:191], 0, s[16:17]
	s_addc_u32 s19, s37, 0
	s_add_i32 s24, s25, s43
	global_load_lds_dwordx4 v[168:169], off
	s_mov_b32 m0, s24
	v_lshl_add_u64 v[168:169], s[18:19], 0, v[156:157]
	global_load_lds_dwordx4 v[168:169], off
	s_add_i32 m0, s24, 0x2000
	v_lshl_add_u64 v[168:169], s[18:19], 0, v[152:153]
	global_load_lds_dwordx4 v[168:169], off
	s_mov_b32 m0, s51
	v_lshl_add_u64 v[168:169], v[218:219], 0, s[16:17]
	global_load_lds_dwordx4 v[168:169], off
	s_mov_b32 m0, s52
	v_lshl_add_u64 v[168:169], v[220:221], 0, s[16:17]
	global_load_lds_dwordx4 v[168:169], off
	ds_read_b128 v[178:181], v173 offset:49152
	ds_read_b128 v[182:185], v173 offset:50176
	ds_read_b128 v[186:189], v173 offset:51200
	ds_read_b128 v[194:197], v173 offset:52224
	ds_read_b128 v[202:205], v173 offset:53248
	ds_read_b128 v[206:209], v173 offset:54272
	ds_read_b128 v[210:213], v173 offset:55296
	ds_read_b128 v[214:217], v173 offset:56320
	s_waitcnt vmcnt(8)
	s_waitcnt lgkmcnt(0)
	s_barrier
	s_setprio 1
	s_waitcnt lgkmcnt(0)
	v_mfma_f32_16x16x32_bf16 v[60:63], v[128:131], v[178:181], v[60:63]
	v_mfma_f32_16x16x32_bf16 v[56:59], v[136:139], v[178:181], v[56:59]
	v_mfma_f32_16x16x32_bf16 v[44:47], v[128:131], v[186:189], v[44:47]
	v_mfma_f32_16x16x32_bf16 v[40:43], v[136:139], v[186:189], v[40:43]
	v_mfma_f32_16x16x32_bf16 v[28:31], v[128:131], v[202:205], v[28:31]
	v_mfma_f32_16x16x32_bf16 v[24:27], v[136:139], v[202:205], v[24:27]
	v_mfma_f32_16x16x32_bf16 v[12:15], v[128:131], v[210:213], v[12:15]
	v_mfma_f32_16x16x32_bf16 v[8:11], v[136:139], v[210:213], v[8:11]
	v_mfma_f32_16x16x32_bf16 v[60:63], v[132:135], v[182:185], v[60:63]
	v_mfma_f32_16x16x32_bf16 v[56:59], v[140:143], v[182:185], v[56:59]
	v_mfma_f32_16x16x32_bf16 v[44:47], v[132:135], v[194:197], v[44:47]
	v_mfma_f32_16x16x32_bf16 v[40:43], v[140:143], v[194:197], v[40:43]
	v_mfma_f32_16x16x32_bf16 v[28:31], v[132:135], v[206:209], v[28:31]
	v_mfma_f32_16x16x32_bf16 v[24:27], v[140:143], v[206:209], v[24:27]
	v_mfma_f32_16x16x32_bf16 v[12:15], v[132:135], v[214:217], v[12:15]
	v_mfma_f32_16x16x32_bf16 v[8:11], v[140:143], v[214:217], v[8:11]
	s_setprio 0
	s_setprio 1
	v_mfma_f32_16x16x32_bf16 v[52:55], v[144:147], v[178:181], v[52:55]
	v_mfma_f32_16x16x32_bf16 v[48:51], v[164:167], v[178:181], v[48:51]
	v_mfma_f32_16x16x32_bf16 v[36:39], v[144:147], v[186:189], v[36:39]
	v_mfma_f32_16x16x32_bf16 v[32:35], v[164:167], v[186:189], v[32:35]
	v_mfma_f32_16x16x32_bf16 v[20:23], v[144:147], v[202:205], v[20:23]
	v_mfma_f32_16x16x32_bf16 v[16:19], v[164:167], v[202:205], v[16:19]
	v_mfma_f32_16x16x32_bf16 v[4:7], v[144:147], v[210:213], v[4:7]
	v_mfma_f32_16x16x32_bf16 v[0:3], v[164:167], v[210:213], v[0:3]
	v_mfma_f32_16x16x32_bf16 v[52:55], v[148:151], v[182:185], v[52:55]
	v_mfma_f32_16x16x32_bf16 v[48:51], v[174:177], v[182:185], v[48:51]
	v_mfma_f32_16x16x32_bf16 v[36:39], v[148:151], v[194:197], v[36:39]
	v_mfma_f32_16x16x32_bf16 v[32:35], v[174:177], v[194:197], v[32:35]
	s_barrier
	s_setprio 2
	v_mfma_f32_16x16x32_bf16 v[20:23], v[148:151], v[206:209], v[20:23]
	v_mfma_f32_16x16x32_bf16 v[16:19], v[174:177], v[206:209], v[16:19]
	v_mfma_f32_16x16x32_bf16 v[4:7], v[148:151], v[214:217], v[4:7]
	v_mfma_f32_16x16x32_bf16 v[0:3], v[174:177], v[214:217], v[0:3]
	s_setprio 0
	s_add_i32 s61, s61, 2
	s_add_u32 s59, s59, 0x100
	s_addc_u32 s60, s60, 0
	s_cmpk_gt_u32 s61, 0x55
	s_mov_b64 s[18:19], s[30:31]
	s_cbranch_scc0 .LBB0_817
	s_and_b64 vcc, exec, s[12:13]
	s_cbranch_vccz .LBB0_820
	s_barrier
